# v17 + GEMM K-loops: one static s_setprio 1 for waves 4-7 per tile, per-segment priority flips deleted
# speedup vs baseline: 1.0039x; 1.0037x over previous
.LBB0_31:
	s_ashr_i32 s19, s18, 31
	s_lshl_b64 s[4:5], s[18:19], 21
	s_add_u32 s20, s34, s4
	s_addc_u32 s21, s35, s5
	s_and_b64 s[4:5], s[6:7], exec
	s_cselect_b32 s1, s21, s27
	s_cselect_b32 s2, s20, s26
	s_ashr_i32 s17, s16, 31
	s_lshl_b64 s[4:5], s[16:17], 21
	s_add_u32 s22, s36, s4
	s_addc_u32 s23, s37, s5
	s_and_b64 s[4:5], s[6:7], exec
	s_cselect_b32 s4, s23, s29
	s_cselect_b32 s5, s22, s28
	s_add_u32 s26, s26, 0x100080
	s_addc_u32 s27, s27, 0
	s_add_u32 s17, s28, 0x100
	v_mov_b32_e32 v4, 0
	s_addc_u32 s19, s29, 0
	s_mov_b32 s25, -2
	v_mov_b32_e32 v5, v4
	v_mov_b32_e32 v6, v4
	v_mov_b32_e32 v7, v4
	v_mov_b32_e32 v8, v4
	v_mov_b32_e32 v9, v4
	v_mov_b32_e32 v10, v4
	v_mov_b32_e32 v11, v4
	v_mov_b32_e32 v20, v4
	v_mov_b32_e32 v21, v4
	v_mov_b32_e32 v22, v4
	v_mov_b32_e32 v23, v4
	v_mov_b32_e32 v24, v4
	v_mov_b32_e32 v25, v4
	v_mov_b32_e32 v26, v4
	v_mov_b32_e32 v27, v4
	v_mov_b32_e32 v36, v4
	v_mov_b32_e32 v37, v4
	v_mov_b32_e32 v38, v4
	v_mov_b32_e32 v39, v4
	v_mov_b32_e32 v40, v4
	v_mov_b32_e32 v41, v4
	v_mov_b32_e32 v42, v4
	v_mov_b32_e32 v43, v4
	v_mov_b32_e32 v44, v4
	v_mov_b32_e32 v45, v4
	v_mov_b32_e32 v46, v4
	v_mov_b32_e32 v47, v4
	v_mov_b32_e32 v48, v4
	v_mov_b32_e32 v49, v4
	v_mov_b32_e32 v50, v4
	v_mov_b32_e32 v51, v4
	v_mov_b32_e32 v12, v4
	v_mov_b32_e32 v13, v4
	v_mov_b32_e32 v14, v4
	v_mov_b32_e32 v15, v4
	v_mov_b32_e32 v16, v4
	v_mov_b32_e32 v17, v4
	v_mov_b32_e32 v18, v4
	v_mov_b32_e32 v19, v4
	v_mov_b32_e32 v28, v4
	v_mov_b32_e32 v29, v4
	v_mov_b32_e32 v30, v4
	v_mov_b32_e32 v31, v4
	v_mov_b32_e32 v32, v4
	v_mov_b32_e32 v33, v4
	v_mov_b32_e32 v34, v4
	v_mov_b32_e32 v35, v4
	v_mov_b32_e32 v52, v4
	v_mov_b32_e32 v53, v4
	v_mov_b32_e32 v54, v4
	v_mov_b32_e32 v55, v4
	v_mov_b32_e32 v56, v4
	v_mov_b32_e32 v57, v4
	v_mov_b32_e32 v58, v4
	v_mov_b32_e32 v59, v4
	v_mov_b32_e32 v60, v4
	v_mov_b32_e32 v61, v4
	v_mov_b32_e32 v62, v4
	v_mov_b32_e32 v63, v4
	v_mov_b32_e32 v64, v4
	v_mov_b32_e32 v65, v4
	v_mov_b32_e32 v66, v4
	v_mov_b32_e32 v67, v4
	v_mov_b32_e32 v84, v4
	v_mov_b32_e32 v85, v4
	v_mov_b32_e32 v86, v4
	v_mov_b32_e32 v87, v4
	v_mov_b32_e32 v88, v4
	v_mov_b32_e32 v89, v4
	v_mov_b32_e32 v90, v4
	v_mov_b32_e32 v91, v4
	v_mov_b32_e32 v92, v4
	v_mov_b32_e32 v93, v4
	v_mov_b32_e32 v94, v4
	v_mov_b32_e32 v95, v4
	v_mov_b32_e32 v96, v4
	v_mov_b32_e32 v97, v4
	v_mov_b32_e32 v98, v4
	v_mov_b32_e32 v99, v4
	v_mov_b32_e32 v116, v4
	v_mov_b32_e32 v117, v4
	v_mov_b32_e32 v118, v4
	v_mov_b32_e32 v119, v4
	v_mov_b32_e32 v120, v4
	v_mov_b32_e32 v121, v4
	v_mov_b32_e32 v122, v4
	v_mov_b32_e32 v123, v4
	v_mov_b32_e32 v124, v4
	v_mov_b32_e32 v125, v4
	v_mov_b32_e32 v126, v4
	v_mov_b32_e32 v127, v4
	v_mov_b32_e32 v128, v4
	v_mov_b32_e32 v129, v4
	v_mov_b32_e32 v130, v4
	v_mov_b32_e32 v131, v4
	v_mov_b32_e32 v100, v4
	v_mov_b32_e32 v101, v4
	v_mov_b32_e32 v102, v4
	v_mov_b32_e32 v103, v4
	v_mov_b32_e32 v104, v4
	v_mov_b32_e32 v105, v4
	v_mov_b32_e32 v106, v4
	v_mov_b32_e32 v107, v4
	v_mov_b32_e32 v108, v4
	v_mov_b32_e32 v109, v4
	v_mov_b32_e32 v110, v4
	v_mov_b32_e32 v111, v4
	v_mov_b32_e32 v112, v4
	v_mov_b32_e32 v113, v4
	v_mov_b32_e32 v114, v4
	v_mov_b32_e32 v115, v4
	v_mov_b32_e32 v132, v4
	v_mov_b32_e32 v133, v4
	v_mov_b32_e32 v134, v4
	v_mov_b32_e32 v135, v4
	v_mov_b32_e32 v136, v4
	v_mov_b32_e32 v137, v4
	v_mov_b32_e32 v138, v4
	v_mov_b32_e32 v139, v4
	v_mov_b32_e32 v140, v4
	v_mov_b32_e32 v141, v4
	v_mov_b32_e32 v142, v4
	v_mov_b32_e32 v143, v4
	v_mov_b32_e32 v144, v4
	v_mov_b32_e32 v145, v4
	v_mov_b32_e32 v146, v4
	v_mov_b32_e32 v147, v4
	s_waitcnt vmcnt(0)
	v_readfirstlane_b32 s101, v186
	s_nop 3
	s_lshr_b32 s101, s101, 8
	s_cmp_eq_u32 s101, 1
	s_cbranch_scc0 .Lprio_0
	s_setprio 1
.Lprio_0:
.LBB0_32:
	s_add_u32 s28, s26, 0xfff00080
	s_addc_u32 s29, s27, -1
	s_add_i32 s33, 0, 0x10000
	s_cmp_eq_u32 s25, 60
	s_cselect_b32 s31, s1, s29
	s_cselect_b32 s30, s2, s28
	s_cselect_b32 s29, s4, s19
	s_cselect_b32 s28, s5, s17
	s_add_i32 s47, 0, 0x14000
	v_add_u32_e32 v80, s33, v214
	v_add_u32_e32 v168, s47, v214
	ds_read_b128 v[68:71], v80
	ds_read_b128 v[72:75], v80 offset:1024
	ds_read_b128 v[76:79], v80 offset:2048
	ds_read_b128 v[80:83], v80 offset:3072
	ds_read_b128 v[148:151], v168
	ds_read_b128 v[160:163], v168 offset:1024
	ds_read_b128 v[164:167], v168 offset:2048
	ds_read_b128 v[168:171], v168 offset:3072
	v_lshl_add_u64 v[212:213], s[26:27], 0, v[154:155]
	s_add_i32 m0, s50, 0xc000
	ds_read_b128 v[172:175], v215
	ds_read_b128 v[176:179], v215 offset:1024
	ds_read_b128 v[188:191], v215 offset:2048
	ds_read_b128 v[192:195], v215 offset:3072
	ds_read_b128 v[196:199], v215 offset:4096
	ds_read_b128 v[200:203], v215 offset:5120
	ds_read_b128 v[204:207], v215 offset:6144
	ds_read_b128 v[208:211], v215 offset:7168
	global_load_lds_dwordx4 v[212:213], off
	v_lshl_add_u64 v[212:213], s[26:27], 0, v[156:157]
	s_add_i32 m0, s50, 0xe000
	s_nop 0
	global_load_lds_dwordx4 v[212:213], off
	s_waitcnt vmcnt(8)
	s_waitcnt lgkmcnt(0)
	s_barrier

	s_waitcnt lgkmcnt(0)
	v_mfma_f32_16x16x32_bf16 v[144:147], v[68:71], v[172:175], v[144:147]
	v_mfma_f32_16x16x32_bf16 v[140:143], v[76:79], v[172:175], v[140:143]
	v_mfma_f32_16x16x32_bf16 v[136:139], v[68:71], v[188:191], v[136:139]
	v_mfma_f32_16x16x32_bf16 v[132:135], v[76:79], v[188:191], v[132:135]
	v_mfma_f32_16x16x32_bf16 v[112:115], v[68:71], v[196:199], v[112:115]
	v_mfma_f32_16x16x32_bf16 v[108:111], v[76:79], v[196:199], v[108:111]
	v_mfma_f32_16x16x32_bf16 v[104:107], v[68:71], v[204:207], v[104:107]
	v_mfma_f32_16x16x32_bf16 v[100:103], v[76:79], v[204:207], v[100:103]
	v_mfma_f32_16x16x32_bf16 v[144:147], v[72:75], v[176:179], v[144:147]
	v_mfma_f32_16x16x32_bf16 v[140:143], v[80:83], v[176:179], v[140:143]
	v_mfma_f32_16x16x32_bf16 v[136:139], v[72:75], v[192:195], v[136:139]
	v_mfma_f32_16x16x32_bf16 v[132:135], v[80:83], v[192:195], v[132:135]
	v_mfma_f32_16x16x32_bf16 v[112:115], v[72:75], v[200:203], v[112:115]
	v_mfma_f32_16x16x32_bf16 v[108:111], v[80:83], v[200:203], v[108:111]
	v_mfma_f32_16x16x32_bf16 v[104:107], v[72:75], v[208:211], v[104:107]
	v_mfma_f32_16x16x32_bf16 v[100:103], v[80:83], v[208:211], v[100:103]


	v_mfma_f32_16x16x32_bf16 v[128:131], v[148:151], v[172:175], v[128:131]
	v_mfma_f32_16x16x32_bf16 v[124:127], v[164:167], v[172:175], v[124:127]
	v_mfma_f32_16x16x32_bf16 v[120:123], v[148:151], v[188:191], v[120:123]
	v_mfma_f32_16x16x32_bf16 v[116:119], v[164:167], v[188:191], v[116:119]
	v_mfma_f32_16x16x32_bf16 v[96:99], v[148:151], v[196:199], v[96:99]
	v_mfma_f32_16x16x32_bf16 v[92:95], v[164:167], v[196:199], v[92:95]
	v_mfma_f32_16x16x32_bf16 v[88:91], v[148:151], v[204:207], v[88:91]
	v_mfma_f32_16x16x32_bf16 v[84:87], v[164:167], v[204:207], v[84:87]
	v_mfma_f32_16x16x32_bf16 v[128:131], v[160:163], v[176:179], v[128:131]
	v_mfma_f32_16x16x32_bf16 v[124:127], v[168:171], v[176:179], v[124:127]
	v_mfma_f32_16x16x32_bf16 v[120:123], v[160:163], v[192:195], v[120:123]
	v_mfma_f32_16x16x32_bf16 v[116:119], v[168:171], v[192:195], v[116:119]
	v_mfma_f32_16x16x32_bf16 v[96:99], v[160:163], v[200:203], v[96:99]
	v_mfma_f32_16x16x32_bf16 v[92:95], v[168:171], v[200:203], v[92:95]
	v_mfma_f32_16x16x32_bf16 v[88:91], v[160:163], v[208:211], v[88:91]
	v_mfma_f32_16x16x32_bf16 v[84:87], v[168:171], v[208:211], v[84:87]

	s_barrier
	s_add_i32 s33, s33, s41
	v_lshl_add_u64 v[212:213], s[28:29], 0, v[180:181]
	s_mov_b32 m0, s33
	ds_read_b128 v[172:175], v215 offset:16384
	ds_read_b128 v[176:179], v215 offset:17408
	ds_read_b128 v[188:191], v215 offset:18432
	ds_read_b128 v[192:195], v215 offset:19456
	ds_read_b128 v[196:199], v215 offset:20480
	ds_read_b128 v[200:203], v215 offset:21504
	ds_read_b128 v[204:207], v215 offset:22528
	ds_read_b128 v[208:211], v215 offset:23552
	global_load_lds_dwordx4 v[212:213], off
	s_add_i32 m0, s33, 0x2000
	s_add_u32 s44, s28, 0x100000
	v_lshl_add_u64 v[216:217], s[28:29], 0, v[152:153]
	s_addc_u32 s45, s29, 0
	s_add_i32 s33, s47, s41
	global_load_lds_dwordx4 v[216:217], off
	v_lshl_add_u64 v[218:219], s[44:45], 0, v[180:181]
	s_mov_b32 m0, s33
	v_lshl_add_u64 v[220:221], s[30:31], 0, v[152:153]
	global_load_lds_dwordx4 v[218:219], off
	v_lshl_add_u64 v[218:219], s[44:45], 0, v[152:153]
	s_add_i32 m0, s33, 0x2000
	s_nop 0
	global_load_lds_dwordx4 v[218:219], off
	v_lshl_add_u64 v[218:219], s[30:31], 0, v[180:181]
	s_mov_b32 m0, s50
	s_nop 0
	global_load_lds_dwordx4 v[218:219], off
	s_mov_b32 m0, s51
	s_nop 0
	global_load_lds_dwordx4 v[220:221], off
	s_waitcnt vmcnt(8)
	s_waitcnt lgkmcnt(0)
	s_barrier

	s_waitcnt lgkmcnt(0)
	v_mfma_f32_16x16x32_bf16 v[64:67], v[68:71], v[172:175], v[64:67]
	v_mfma_f32_16x16x32_bf16 v[60:63], v[76:79], v[172:175], v[60:63]
	v_mfma_f32_16x16x32_bf16 v[56:59], v[68:71], v[188:191], v[56:59]
	v_mfma_f32_16x16x32_bf16 v[52:55], v[76:79], v[188:191], v[52:55]
	v_mfma_f32_16x16x32_bf16 v[32:35], v[68:71], v[196:199], v[32:35]
	v_mfma_f32_16x16x32_bf16 v[28:31], v[76:79], v[196:199], v[28:31]
	v_mfma_f32_16x16x32_bf16 v[16:19], v[68:71], v[204:207], v[16:19]
	v_mfma_f32_16x16x32_bf16 v[12:15], v[76:79], v[204:207], v[12:15]
	v_mfma_f32_16x16x32_bf16 v[64:67], v[72:75], v[176:179], v[64:67]
	v_mfma_f32_16x16x32_bf16 v[60:63], v[80:83], v[176:179], v[60:63]
	v_mfma_f32_16x16x32_bf16 v[56:59], v[72:75], v[192:195], v[56:59]
	v_mfma_f32_16x16x32_bf16 v[52:55], v[80:83], v[192:195], v[52:55]
	v_mfma_f32_16x16x32_bf16 v[32:35], v[72:75], v[200:203], v[32:35]
	v_mfma_f32_16x16x32_bf16 v[28:31], v[80:83], v[200:203], v[28:31]
	v_mfma_f32_16x16x32_bf16 v[16:19], v[72:75], v[208:211], v[16:19]
	v_mfma_f32_16x16x32_bf16 v[12:15], v[80:83], v[208:211], v[12:15]


	v_mfma_f32_16x16x32_bf16 v[48:51], v[148:151], v[172:175], v[48:51]
	v_mfma_f32_16x16x32_bf16 v[44:47], v[164:167], v[172:175], v[44:47]
	v_mfma_f32_16x16x32_bf16 v[40:43], v[148:151], v[188:191], v[40:43]
	v_mfma_f32_16x16x32_bf16 v[36:39], v[164:167], v[188:191], v[36:39]
	v_mfma_f32_16x16x32_bf16 v[24:27], v[148:151], v[196:199], v[24:27]
	v_mfma_f32_16x16x32_bf16 v[20:23], v[164:167], v[196:199], v[20:23]
	v_mfma_f32_16x16x32_bf16 v[8:11], v[148:151], v[204:207], v[8:11]
	v_mfma_f32_16x16x32_bf16 v[4:7], v[164:167], v[204:207], v[4:7]
	v_mfma_f32_16x16x32_bf16 v[48:51], v[160:163], v[176:179], v[48:51]
	v_mfma_f32_16x16x32_bf16 v[44:47], v[168:171], v[176:179], v[44:47]
	v_mfma_f32_16x16x32_bf16 v[40:43], v[160:163], v[192:195], v[40:43]
	v_mfma_f32_16x16x32_bf16 v[36:39], v[168:171], v[192:195], v[36:39]
	v_mfma_f32_16x16x32_bf16 v[24:27], v[160:163], v[200:203], v[24:27]
	v_mfma_f32_16x16x32_bf16 v[20:23], v[168:171], v[200:203], v[20:23]
	v_mfma_f32_16x16x32_bf16 v[8:11], v[160:163], v[208:211], v[8:11]
	v_mfma_f32_16x16x32_bf16 v[4:7], v[168:171], v[208:211], v[4:7]

	s_barrier
	s_add_i32 s33, 0, 0x18000
	s_add_i32 s44, 0, 0x1c000
	v_add_u32_e32 v80, s33, v214
	v_add_u32_e32 v168, s44, v214
	ds_read_b128 v[68:71], v80
	ds_read_b128 v[72:75], v80 offset:1024
	ds_read_b128 v[76:79], v80 offset:2048
	ds_read_b128 v[80:83], v80 offset:3072
	ds_read_b128 v[148:151], v168
	ds_read_b128 v[160:163], v168 offset:1024
	ds_read_b128 v[164:167], v168 offset:2048
	ds_read_b128 v[168:171], v168 offset:3072
	s_add_u32 s30, s30, 0x100000
	s_addc_u32 s31, s31, 0
	s_mov_b32 m0, s57
	v_lshl_add_u64 v[222:223], s[30:31], 0, v[180:181]
	ds_read_b128 v[172:175], v215 offset:32768
	ds_read_b128 v[176:179], v215 offset:33792
	ds_read_b128 v[188:191], v215 offset:34816
	ds_read_b128 v[192:195], v215 offset:35840
	ds_read_b128 v[196:199], v215 offset:36864
	ds_read_b128 v[200:203], v215 offset:37888
	ds_read_b128 v[204:207], v215 offset:38912
	ds_read_b128 v[208:211], v215 offset:39936
	global_load_lds_dwordx4 v[222:223], off
	v_lshl_add_u64 v[222:223], s[30:31], 0, v[152:153]
	s_mov_b32 m0, s58
	s_nop 0
	global_load_lds_dwordx4 v[222:223], off
	s_waitcnt vmcnt(8)
	s_waitcnt lgkmcnt(0)
	s_barrier

	s_waitcnt lgkmcnt(0)
	v_mfma_f32_16x16x32_bf16 v[144:147], v[68:71], v[172:175], v[144:147]
	v_mfma_f32_16x16x32_bf16 v[140:143], v[76:79], v[172:175], v[140:143]
	v_mfma_f32_16x16x32_bf16 v[136:139], v[68:71], v[188:191], v[136:139]
	v_mfma_f32_16x16x32_bf16 v[132:135], v[76:79], v[188:191], v[132:135]
	v_mfma_f32_16x16x32_bf16 v[112:115], v[68:71], v[196:199], v[112:115]
	v_mfma_f32_16x16x32_bf16 v[108:111], v[76:79], v[196:199], v[108:111]
	v_mfma_f32_16x16x32_bf16 v[104:107], v[68:71], v[204:207], v[104:107]
	v_mfma_f32_16x16x32_bf16 v[100:103], v[76:79], v[204:207], v[100:103]
	v_mfma_f32_16x16x32_bf16 v[144:147], v[72:75], v[176:179], v[144:147]
	v_mfma_f32_16x16x32_bf16 v[140:143], v[80:83], v[176:179], v[140:143]
	v_mfma_f32_16x16x32_bf16 v[136:139], v[72:75], v[192:195], v[136:139]
	v_mfma_f32_16x16x32_bf16 v[132:135], v[80:83], v[192:195], v[132:135]
	v_mfma_f32_16x16x32_bf16 v[112:115], v[72:75], v[200:203], v[112:115]
	v_mfma_f32_16x16x32_bf16 v[108:111], v[80:83], v[200:203], v[108:111]
	v_mfma_f32_16x16x32_bf16 v[104:107], v[72:75], v[208:211], v[104:107]
	v_mfma_f32_16x16x32_bf16 v[100:103], v[80:83], v[208:211], v[100:103]


	v_mfma_f32_16x16x32_bf16 v[128:131], v[148:151], v[172:175], v[128:131]
	v_mfma_f32_16x16x32_bf16 v[124:127], v[164:167], v[172:175], v[124:127]
	v_mfma_f32_16x16x32_bf16 v[120:123], v[148:151], v[188:191], v[120:123]
	v_mfma_f32_16x16x32_bf16 v[116:119], v[164:167], v[188:191], v[116:119]
	v_mfma_f32_16x16x32_bf16 v[96:99], v[148:151], v[196:199], v[96:99]
	v_mfma_f32_16x16x32_bf16 v[92:95], v[164:167], v[196:199], v[92:95]
	v_mfma_f32_16x16x32_bf16 v[88:91], v[148:151], v[204:207], v[88:91]
	v_mfma_f32_16x16x32_bf16 v[84:87], v[164:167], v[204:207], v[84:87]
	v_mfma_f32_16x16x32_bf16 v[128:131], v[160:163], v[176:179], v[128:131]
	v_mfma_f32_16x16x32_bf16 v[124:127], v[168:171], v[176:179], v[124:127]
	v_mfma_f32_16x16x32_bf16 v[120:123], v[160:163], v[192:195], v[120:123]
	v_mfma_f32_16x16x32_bf16 v[116:119], v[168:171], v[192:195], v[116:119]
	v_mfma_f32_16x16x32_bf16 v[96:99], v[160:163], v[200:203], v[96:99]
	v_mfma_f32_16x16x32_bf16 v[92:95], v[168:171], v[200:203], v[92:95]
	v_mfma_f32_16x16x32_bf16 v[88:91], v[160:163], v[208:211], v[88:91]
	v_mfma_f32_16x16x32_bf16 v[84:87], v[168:171], v[208:211], v[84:87]

	s_barrier
	s_add_i32 s30, s33, s41
	v_lshl_add_u64 v[212:213], v[212:213], 0, s[52:53]
	s_mov_b32 m0, s30
	ds_read_b128 v[172:175], v215 offset:49152
	ds_read_b128 v[176:179], v215 offset:50176
	ds_read_b128 v[188:191], v215 offset:51200
	ds_read_b128 v[192:195], v215 offset:52224
	ds_read_b128 v[196:199], v215 offset:53248
	ds_read_b128 v[200:203], v215 offset:54272
	ds_read_b128 v[204:207], v215 offset:55296
	ds_read_b128 v[208:211], v215 offset:56320
	global_load_lds_dwordx4 v[212:213], off
	s_add_i32 m0, s30, 0x2000
	s_add_u32 s28, s28, 0x100080
	v_lshl_add_u64 v[212:213], v[216:217], 0, s[52:53]
	s_addc_u32 s29, s29, 0
	s_add_i32 s30, s44, s41
	global_load_lds_dwordx4 v[212:213], off
	v_lshl_add_u64 v[212:213], s[28:29], 0, v[180:181]
	s_mov_b32 m0, s30
	s_nop 0
	global_load_lds_dwordx4 v[212:213], off
	v_lshl_add_u64 v[212:213], s[28:29], 0, v[152:153]
	s_add_i32 m0, s30, 0x2000
	s_nop 0
	global_load_lds_dwordx4 v[212:213], off
	v_lshl_add_u64 v[212:213], v[218:219], 0, s[52:53]
	s_mov_b32 m0, s83
	s_nop 0
	global_load_lds_dwordx4 v[212:213], off
	v_lshl_add_u64 v[212:213], v[220:221], 0, s[52:53]
	s_mov_b32 m0, s84
	s_nop 0
	global_load_lds_dwordx4 v[212:213], off
	s_waitcnt vmcnt(8)
	s_waitcnt lgkmcnt(0)
	s_barrier

	s_waitcnt lgkmcnt(0)
	v_mfma_f32_16x16x32_bf16 v[64:67], v[68:71], v[172:175], v[64:67]
	v_mfma_f32_16x16x32_bf16 v[60:63], v[76:79], v[172:175], v[60:63]
	v_mfma_f32_16x16x32_bf16 v[56:59], v[68:71], v[188:191], v[56:59]
	v_mfma_f32_16x16x32_bf16 v[52:55], v[76:79], v[188:191], v[52:55]
	v_mfma_f32_16x16x32_bf16 v[32:35], v[68:71], v[196:199], v[32:35]
	v_mfma_f32_16x16x32_bf16 v[28:31], v[76:79], v[196:199], v[28:31]
	v_mfma_f32_16x16x32_bf16 v[16:19], v[68:71], v[204:207], v[16:19]
	v_mfma_f32_16x16x32_bf16 v[12:15], v[76:79], v[204:207], v[12:15]
	v_mfma_f32_16x16x32_bf16 v[64:67], v[72:75], v[176:179], v[64:67]
	v_mfma_f32_16x16x32_bf16 v[60:63], v[80:83], v[176:179], v[60:63]
	v_mfma_f32_16x16x32_bf16 v[56:59], v[72:75], v[192:195], v[56:59]
	v_mfma_f32_16x16x32_bf16 v[52:55], v[80:83], v[192:195], v[52:55]
	v_mfma_f32_16x16x32_bf16 v[32:35], v[72:75], v[200:203], v[32:35]
	v_mfma_f32_16x16x32_bf16 v[28:31], v[80:83], v[200:203], v[28:31]
	v_mfma_f32_16x16x32_bf16 v[16:19], v[72:75], v[208:211], v[16:19]
	v_mfma_f32_16x16x32_bf16 v[12:15], v[80:83], v[208:211], v[12:15]


	v_mfma_f32_16x16x32_bf16 v[48:51], v[148:151], v[172:175], v[48:51]
	v_mfma_f32_16x16x32_bf16 v[44:47], v[164:167], v[172:175], v[44:47]
	v_mfma_f32_16x16x32_bf16 v[40:43], v[148:151], v[188:191], v[40:43]
	v_mfma_f32_16x16x32_bf16 v[36:39], v[164:167], v[188:191], v[36:39]
	v_mfma_f32_16x16x32_bf16 v[24:27], v[148:151], v[196:199], v[24:27]
	v_mfma_f32_16x16x32_bf16 v[20:23], v[164:167], v[196:199], v[20:23]
	v_mfma_f32_16x16x32_bf16 v[8:11], v[148:151], v[204:207], v[8:11]
	v_mfma_f32_16x16x32_bf16 v[4:7], v[164:167], v[204:207], v[4:7]
	v_mfma_f32_16x16x32_bf16 v[48:51], v[160:163], v[176:179], v[48:51]
	v_mfma_f32_16x16x32_bf16 v[44:47], v[168:171], v[176:179], v[44:47]
	v_mfma_f32_16x16x32_bf16 v[40:43], v[160:163], v[192:195], v[40:43]
	v_mfma_f32_16x16x32_bf16 v[36:39], v[168:171], v[192:195], v[36:39]
	v_mfma_f32_16x16x32_bf16 v[24:27], v[160:163], v[200:203], v[24:27]
	v_mfma_f32_16x16x32_bf16 v[20:23], v[168:171], v[200:203], v[20:23]
	v_mfma_f32_16x16x32_bf16 v[8:11], v[160:163], v[208:211], v[8:11]
	v_mfma_f32_16x16x32_bf16 v[4:7], v[168:171], v[208:211], v[4:7]

	s_barrier
	s_add_i32 s25, s25, 2
	s_add_u32 s26, s26, 0x100
	s_addc_u32 s27, s27, 0
	s_add_u32 s17, s17, 0x100
	s_addc_u32 s19, s19, 0
	s_cmp_gt_u32 s25, 61
	s_cbranch_scc0 .LBB0_32
	s_setprio 0
	s_and_b64 vcc, exec, s[12:13]
	s_cbranch_vccz .LBB0_35
	s_barrier

.LBB0_75:
	s_mov_b32 s18, s2
	s_ashr_i32 s19, s2, 31
	s_mov_b32 s14, s5
	s_mov_b32 s16, s4
	s_lshl_b64 s[4:5], s[18:19], 21
	s_add_u32 s2, s38, s4
	s_mov_b32 s6, s15
	s_addc_u32 s4, s39, s5
	s_ashr_i32 s15, s14, 31
	s_lshl_b64 s[24:25], s[14:15], 1
	s_add_u32 s22, s2, s24
	s_addc_u32 s23, s4, s25
	s_and_b64 s[4:5], s[20:21], exec
	s_cselect_b32 s2, s23, s31
	s_cselect_b32 s4, s22, s30
	s_ashr_i32 s17, s16, 31
	s_lshl_b64 s[36:37], s[16:17], 21
	s_add_u32 s5, s40, s36
	s_mov_b32 s97, s7
	s_addc_u32 s7, s41, s37
	s_add_u32 s24, s5, s24
	s_addc_u32 s25, s7, s25
	s_and_b64 s[36:37], s[20:21], exec
	s_cselect_b32 s5, s25, s35
	s_cselect_b32 s7, s24, s34
	s_add_i32 s15, s1, -2
	s_add_u32 s30, s30, 0x100080
	s_addc_u32 s31, s31, 0
	s_add_u32 s17, s34, 0x100
	v_mov_b32_e32 v4, 0
	s_addc_u32 s19, s35, 0
	s_mov_b32 s27, 0
	v_mov_b32_e32 v5, v4
	v_mov_b32_e32 v6, v4
	v_mov_b32_e32 v7, v4
	v_mov_b32_e32 v8, v4
	v_mov_b32_e32 v9, v4
	v_mov_b32_e32 v10, v4
	v_mov_b32_e32 v11, v4
	v_mov_b32_e32 v20, v4
	v_mov_b32_e32 v21, v4
	v_mov_b32_e32 v22, v4
	v_mov_b32_e32 v23, v4
	v_mov_b32_e32 v24, v4
	v_mov_b32_e32 v25, v4
	v_mov_b32_e32 v26, v4
	v_mov_b32_e32 v27, v4
	v_mov_b32_e32 v36, v4
	v_mov_b32_e32 v37, v4
	v_mov_b32_e32 v38, v4
	v_mov_b32_e32 v39, v4
	v_mov_b32_e32 v40, v4
	v_mov_b32_e32 v41, v4
	v_mov_b32_e32 v42, v4
	v_mov_b32_e32 v43, v4
	v_mov_b32_e32 v44, v4
	v_mov_b32_e32 v45, v4
	v_mov_b32_e32 v46, v4
	v_mov_b32_e32 v47, v4
	v_mov_b32_e32 v48, v4
	v_mov_b32_e32 v49, v4
	v_mov_b32_e32 v50, v4
	v_mov_b32_e32 v51, v4
	v_mov_b32_e32 v12, v4
	v_mov_b32_e32 v13, v4
	v_mov_b32_e32 v14, v4
	v_mov_b32_e32 v15, v4
	v_mov_b32_e32 v16, v4
	v_mov_b32_e32 v17, v4
	v_mov_b32_e32 v18, v4
	v_mov_b32_e32 v19, v4
	v_mov_b32_e32 v28, v4
	v_mov_b32_e32 v29, v4
	v_mov_b32_e32 v30, v4
	v_mov_b32_e32 v31, v4
	v_mov_b32_e32 v32, v4
	v_mov_b32_e32 v33, v4
	v_mov_b32_e32 v34, v4
	v_mov_b32_e32 v35, v4
	v_mov_b32_e32 v52, v4
	v_mov_b32_e32 v53, v4
	v_mov_b32_e32 v54, v4
	v_mov_b32_e32 v55, v4
	v_mov_b32_e32 v56, v4
	v_mov_b32_e32 v57, v4
	v_mov_b32_e32 v58, v4
	v_mov_b32_e32 v59, v4
	v_mov_b32_e32 v60, v4
	v_mov_b32_e32 v61, v4
	v_mov_b32_e32 v62, v4
	v_mov_b32_e32 v63, v4
	v_mov_b32_e32 v64, v4
	v_mov_b32_e32 v65, v4
	v_mov_b32_e32 v66, v4
	v_mov_b32_e32 v67, v4
	s_waitcnt vmcnt(0)
	v_mov_b32_e32 v68, v4
	v_mov_b32_e32 v69, v4
	v_mov_b32_e32 v70, v4
	v_mov_b32_e32 v71, v4
	v_mov_b32_e32 v72, v4
	v_mov_b32_e32 v73, v4
	v_mov_b32_e32 v74, v4
	v_mov_b32_e32 v75, v4
	v_mov_b32_e32 v80, v4
	v_mov_b32_e32 v81, v4
	v_mov_b32_e32 v82, v4
	v_mov_b32_e32 v83, v4
	v_mov_b32_e32 v88, v4
	v_mov_b32_e32 v89, v4
	v_mov_b32_e32 v90, v4
	v_mov_b32_e32 v91, v4
	v_mov_b32_e32 v116, v4
	v_mov_b32_e32 v117, v4
	v_mov_b32_e32 v118, v4
	v_mov_b32_e32 v119, v4
	v_mov_b32_e32 v120, v4
	v_mov_b32_e32 v121, v4
	v_mov_b32_e32 v122, v4
	v_mov_b32_e32 v123, v4
	v_mov_b32_e32 v124, v4
	v_mov_b32_e32 v125, v4
	v_mov_b32_e32 v126, v4
	v_mov_b32_e32 v127, v4
	v_mov_b32_e32 v128, v4
	v_mov_b32_e32 v129, v4
	v_mov_b32_e32 v130, v4
	v_mov_b32_e32 v131, v4
	v_mov_b32_e32 v92, v4
	v_mov_b32_e32 v93, v4
	v_mov_b32_e32 v94, v4
	v_mov_b32_e32 v95, v4
	v_mov_b32_e32 v100, v4
	v_mov_b32_e32 v101, v4
	v_mov_b32_e32 v102, v4
	v_mov_b32_e32 v103, v4
	v_mov_b32_e32 v104, v4
	v_mov_b32_e32 v105, v4
	v_mov_b32_e32 v106, v4
	v_mov_b32_e32 v107, v4
	v_mov_b32_e32 v108, v4
	v_mov_b32_e32 v109, v4
	v_mov_b32_e32 v110, v4
	v_mov_b32_e32 v111, v4
	v_mov_b32_e32 v132, v4
	v_mov_b32_e32 v133, v4
	v_mov_b32_e32 v134, v4
	v_mov_b32_e32 v135, v4
	v_mov_b32_e32 v136, v4
	v_mov_b32_e32 v137, v4
	v_mov_b32_e32 v138, v4
	v_mov_b32_e32 v139, v4
	v_mov_b32_e32 v140, v4
	v_mov_b32_e32 v141, v4
	v_mov_b32_e32 v142, v4
	v_mov_b32_e32 v143, v4
	v_mov_b32_e32 v144, v4
	v_mov_b32_e32 v145, v4
	v_mov_b32_e32 v146, v4
	v_mov_b32_e32 v147, v4
	v_readfirstlane_b32 s101, v186
	s_nop 3
	s_lshr_b32 s101, s101, 8
	s_cmp_eq_u32 s101, 1
	s_cbranch_scc0 .Lprio_1
	s_setprio 1
.Lprio_1:
.LBB0_76:
	s_add_i32 s29, s27, 2
	s_add_u32 s33, s30, 0xfff00080
	s_addc_u32 s34, s31, -1
	s_add_i32 s44, 0, 0x10000
	s_cmp_eq_u32 s15, s27
	s_cselect_b32 s37, s2, s34
	s_cselect_b32 s36, s4, s33
	s_cselect_b32 s35, s5, s19
	s_cselect_b32 s34, s7, s17
	s_add_i32 s27, 0, 0x14000
	v_add_u32_e32 v112, s44, v212
	v_add_u32_e32 v166, s27, v212
	ds_read_b128 v[76:79], v112
	ds_read_b128 v[84:87], v112 offset:1024
	ds_read_b128 v[96:99], v112 offset:2048
	ds_read_b128 v[112:115], v112 offset:3072
	ds_read_b128 v[148:151], v166
	ds_read_b128 v[158:161], v166 offset:1024
	ds_read_b128 v[162:165], v166 offset:2048
	ds_read_b128 v[166:169], v166 offset:3072
	v_lshl_add_u64 v[178:179], s[30:31], 0, v[154:155]
	s_add_i32 m0, s43, 0xc000
	ds_read_b128 v[170:173], v213
	ds_read_b128 v[174:177], v213 offset:1024
	ds_read_b128 v[188:191], v213 offset:2048
	ds_read_b128 v[192:195], v213 offset:3072
	ds_read_b128 v[196:199], v213 offset:4096
	ds_read_b128 v[200:203], v213 offset:5120
	ds_read_b128 v[204:207], v213 offset:6144
	ds_read_b128 v[208:211], v213 offset:7168
	global_load_lds_dwordx4 v[178:179], off
	v_lshl_add_u64 v[178:179], s[30:31], 0, v[156:157]
	s_add_i32 m0, s43, 0xe000
	s_nop 0
	global_load_lds_dwordx4 v[178:179], off
	s_waitcnt vmcnt(8)
	s_waitcnt lgkmcnt(0)
	s_barrier

	s_waitcnt lgkmcnt(0)
	v_mfma_f32_16x16x32_bf16 v[144:147], v[76:79], v[170:173], v[144:147]
	v_mfma_f32_16x16x32_bf16 v[140:143], v[96:99], v[170:173], v[140:143]
	v_mfma_f32_16x16x32_bf16 v[136:139], v[76:79], v[188:191], v[136:139]
	v_mfma_f32_16x16x32_bf16 v[132:135], v[96:99], v[188:191], v[132:135]
	v_mfma_f32_16x16x32_bf16 v[108:111], v[76:79], v[196:199], v[108:111]
	v_mfma_f32_16x16x32_bf16 v[104:107], v[96:99], v[196:199], v[104:107]
	v_mfma_f32_16x16x32_bf16 v[100:103], v[76:79], v[204:207], v[100:103]
	v_mfma_f32_16x16x32_bf16 v[92:95], v[96:99], v[204:207], v[92:95]
	v_mfma_f32_16x16x32_bf16 v[144:147], v[84:87], v[174:177], v[144:147]
	v_mfma_f32_16x16x32_bf16 v[140:143], v[112:115], v[174:177], v[140:143]
	v_mfma_f32_16x16x32_bf16 v[136:139], v[84:87], v[192:195], v[136:139]
	v_mfma_f32_16x16x32_bf16 v[132:135], v[112:115], v[192:195], v[132:135]
	v_mfma_f32_16x16x32_bf16 v[108:111], v[84:87], v[200:203], v[108:111]
	v_mfma_f32_16x16x32_bf16 v[104:107], v[112:115], v[200:203], v[104:107]
	v_mfma_f32_16x16x32_bf16 v[100:103], v[84:87], v[208:211], v[100:103]
	v_mfma_f32_16x16x32_bf16 v[92:95], v[112:115], v[208:211], v[92:95]


	v_mfma_f32_16x16x32_bf16 v[128:131], v[148:151], v[170:173], v[128:131]
	v_mfma_f32_16x16x32_bf16 v[124:127], v[162:165], v[170:173], v[124:127]
	v_mfma_f32_16x16x32_bf16 v[120:123], v[148:151], v[188:191], v[120:123]
	v_mfma_f32_16x16x32_bf16 v[116:119], v[162:165], v[188:191], v[116:119]
	v_mfma_f32_16x16x32_bf16 v[88:91], v[148:151], v[196:199], v[88:91]
	v_mfma_f32_16x16x32_bf16 v[80:83], v[162:165], v[196:199], v[80:83]
	v_mfma_f32_16x16x32_bf16 v[72:75], v[148:151], v[204:207], v[72:75]
	v_mfma_f32_16x16x32_bf16 v[68:71], v[162:165], v[204:207], v[68:71]
	v_mfma_f32_16x16x32_bf16 v[128:131], v[158:161], v[174:177], v[128:131]
	v_mfma_f32_16x16x32_bf16 v[124:127], v[166:169], v[174:177], v[124:127]
	v_mfma_f32_16x16x32_bf16 v[120:123], v[158:161], v[192:195], v[120:123]
	v_mfma_f32_16x16x32_bf16 v[116:119], v[166:169], v[192:195], v[116:119]
	v_mfma_f32_16x16x32_bf16 v[88:91], v[158:161], v[200:203], v[88:91]
	v_mfma_f32_16x16x32_bf16 v[80:83], v[166:169], v[200:203], v[80:83]
	v_mfma_f32_16x16x32_bf16 v[72:75], v[158:161], v[208:211], v[72:75]
	v_mfma_f32_16x16x32_bf16 v[68:71], v[166:169], v[208:211], v[68:71]

	s_barrier
	s_add_i32 s33, s44, s42
	v_lshl_add_u64 v[178:179], s[34:35], 0, v[180:181]
	s_mov_b32 m0, s33
	ds_read_b128 v[170:173], v213 offset:16384
	ds_read_b128 v[174:177], v213 offset:17408
	ds_read_b128 v[188:191], v213 offset:18432
	ds_read_b128 v[192:195], v213 offset:19456
	ds_read_b128 v[196:199], v213 offset:20480
	ds_read_b128 v[200:203], v213 offset:21504
	ds_read_b128 v[204:207], v213 offset:22528
	ds_read_b128 v[208:211], v213 offset:23552
	global_load_lds_dwordx4 v[178:179], off
	s_add_i32 m0, s33, 0x2000
	s_add_u32 s44, s34, 0x100000
	v_lshl_add_u64 v[214:215], s[34:35], 0, v[152:153]
	s_addc_u32 s45, s35, 0
	s_add_i32 s27, s27, s42
	global_load_lds_dwordx4 v[214:215], off
	v_lshl_add_u64 v[216:217], s[44:45], 0, v[180:181]
	s_mov_b32 m0, s27
	v_lshl_add_u64 v[218:219], s[36:37], 0, v[152:153]
	global_load_lds_dwordx4 v[216:217], off
	v_lshl_add_u64 v[216:217], s[44:45], 0, v[152:153]
	s_add_i32 m0, s27, 0x2000
	s_nop 0
	global_load_lds_dwordx4 v[216:217], off
	v_lshl_add_u64 v[216:217], s[36:37], 0, v[180:181]
	s_mov_b32 m0, s43
	s_nop 0
	global_load_lds_dwordx4 v[216:217], off
	s_mov_b32 m0, s50
	s_nop 0
	global_load_lds_dwordx4 v[218:219], off
	s_waitcnt vmcnt(8)
	s_waitcnt lgkmcnt(0)
	s_barrier

	s_waitcnt lgkmcnt(0)
	v_mfma_f32_16x16x32_bf16 v[64:67], v[76:79], v[170:173], v[64:67]
	v_mfma_f32_16x16x32_bf16 v[60:63], v[96:99], v[170:173], v[60:63]
	v_mfma_f32_16x16x32_bf16 v[56:59], v[76:79], v[188:191], v[56:59]
	v_mfma_f32_16x16x32_bf16 v[52:55], v[96:99], v[188:191], v[52:55]
	v_mfma_f32_16x16x32_bf16 v[32:35], v[76:79], v[196:199], v[32:35]
	v_mfma_f32_16x16x32_bf16 v[28:31], v[96:99], v[196:199], v[28:31]
	v_mfma_f32_16x16x32_bf16 v[16:19], v[76:79], v[204:207], v[16:19]
	v_mfma_f32_16x16x32_bf16 v[12:15], v[96:99], v[204:207], v[12:15]
	v_mfma_f32_16x16x32_bf16 v[64:67], v[84:87], v[174:177], v[64:67]
	v_mfma_f32_16x16x32_bf16 v[60:63], v[112:115], v[174:177], v[60:63]
	v_mfma_f32_16x16x32_bf16 v[56:59], v[84:87], v[192:195], v[56:59]
	v_mfma_f32_16x16x32_bf16 v[52:55], v[112:115], v[192:195], v[52:55]
	v_mfma_f32_16x16x32_bf16 v[32:35], v[84:87], v[200:203], v[32:35]
	v_mfma_f32_16x16x32_bf16 v[28:31], v[112:115], v[200:203], v[28:31]
	v_mfma_f32_16x16x32_bf16 v[16:19], v[84:87], v[208:211], v[16:19]
	v_mfma_f32_16x16x32_bf16 v[12:15], v[112:115], v[208:211], v[12:15]


	v_mfma_f32_16x16x32_bf16 v[48:51], v[148:151], v[170:173], v[48:51]
	v_mfma_f32_16x16x32_bf16 v[44:47], v[162:165], v[170:173], v[44:47]
	v_mfma_f32_16x16x32_bf16 v[40:43], v[148:151], v[188:191], v[40:43]
	v_mfma_f32_16x16x32_bf16 v[36:39], v[162:165], v[188:191], v[36:39]
	v_mfma_f32_16x16x32_bf16 v[24:27], v[148:151], v[196:199], v[24:27]
	v_mfma_f32_16x16x32_bf16 v[20:23], v[162:165], v[196:199], v[20:23]
	v_mfma_f32_16x16x32_bf16 v[8:11], v[148:151], v[204:207], v[8:11]
	v_mfma_f32_16x16x32_bf16 v[4:7], v[162:165], v[204:207], v[4:7]
	v_mfma_f32_16x16x32_bf16 v[48:51], v[158:161], v[174:177], v[48:51]
	v_mfma_f32_16x16x32_bf16 v[44:47], v[166:169], v[174:177], v[44:47]
	v_mfma_f32_16x16x32_bf16 v[40:43], v[158:161], v[192:195], v[40:43]
	v_mfma_f32_16x16x32_bf16 v[36:39], v[166:169], v[192:195], v[36:39]
	v_mfma_f32_16x16x32_bf16 v[24:27], v[158:161], v[200:203], v[24:27]
	v_mfma_f32_16x16x32_bf16 v[20:23], v[166:169], v[200:203], v[20:23]
	v_mfma_f32_16x16x32_bf16 v[8:11], v[158:161], v[208:211], v[8:11]
	v_mfma_f32_16x16x32_bf16 v[4:7], v[166:169], v[208:211], v[4:7]

	s_barrier
	s_add_i32 s27, 0, 0x18000
	s_add_i32 s33, 0, 0x1c000
	v_add_u32_e32 v112, s27, v212
	v_add_u32_e32 v166, s33, v212
	ds_read_b128 v[76:79], v112
	ds_read_b128 v[84:87], v112 offset:1024
	ds_read_b128 v[96:99], v112 offset:2048
	ds_read_b128 v[112:115], v112 offset:3072
	ds_read_b128 v[148:151], v166
	ds_read_b128 v[158:161], v166 offset:1024
	ds_read_b128 v[162:165], v166 offset:2048
	ds_read_b128 v[166:169], v166 offset:3072
	s_add_u32 s36, s36, 0x100000
	s_addc_u32 s37, s37, 0
	s_mov_b32 m0, s51
	v_lshl_add_u64 v[220:221], s[36:37], 0, v[180:181]
	ds_read_b128 v[170:173], v213 offset:32768
	ds_read_b128 v[174:177], v213 offset:33792
	ds_read_b128 v[188:191], v213 offset:34816
	ds_read_b128 v[192:195], v213 offset:35840
	ds_read_b128 v[196:199], v213 offset:36864
	ds_read_b128 v[200:203], v213 offset:37888
	ds_read_b128 v[204:207], v213 offset:38912
	ds_read_b128 v[208:211], v213 offset:39936
	global_load_lds_dwordx4 v[220:221], off
	v_lshl_add_u64 v[220:221], s[36:37], 0, v[152:153]
	s_mov_b32 m0, s57
	s_nop 0
	global_load_lds_dwordx4 v[220:221], off
	s_waitcnt vmcnt(8)
	s_waitcnt lgkmcnt(0)
	s_barrier

	s_waitcnt lgkmcnt(0)
	v_mfma_f32_16x16x32_bf16 v[144:147], v[76:79], v[170:173], v[144:147]
	v_mfma_f32_16x16x32_bf16 v[140:143], v[96:99], v[170:173], v[140:143]
	v_mfma_f32_16x16x32_bf16 v[136:139], v[76:79], v[188:191], v[136:139]
	v_mfma_f32_16x16x32_bf16 v[132:135], v[96:99], v[188:191], v[132:135]
	v_mfma_f32_16x16x32_bf16 v[108:111], v[76:79], v[196:199], v[108:111]
	v_mfma_f32_16x16x32_bf16 v[104:107], v[96:99], v[196:199], v[104:107]
	v_mfma_f32_16x16x32_bf16 v[100:103], v[76:79], v[204:207], v[100:103]
	v_mfma_f32_16x16x32_bf16 v[92:95], v[96:99], v[204:207], v[92:95]
	v_mfma_f32_16x16x32_bf16 v[144:147], v[84:87], v[174:177], v[144:147]
	v_mfma_f32_16x16x32_bf16 v[140:143], v[112:115], v[174:177], v[140:143]
	v_mfma_f32_16x16x32_bf16 v[136:139], v[84:87], v[192:195], v[136:139]
	v_mfma_f32_16x16x32_bf16 v[132:135], v[112:115], v[192:195], v[132:135]
	v_mfma_f32_16x16x32_bf16 v[108:111], v[84:87], v[200:203], v[108:111]
	v_mfma_f32_16x16x32_bf16 v[104:107], v[112:115], v[200:203], v[104:107]
	v_mfma_f32_16x16x32_bf16 v[100:103], v[84:87], v[208:211], v[100:103]
	v_mfma_f32_16x16x32_bf16 v[92:95], v[112:115], v[208:211], v[92:95]


	v_mfma_f32_16x16x32_bf16 v[128:131], v[148:151], v[170:173], v[128:131]
	v_mfma_f32_16x16x32_bf16 v[124:127], v[162:165], v[170:173], v[124:127]
	v_mfma_f32_16x16x32_bf16 v[120:123], v[148:151], v[188:191], v[120:123]
	v_mfma_f32_16x16x32_bf16 v[116:119], v[162:165], v[188:191], v[116:119]
	v_mfma_f32_16x16x32_bf16 v[88:91], v[148:151], v[196:199], v[88:91]
	v_mfma_f32_16x16x32_bf16 v[80:83], v[162:165], v[196:199], v[80:83]
	v_mfma_f32_16x16x32_bf16 v[72:75], v[148:151], v[204:207], v[72:75]
	v_mfma_f32_16x16x32_bf16 v[68:71], v[162:165], v[204:207], v[68:71]
	v_mfma_f32_16x16x32_bf16 v[128:131], v[158:161], v[174:177], v[128:131]
	v_mfma_f32_16x16x32_bf16 v[124:127], v[166:169], v[174:177], v[124:127]
	v_mfma_f32_16x16x32_bf16 v[120:123], v[158:161], v[192:195], v[120:123]
	v_mfma_f32_16x16x32_bf16 v[116:119], v[166:169], v[192:195], v[116:119]
	v_mfma_f32_16x16x32_bf16 v[88:91], v[158:161], v[200:203], v[88:91]
	v_mfma_f32_16x16x32_bf16 v[80:83], v[166:169], v[200:203], v[80:83]
	v_mfma_f32_16x16x32_bf16 v[72:75], v[158:161], v[208:211], v[72:75]
	v_mfma_f32_16x16x32_bf16 v[68:71], v[166:169], v[208:211], v[68:71]

	s_barrier
	s_add_i32 s27, s27, s42
	v_lshl_add_u64 v[178:179], v[178:179], 0, s[52:53]
	s_mov_b32 m0, s27
	ds_read_b128 v[170:173], v213 offset:49152
	ds_read_b128 v[174:177], v213 offset:50176
	ds_read_b128 v[188:191], v213 offset:51200
	ds_read_b128 v[192:195], v213 offset:52224
	ds_read_b128 v[196:199], v213 offset:53248
	ds_read_b128 v[200:203], v213 offset:54272
	ds_read_b128 v[204:207], v213 offset:55296
	ds_read_b128 v[208:211], v213 offset:56320
	global_load_lds_dwordx4 v[178:179], off
	s_add_i32 m0, s27, 0x2000
	s_add_u32 s34, s34, 0x100080
	v_lshl_add_u64 v[178:179], v[214:215], 0, s[52:53]
	s_addc_u32 s35, s35, 0
	s_add_i32 s27, s33, s42
	global_load_lds_dwordx4 v[178:179], off
	v_lshl_add_u64 v[178:179], s[34:35], 0, v[180:181]
	s_mov_b32 m0, s27
	s_nop 0
	global_load_lds_dwordx4 v[178:179], off
	v_lshl_add_u64 v[178:179], s[34:35], 0, v[152:153]
	s_add_i32 m0, s27, 0x2000
	s_nop 0
	global_load_lds_dwordx4 v[178:179], off
	v_lshl_add_u64 v[178:179], v[216:217], 0, s[52:53]
	s_mov_b32 m0, s84
	s_nop 0
	global_load_lds_dwordx4 v[178:179], off
	v_lshl_add_u64 v[178:179], v[218:219], 0, s[52:53]
	s_mov_b32 m0, s85
	s_nop 0
	global_load_lds_dwordx4 v[178:179], off
	s_waitcnt vmcnt(8)
	s_waitcnt lgkmcnt(0)
	s_barrier

	s_waitcnt lgkmcnt(0)
	v_mfma_f32_16x16x32_bf16 v[64:67], v[76:79], v[170:173], v[64:67]
	v_mfma_f32_16x16x32_bf16 v[60:63], v[96:99], v[170:173], v[60:63]
	v_mfma_f32_16x16x32_bf16 v[56:59], v[76:79], v[188:191], v[56:59]
	v_mfma_f32_16x16x32_bf16 v[52:55], v[96:99], v[188:191], v[52:55]
	v_mfma_f32_16x16x32_bf16 v[32:35], v[76:79], v[196:199], v[32:35]
	v_mfma_f32_16x16x32_bf16 v[28:31], v[96:99], v[196:199], v[28:31]
	v_mfma_f32_16x16x32_bf16 v[16:19], v[76:79], v[204:207], v[16:19]
	v_mfma_f32_16x16x32_bf16 v[12:15], v[96:99], v[204:207], v[12:15]
	v_mfma_f32_16x16x32_bf16 v[64:67], v[84:87], v[174:177], v[64:67]
	v_mfma_f32_16x16x32_bf16 v[60:63], v[112:115], v[174:177], v[60:63]
	v_mfma_f32_16x16x32_bf16 v[56:59], v[84:87], v[192:195], v[56:59]
	v_mfma_f32_16x16x32_bf16 v[52:55], v[112:115], v[192:195], v[52:55]
	v_mfma_f32_16x16x32_bf16 v[32:35], v[84:87], v[200:203], v[32:35]
	v_mfma_f32_16x16x32_bf16 v[28:31], v[112:115], v[200:203], v[28:31]
	v_mfma_f32_16x16x32_bf16 v[16:19], v[84:87], v[208:211], v[16:19]
	v_mfma_f32_16x16x32_bf16 v[12:15], v[112:115], v[208:211], v[12:15]


	v_mfma_f32_16x16x32_bf16 v[48:51], v[148:151], v[170:173], v[48:51]
	v_mfma_f32_16x16x32_bf16 v[44:47], v[162:165], v[170:173], v[44:47]
	v_mfma_f32_16x16x32_bf16 v[40:43], v[148:151], v[188:191], v[40:43]
	v_mfma_f32_16x16x32_bf16 v[36:39], v[162:165], v[188:191], v[36:39]
	v_mfma_f32_16x16x32_bf16 v[24:27], v[148:151], v[196:199], v[24:27]
	v_mfma_f32_16x16x32_bf16 v[20:23], v[162:165], v[196:199], v[20:23]
	v_mfma_f32_16x16x32_bf16 v[8:11], v[148:151], v[204:207], v[8:11]
	v_mfma_f32_16x16x32_bf16 v[4:7], v[162:165], v[204:207], v[4:7]
	v_mfma_f32_16x16x32_bf16 v[48:51], v[158:161], v[174:177], v[48:51]
	v_mfma_f32_16x16x32_bf16 v[44:47], v[166:169], v[174:177], v[44:47]
	v_mfma_f32_16x16x32_bf16 v[40:43], v[158:161], v[192:195], v[40:43]
	v_mfma_f32_16x16x32_bf16 v[36:39], v[166:169], v[192:195], v[36:39]
	v_mfma_f32_16x16x32_bf16 v[24:27], v[158:161], v[200:203], v[24:27]
	v_mfma_f32_16x16x32_bf16 v[20:23], v[166:169], v[200:203], v[20:23]
	v_mfma_f32_16x16x32_bf16 v[8:11], v[158:161], v[208:211], v[8:11]
	v_mfma_f32_16x16x32_bf16 v[4:7], v[166:169], v[208:211], v[4:7]

	s_barrier
	s_add_u32 s30, s30, 0x100
	s_addc_u32 s31, s31, 0
	s_add_u32 s17, s17, 0x100
	s_addc_u32 s19, s19, 0
	s_cmp_ge_i32 s29, s1
	s_mov_b32 s27, s29
	s_cbranch_scc0 .LBB0_76
	s_setprio 0
	s_and_b64 vcc, exec, s[10:11]
	s_cbranch_vccz .LBB0_79
	s_barrier

.LBB0_104:
	s_ashr_i32 s17, s16, 31
	s_lshl_b64 s[4:5], s[16:17], 19
	s_add_u32 s18, s0, s4
	s_addc_u32 s19, s2, s5
	s_and_b64 s[4:5], s[6:7], exec
	s_cselect_b32 s4, s19, s25
	s_cselect_b32 s5, s18, s24
	s_ashr_i32 s15, s14, 31
	s_lshl_b64 s[20:21], s[14:15], 19
	s_add_u32 s20, s30, s20
	s_addc_u32 s21, s31, s21
	s_and_b64 s[28:29], s[6:7], exec
	s_cselect_b32 s15, s21, s27
	s_cselect_b32 s17, s20, s26
	s_add_u32 s24, s24, 0x40080
	s_addc_u32 s25, s25, 0
	s_add_u32 s50, s26, 0x100
	s_addc_u32 s51, s27, 0
	s_mov_b32 s54, -2
	v_readfirstlane_b32 s101, v186
	s_nop 3
	s_lshr_b32 s101, s101, 8
	s_cmp_eq_u32 s101, 1
	s_cbranch_scc0 .Lprio_2
	s_setprio 1
.Lprio_2:
	s_add_u32 s26, s24, 0xfffc0080
	s_addc_u32 s27, s25, -1
	s_add_i32 s55, 0, 0x10000
	s_cmp_eq_u32 s54, 12
	s_cselect_b32 s29, s4, s27
	s_cselect_b32 s28, s5, s26
	v_add_u32_e32 v142, s55, v146
	s_cselect_b32 s27, s15, s51
	s_cselect_b32 s26, s17, s50
	s_add_i32 s57, 0, 0x14000
	ds_read_b128 v[148:151], v142
	ds_read_b128 v[152:155], v142 offset:1024
	ds_read_b128 v[156:159], v142 offset:2048
	ds_read_b128 v[160:163], v142 offset:3072
	v_add_u32_e32 v142, s57, v146
	ds_read_b128 v[164:167], v142
	ds_read_b128 v[168:171], v142 offset:1024
	ds_read_b128 v[172:175], v142 offset:2048
	ds_read_b128 v[176:179], v142 offset:3072
	v_lshl_add_u64 v[142:143], s[24:25], 0, v[138:139]
	s_add_i32 m0, s1, 0xc000
	ds_read_b128 v[188:191], v147
	ds_read_b128 v[192:195], v147 offset:1024
	ds_read_b128 v[196:199], v147 offset:2048
	ds_read_b128 v[200:203], v147 offset:3072
	ds_read_b128 v[204:207], v147 offset:4096
	ds_read_b128 v[208:211], v147 offset:5120
	ds_read_b128 v[212:215], v147 offset:6144
	ds_read_b128 v[216:219], v147 offset:7168
	global_load_lds_dwordx4 v[142:143], off
	v_lshl_add_u64 v[142:143], s[24:25], 0, v[140:141]
	s_add_i32 m0, s1, 0xe000
	s_nop 0
	global_load_lds_dwordx4 v[142:143], off
	s_waitcnt vmcnt(24)
	s_waitcnt lgkmcnt(0)
	s_barrier

	s_waitcnt lgkmcnt(0)
	v_mfma_f32_16x16x32_bf16 v[128:131], v[148:151], v[188:191], 0
	v_mfma_f32_16x16x32_bf16 v[124:127], v[156:159], v[188:191], 0
	v_mfma_f32_16x16x32_bf16 v[112:115], v[148:151], v[196:199], 0
	v_mfma_f32_16x16x32_bf16 v[108:111], v[156:159], v[196:199], 0
	v_mfma_f32_16x16x32_bf16 v[96:99], v[148:151], v[204:207], 0
	v_mfma_f32_16x16x32_bf16 v[92:95], v[156:159], v[204:207], 0
	v_mfma_f32_16x16x32_bf16 v[80:83], v[148:151], v[212:215], 0
	v_mfma_f32_16x16x32_bf16 v[76:79], v[156:159], v[212:215], 0
	v_mfma_f32_16x16x32_bf16 v[128:131], v[152:155], v[192:195], v[128:131]
	v_mfma_f32_16x16x32_bf16 v[124:127], v[160:163], v[192:195], v[124:127]
	v_mfma_f32_16x16x32_bf16 v[112:115], v[152:155], v[200:203], v[112:115]
	v_mfma_f32_16x16x32_bf16 v[108:111], v[160:163], v[200:203], v[108:111]
	v_mfma_f32_16x16x32_bf16 v[96:99], v[152:155], v[208:211], v[96:99]
	v_mfma_f32_16x16x32_bf16 v[92:95], v[160:163], v[208:211], v[92:95]
	v_mfma_f32_16x16x32_bf16 v[80:83], v[152:155], v[216:219], v[80:83]
	v_mfma_f32_16x16x32_bf16 v[76:79], v[160:163], v[216:219], v[76:79]


	v_mfma_f32_16x16x32_bf16 v[120:123], v[164:167], v[188:191], 0
	v_mfma_f32_16x16x32_bf16 v[116:119], v[172:175], v[188:191], 0
	v_mfma_f32_16x16x32_bf16 v[104:107], v[164:167], v[196:199], 0
	v_mfma_f32_16x16x32_bf16 v[100:103], v[172:175], v[196:199], 0
	v_mfma_f32_16x16x32_bf16 v[88:91], v[164:167], v[204:207], 0
	v_mfma_f32_16x16x32_bf16 v[84:87], v[172:175], v[204:207], 0
	v_mfma_f32_16x16x32_bf16 v[72:75], v[164:167], v[212:215], 0
	v_mfma_f32_16x16x32_bf16 v[68:71], v[172:175], v[212:215], 0
	v_mfma_f32_16x16x32_bf16 v[120:123], v[168:171], v[192:195], v[120:123]
	v_mfma_f32_16x16x32_bf16 v[116:119], v[176:179], v[192:195], v[116:119]
	v_mfma_f32_16x16x32_bf16 v[104:107], v[168:171], v[200:203], v[104:107]
	v_mfma_f32_16x16x32_bf16 v[100:103], v[176:179], v[200:203], v[100:103]
	v_mfma_f32_16x16x32_bf16 v[88:91], v[168:171], v[208:211], v[88:91]
	v_mfma_f32_16x16x32_bf16 v[84:87], v[176:179], v[208:211], v[84:87]
	v_mfma_f32_16x16x32_bf16 v[72:75], v[168:171], v[216:219], v[72:75]
	v_mfma_f32_16x16x32_bf16 v[68:71], v[176:179], v[216:219], v[68:71]

	s_barrier
	s_add_i32 s55, s55, s35
	v_lshl_add_u64 v[142:143], s[26:27], 0, v[180:181]
	s_mov_b32 m0, s55
	ds_read_b128 v[188:191], v147 offset:16384
	ds_read_b128 v[192:195], v147 offset:17408
	ds_read_b128 v[196:199], v147 offset:18432
	ds_read_b128 v[200:203], v147 offset:19456
	ds_read_b128 v[204:207], v147 offset:20480
	ds_read_b128 v[208:211], v147 offset:21504
	ds_read_b128 v[212:215], v147 offset:22528
	ds_read_b128 v[216:219], v147 offset:23552
	global_load_lds_dwordx4 v[142:143], off
	s_add_i32 m0, s55, 0x2000
	s_add_u32 s58, s26, 0x40000
	v_lshl_add_u64 v[220:221], s[26:27], 0, v[132:133]
	s_addc_u32 s59, s27, 0
	s_add_i32 s55, s57, s35
	global_load_lds_dwordx4 v[220:221], off
	v_lshl_add_u64 v[222:223], s[58:59], 0, v[180:181]
	s_mov_b32 m0, s55
	v_lshl_add_u64 v[224:225], s[28:29], 0, v[134:135]
	global_load_lds_dwordx4 v[222:223], off
	v_lshl_add_u64 v[222:223], s[58:59], 0, v[132:133]
	s_add_i32 m0, s55, 0x2000
	s_nop 0
	global_load_lds_dwordx4 v[222:223], off
	v_lshl_add_u64 v[222:223], s[28:29], 0, v[136:137]
	s_mov_b32 m0, s1
	s_nop 0
	global_load_lds_dwordx4 v[222:223], off
	s_mov_b32 m0, s23
	s_nop 0
	global_load_lds_dwordx4 v[224:225], off
	s_waitcnt vmcnt(24)
	s_waitcnt lgkmcnt(0)
	s_barrier

	s_waitcnt lgkmcnt(0)
	v_mfma_f32_16x16x32_bf16 v[64:67], v[148:151], v[188:191], 0
	v_mfma_f32_16x16x32_bf16 v[60:63], v[156:159], v[188:191], 0
	v_mfma_f32_16x16x32_bf16 v[48:51], v[148:151], v[196:199], 0
	v_mfma_f32_16x16x32_bf16 v[44:47], v[156:159], v[196:199], 0
	v_mfma_f32_16x16x32_bf16 v[32:35], v[148:151], v[204:207], 0
	v_mfma_f32_16x16x32_bf16 v[28:31], v[156:159], v[204:207], 0
	v_mfma_f32_16x16x32_bf16 v[16:19], v[148:151], v[212:215], 0
	v_mfma_f32_16x16x32_bf16 v[12:15], v[156:159], v[212:215], 0
	v_mfma_f32_16x16x32_bf16 v[64:67], v[152:155], v[192:195], v[64:67]
	v_mfma_f32_16x16x32_bf16 v[60:63], v[160:163], v[192:195], v[60:63]
	v_mfma_f32_16x16x32_bf16 v[48:51], v[152:155], v[200:203], v[48:51]
	v_mfma_f32_16x16x32_bf16 v[44:47], v[160:163], v[200:203], v[44:47]
	v_mfma_f32_16x16x32_bf16 v[32:35], v[152:155], v[208:211], v[32:35]
	v_mfma_f32_16x16x32_bf16 v[28:31], v[160:163], v[208:211], v[28:31]
	v_mfma_f32_16x16x32_bf16 v[16:19], v[152:155], v[216:219], v[16:19]
	v_mfma_f32_16x16x32_bf16 v[12:15], v[160:163], v[216:219], v[12:15]


	v_mfma_f32_16x16x32_bf16 v[56:59], v[164:167], v[188:191], 0
	v_mfma_f32_16x16x32_bf16 v[52:55], v[172:175], v[188:191], 0
	v_mfma_f32_16x16x32_bf16 v[40:43], v[164:167], v[196:199], 0
	v_mfma_f32_16x16x32_bf16 v[36:39], v[172:175], v[196:199], 0
	v_mfma_f32_16x16x32_bf16 v[24:27], v[164:167], v[204:207], 0
	v_mfma_f32_16x16x32_bf16 v[20:23], v[172:175], v[204:207], 0
	v_mfma_f32_16x16x32_bf16 v[8:11], v[164:167], v[212:215], 0
	v_mfma_f32_16x16x32_bf16 v[4:7], v[172:175], v[212:215], 0
	v_mfma_f32_16x16x32_bf16 v[56:59], v[168:171], v[192:195], v[56:59]
	v_mfma_f32_16x16x32_bf16 v[52:55], v[176:179], v[192:195], v[52:55]
	v_mfma_f32_16x16x32_bf16 v[40:43], v[168:171], v[200:203], v[40:43]
	v_mfma_f32_16x16x32_bf16 v[36:39], v[176:179], v[200:203], v[36:39]
	v_mfma_f32_16x16x32_bf16 v[24:27], v[168:171], v[208:211], v[24:27]
	v_mfma_f32_16x16x32_bf16 v[20:23], v[176:179], v[208:211], v[20:23]
	v_mfma_f32_16x16x32_bf16 v[8:11], v[168:171], v[216:219], v[8:11]
	v_mfma_f32_16x16x32_bf16 v[4:7], v[176:179], v[216:219], v[4:7]

	s_barrier
	s_add_i32 s55, 0, 0x18000
	s_add_i32 s57, 0, 0x1c000
	v_add_u32_e32 v160, s55, v146
	v_add_u32_e32 v176, s57, v146
	ds_read_b128 v[148:151], v160
	ds_read_b128 v[152:155], v160 offset:1024
	ds_read_b128 v[156:159], v160 offset:2048
	ds_read_b128 v[160:163], v160 offset:3072
	ds_read_b128 v[164:167], v176
	ds_read_b128 v[168:171], v176 offset:1024
	ds_read_b128 v[172:175], v176 offset:2048
	ds_read_b128 v[176:179], v176 offset:3072
	s_add_u32 s28, s28, 0x40000
	s_addc_u32 s29, s29, 0
	s_mov_b32 m0, s38
	v_lshl_add_u64 v[226:227], s[28:29], 0, v[136:137]
	ds_read_b128 v[188:191], v147 offset:32768
	ds_read_b128 v[192:195], v147 offset:33792
	ds_read_b128 v[196:199], v147 offset:34816
	ds_read_b128 v[200:203], v147 offset:35840
	ds_read_b128 v[204:207], v147 offset:36864
	ds_read_b128 v[208:211], v147 offset:37888
	ds_read_b128 v[212:215], v147 offset:38912
	ds_read_b128 v[216:219], v147 offset:39936
	global_load_lds_dwordx4 v[226:227], off
	v_lshl_add_u64 v[226:227], s[28:29], 0, v[134:135]
	s_mov_b32 m0, s39
	s_nop 0
	global_load_lds_dwordx4 v[226:227], off
	s_waitcnt vmcnt(8)
	s_waitcnt lgkmcnt(0)
	s_barrier

	s_waitcnt lgkmcnt(0)
	v_mfma_f32_16x16x32_bf16 v[128:131], v[148:151], v[188:191], v[128:131]
	v_mfma_f32_16x16x32_bf16 v[124:127], v[156:159], v[188:191], v[124:127]
	v_mfma_f32_16x16x32_bf16 v[112:115], v[148:151], v[196:199], v[112:115]
	v_mfma_f32_16x16x32_bf16 v[108:111], v[156:159], v[196:199], v[108:111]
	v_mfma_f32_16x16x32_bf16 v[96:99], v[148:151], v[204:207], v[96:99]
	v_mfma_f32_16x16x32_bf16 v[92:95], v[156:159], v[204:207], v[92:95]
	v_mfma_f32_16x16x32_bf16 v[80:83], v[148:151], v[212:215], v[80:83]
	v_mfma_f32_16x16x32_bf16 v[76:79], v[156:159], v[212:215], v[76:79]
	v_mfma_f32_16x16x32_bf16 v[128:131], v[152:155], v[192:195], v[128:131]
	v_mfma_f32_16x16x32_bf16 v[124:127], v[160:163], v[192:195], v[124:127]
	v_mfma_f32_16x16x32_bf16 v[112:115], v[152:155], v[200:203], v[112:115]
	v_mfma_f32_16x16x32_bf16 v[108:111], v[160:163], v[200:203], v[108:111]
	v_mfma_f32_16x16x32_bf16 v[96:99], v[152:155], v[208:211], v[96:99]
	v_mfma_f32_16x16x32_bf16 v[92:95], v[160:163], v[208:211], v[92:95]
	v_mfma_f32_16x16x32_bf16 v[80:83], v[152:155], v[216:219], v[80:83]
	v_mfma_f32_16x16x32_bf16 v[76:79], v[160:163], v[216:219], v[76:79]


	v_mfma_f32_16x16x32_bf16 v[120:123], v[164:167], v[188:191], v[120:123]
	v_mfma_f32_16x16x32_bf16 v[116:119], v[172:175], v[188:191], v[116:119]
	v_mfma_f32_16x16x32_bf16 v[104:107], v[164:167], v[196:199], v[104:107]
	v_mfma_f32_16x16x32_bf16 v[100:103], v[172:175], v[196:199], v[100:103]
	v_mfma_f32_16x16x32_bf16 v[88:91], v[164:167], v[204:207], v[88:91]
	v_mfma_f32_16x16x32_bf16 v[84:87], v[172:175], v[204:207], v[84:87]
	v_mfma_f32_16x16x32_bf16 v[72:75], v[164:167], v[212:215], v[72:75]
	v_mfma_f32_16x16x32_bf16 v[68:71], v[172:175], v[212:215], v[68:71]
	v_mfma_f32_16x16x32_bf16 v[120:123], v[168:171], v[192:195], v[120:123]
	v_mfma_f32_16x16x32_bf16 v[116:119], v[176:179], v[192:195], v[116:119]
	v_mfma_f32_16x16x32_bf16 v[104:107], v[168:171], v[200:203], v[104:107]
	v_mfma_f32_16x16x32_bf16 v[100:103], v[176:179], v[200:203], v[100:103]
	v_mfma_f32_16x16x32_bf16 v[88:91], v[168:171], v[208:211], v[88:91]
	v_mfma_f32_16x16x32_bf16 v[84:87], v[176:179], v[208:211], v[84:87]
	v_mfma_f32_16x16x32_bf16 v[72:75], v[168:171], v[216:219], v[72:75]
	v_mfma_f32_16x16x32_bf16 v[68:71], v[176:179], v[216:219], v[68:71]

	s_barrier
	s_add_i32 s28, s55, s35
	v_lshl_add_u64 v[142:143], v[142:143], 0, s[52:53]
	s_mov_b32 m0, s28
	ds_read_b128 v[188:191], v147 offset:49152
	ds_read_b128 v[192:195], v147 offset:50176
	ds_read_b128 v[196:199], v147 offset:51200
	ds_read_b128 v[200:203], v147 offset:52224
	ds_read_b128 v[204:207], v147 offset:53248
	ds_read_b128 v[208:211], v147 offset:54272
	ds_read_b128 v[212:215], v147 offset:55296
	ds_read_b128 v[216:219], v147 offset:56320
	global_load_lds_dwordx4 v[142:143], off
	s_add_i32 m0, s28, 0x2000
	s_add_u32 s26, s26, 0x40080
	v_lshl_add_u64 v[142:143], v[220:221], 0, s[52:53]
	s_addc_u32 s27, s27, 0
	s_add_i32 s28, s57, s35
	global_load_lds_dwordx4 v[142:143], off
	v_lshl_add_u64 v[142:143], s[26:27], 0, v[180:181]
	s_mov_b32 m0, s28
	s_nop 0
	global_load_lds_dwordx4 v[142:143], off
	v_lshl_add_u64 v[142:143], s[26:27], 0, v[132:133]
	s_add_i32 m0, s28, 0x2000
	s_nop 0
	global_load_lds_dwordx4 v[142:143], off
	v_lshl_add_u64 v[142:143], v[222:223], 0, s[52:53]
	s_mov_b32 m0, s42
	s_nop 0
	global_load_lds_dwordx4 v[142:143], off
	v_lshl_add_u64 v[142:143], v[224:225], 0, s[52:53]
	s_mov_b32 m0, s43
	s_nop 0
	global_load_lds_dwordx4 v[142:143], off
	s_waitcnt vmcnt(8)
	s_waitcnt lgkmcnt(0)
	s_barrier

	s_waitcnt lgkmcnt(0)
	v_mfma_f32_16x16x32_bf16 v[64:67], v[148:151], v[188:191], v[64:67]
	v_mfma_f32_16x16x32_bf16 v[60:63], v[156:159], v[188:191], v[60:63]
	v_mfma_f32_16x16x32_bf16 v[48:51], v[148:151], v[196:199], v[48:51]
	v_mfma_f32_16x16x32_bf16 v[44:47], v[156:159], v[196:199], v[44:47]
	v_mfma_f32_16x16x32_bf16 v[32:35], v[148:151], v[204:207], v[32:35]
	v_mfma_f32_16x16x32_bf16 v[28:31], v[156:159], v[204:207], v[28:31]
	v_mfma_f32_16x16x32_bf16 v[16:19], v[148:151], v[212:215], v[16:19]
	v_mfma_f32_16x16x32_bf16 v[12:15], v[156:159], v[212:215], v[12:15]
	v_mfma_f32_16x16x32_bf16 v[64:67], v[152:155], v[192:195], v[64:67]
	v_mfma_f32_16x16x32_bf16 v[60:63], v[160:163], v[192:195], v[60:63]
	v_mfma_f32_16x16x32_bf16 v[48:51], v[152:155], v[200:203], v[48:51]
	v_mfma_f32_16x16x32_bf16 v[44:47], v[160:163], v[200:203], v[44:47]
	v_mfma_f32_16x16x32_bf16 v[32:35], v[152:155], v[208:211], v[32:35]
	v_mfma_f32_16x16x32_bf16 v[28:31], v[160:163], v[208:211], v[28:31]
	v_mfma_f32_16x16x32_bf16 v[16:19], v[152:155], v[216:219], v[16:19]
	v_mfma_f32_16x16x32_bf16 v[12:15], v[160:163], v[216:219], v[12:15]


	v_mfma_f32_16x16x32_bf16 v[56:59], v[164:167], v[188:191], v[56:59]
	v_mfma_f32_16x16x32_bf16 v[52:55], v[172:175], v[188:191], v[52:55]
	v_mfma_f32_16x16x32_bf16 v[40:43], v[164:167], v[196:199], v[40:43]
	v_mfma_f32_16x16x32_bf16 v[36:39], v[172:175], v[196:199], v[36:39]
	v_mfma_f32_16x16x32_bf16 v[24:27], v[164:167], v[204:207], v[24:27]
	v_mfma_f32_16x16x32_bf16 v[20:23], v[172:175], v[204:207], v[20:23]
	v_mfma_f32_16x16x32_bf16 v[8:11], v[164:167], v[212:215], v[8:11]
	v_mfma_f32_16x16x32_bf16 v[4:7], v[172:175], v[212:215], v[4:7]
	v_mfma_f32_16x16x32_bf16 v[56:59], v[168:171], v[192:195], v[56:59]
	v_mfma_f32_16x16x32_bf16 v[52:55], v[176:179], v[192:195], v[52:55]
	v_mfma_f32_16x16x32_bf16 v[40:43], v[168:171], v[200:203], v[40:43]
	v_mfma_f32_16x16x32_bf16 v[36:39], v[176:179], v[200:203], v[36:39]
	v_mfma_f32_16x16x32_bf16 v[24:27], v[168:171], v[208:211], v[24:27]
	v_mfma_f32_16x16x32_bf16 v[20:23], v[176:179], v[208:211], v[20:23]
	v_mfma_f32_16x16x32_bf16 v[8:11], v[168:171], v[216:219], v[8:11]
	v_mfma_f32_16x16x32_bf16 v[4:7], v[176:179], v[216:219], v[4:7]

	s_barrier
	s_add_i32 s54, s54, 2
	s_add_u32 s24, s24, 0x100
	s_addc_u32 s25, s25, 0
	s_add_u32 s50, s50, 0x100
	s_addc_u32 s51, s51, 0
	s_cmp_gt_u32 s54, 13
	s_cbranch_scc1 .Lkexit_0
.LBB0_105:
	s_add_u32 s26, s24, 0xfffc0080
	s_addc_u32 s27, s25, -1
	s_add_i32 s55, 0, 0x10000
	s_cmp_eq_u32 s54, 12
	s_cselect_b32 s29, s4, s27
	s_cselect_b32 s28, s5, s26
	v_add_u32_e32 v142, s55, v146
	s_cselect_b32 s27, s15, s51
	s_cselect_b32 s26, s17, s50
	s_add_i32 s57, 0, 0x14000
	ds_read_b128 v[148:151], v142
	ds_read_b128 v[152:155], v142 offset:1024
	ds_read_b128 v[156:159], v142 offset:2048
	ds_read_b128 v[160:163], v142 offset:3072
	v_add_u32_e32 v142, s57, v146
	ds_read_b128 v[164:167], v142
	ds_read_b128 v[168:171], v142 offset:1024
	ds_read_b128 v[172:175], v142 offset:2048
	ds_read_b128 v[176:179], v142 offset:3072
	v_lshl_add_u64 v[142:143], s[24:25], 0, v[138:139]
	s_add_i32 m0, s1, 0xc000
	ds_read_b128 v[188:191], v147
	ds_read_b128 v[192:195], v147 offset:1024
	ds_read_b128 v[196:199], v147 offset:2048
	ds_read_b128 v[200:203], v147 offset:3072
	ds_read_b128 v[204:207], v147 offset:4096
	ds_read_b128 v[208:211], v147 offset:5120
	ds_read_b128 v[212:215], v147 offset:6144
	ds_read_b128 v[216:219], v147 offset:7168
	global_load_lds_dwordx4 v[142:143], off
	v_lshl_add_u64 v[142:143], s[24:25], 0, v[140:141]
	s_add_i32 m0, s1, 0xe000
	s_nop 0
	global_load_lds_dwordx4 v[142:143], off
	s_waitcnt vmcnt(8)
	s_waitcnt lgkmcnt(0)
	s_barrier

	s_waitcnt lgkmcnt(0)
	v_mfma_f32_16x16x32_bf16 v[128:131], v[148:151], v[188:191], v[128:131]
	v_mfma_f32_16x16x32_bf16 v[124:127], v[156:159], v[188:191], v[124:127]
	v_mfma_f32_16x16x32_bf16 v[112:115], v[148:151], v[196:199], v[112:115]
	v_mfma_f32_16x16x32_bf16 v[108:111], v[156:159], v[196:199], v[108:111]
	v_mfma_f32_16x16x32_bf16 v[96:99], v[148:151], v[204:207], v[96:99]
	v_mfma_f32_16x16x32_bf16 v[92:95], v[156:159], v[204:207], v[92:95]
	v_mfma_f32_16x16x32_bf16 v[80:83], v[148:151], v[212:215], v[80:83]
	v_mfma_f32_16x16x32_bf16 v[76:79], v[156:159], v[212:215], v[76:79]
	v_mfma_f32_16x16x32_bf16 v[128:131], v[152:155], v[192:195], v[128:131]
	v_mfma_f32_16x16x32_bf16 v[124:127], v[160:163], v[192:195], v[124:127]
	v_mfma_f32_16x16x32_bf16 v[112:115], v[152:155], v[200:203], v[112:115]
	v_mfma_f32_16x16x32_bf16 v[108:111], v[160:163], v[200:203], v[108:111]
	v_mfma_f32_16x16x32_bf16 v[96:99], v[152:155], v[208:211], v[96:99]
	v_mfma_f32_16x16x32_bf16 v[92:95], v[160:163], v[208:211], v[92:95]
	v_mfma_f32_16x16x32_bf16 v[80:83], v[152:155], v[216:219], v[80:83]
	v_mfma_f32_16x16x32_bf16 v[76:79], v[160:163], v[216:219], v[76:79]


	v_mfma_f32_16x16x32_bf16 v[120:123], v[164:167], v[188:191], v[120:123]
	v_mfma_f32_16x16x32_bf16 v[116:119], v[172:175], v[188:191], v[116:119]
	v_mfma_f32_16x16x32_bf16 v[104:107], v[164:167], v[196:199], v[104:107]
	v_mfma_f32_16x16x32_bf16 v[100:103], v[172:175], v[196:199], v[100:103]
	v_mfma_f32_16x16x32_bf16 v[88:91], v[164:167], v[204:207], v[88:91]
	v_mfma_f32_16x16x32_bf16 v[84:87], v[172:175], v[204:207], v[84:87]
	v_mfma_f32_16x16x32_bf16 v[72:75], v[164:167], v[212:215], v[72:75]
	v_mfma_f32_16x16x32_bf16 v[68:71], v[172:175], v[212:215], v[68:71]
	v_mfma_f32_16x16x32_bf16 v[120:123], v[168:171], v[192:195], v[120:123]
	v_mfma_f32_16x16x32_bf16 v[116:119], v[176:179], v[192:195], v[116:119]
	v_mfma_f32_16x16x32_bf16 v[104:107], v[168:171], v[200:203], v[104:107]
	v_mfma_f32_16x16x32_bf16 v[100:103], v[176:179], v[200:203], v[100:103]
	v_mfma_f32_16x16x32_bf16 v[88:91], v[168:171], v[208:211], v[88:91]
	v_mfma_f32_16x16x32_bf16 v[84:87], v[176:179], v[208:211], v[84:87]
	v_mfma_f32_16x16x32_bf16 v[72:75], v[168:171], v[216:219], v[72:75]
	v_mfma_f32_16x16x32_bf16 v[68:71], v[176:179], v[216:219], v[68:71]

	s_barrier
	s_add_i32 s55, s55, s35
	v_lshl_add_u64 v[142:143], s[26:27], 0, v[180:181]
	s_mov_b32 m0, s55
	ds_read_b128 v[188:191], v147 offset:16384
	ds_read_b128 v[192:195], v147 offset:17408
	ds_read_b128 v[196:199], v147 offset:18432
	ds_read_b128 v[200:203], v147 offset:19456
	ds_read_b128 v[204:207], v147 offset:20480
	ds_read_b128 v[208:211], v147 offset:21504
	ds_read_b128 v[212:215], v147 offset:22528
	ds_read_b128 v[216:219], v147 offset:23552
	global_load_lds_dwordx4 v[142:143], off
	s_add_i32 m0, s55, 0x2000
	s_add_u32 s58, s26, 0x40000
	v_lshl_add_u64 v[220:221], s[26:27], 0, v[132:133]
	s_addc_u32 s59, s27, 0
	s_add_i32 s55, s57, s35
	global_load_lds_dwordx4 v[220:221], off
	v_lshl_add_u64 v[222:223], s[58:59], 0, v[180:181]
	s_mov_b32 m0, s55
	v_lshl_add_u64 v[224:225], s[28:29], 0, v[134:135]
	global_load_lds_dwordx4 v[222:223], off
	v_lshl_add_u64 v[222:223], s[58:59], 0, v[132:133]
	s_add_i32 m0, s55, 0x2000
	s_nop 0
	global_load_lds_dwordx4 v[222:223], off
	v_lshl_add_u64 v[222:223], s[28:29], 0, v[136:137]
	s_mov_b32 m0, s1
	s_nop 0
	global_load_lds_dwordx4 v[222:223], off
	s_mov_b32 m0, s23
	s_nop 0
	global_load_lds_dwordx4 v[224:225], off
	s_waitcnt vmcnt(8)
	s_waitcnt lgkmcnt(0)
	s_barrier

	s_waitcnt lgkmcnt(0)
	v_mfma_f32_16x16x32_bf16 v[64:67], v[148:151], v[188:191], v[64:67]
	v_mfma_f32_16x16x32_bf16 v[60:63], v[156:159], v[188:191], v[60:63]
	v_mfma_f32_16x16x32_bf16 v[48:51], v[148:151], v[196:199], v[48:51]
	v_mfma_f32_16x16x32_bf16 v[44:47], v[156:159], v[196:199], v[44:47]
	v_mfma_f32_16x16x32_bf16 v[32:35], v[148:151], v[204:207], v[32:35]
	v_mfma_f32_16x16x32_bf16 v[28:31], v[156:159], v[204:207], v[28:31]
	v_mfma_f32_16x16x32_bf16 v[16:19], v[148:151], v[212:215], v[16:19]
	v_mfma_f32_16x16x32_bf16 v[12:15], v[156:159], v[212:215], v[12:15]
	v_mfma_f32_16x16x32_bf16 v[64:67], v[152:155], v[192:195], v[64:67]
	v_mfma_f32_16x16x32_bf16 v[60:63], v[160:163], v[192:195], v[60:63]
	v_mfma_f32_16x16x32_bf16 v[48:51], v[152:155], v[200:203], v[48:51]
	v_mfma_f32_16x16x32_bf16 v[44:47], v[160:163], v[200:203], v[44:47]
	v_mfma_f32_16x16x32_bf16 v[32:35], v[152:155], v[208:211], v[32:35]
	v_mfma_f32_16x16x32_bf16 v[28:31], v[160:163], v[208:211], v[28:31]
	v_mfma_f32_16x16x32_bf16 v[16:19], v[152:155], v[216:219], v[16:19]
	v_mfma_f32_16x16x32_bf16 v[12:15], v[160:163], v[216:219], v[12:15]


	v_mfma_f32_16x16x32_bf16 v[56:59], v[164:167], v[188:191], v[56:59]
	v_mfma_f32_16x16x32_bf16 v[52:55], v[172:175], v[188:191], v[52:55]
	v_mfma_f32_16x16x32_bf16 v[40:43], v[164:167], v[196:199], v[40:43]
	v_mfma_f32_16x16x32_bf16 v[36:39], v[172:175], v[196:199], v[36:39]
	v_mfma_f32_16x16x32_bf16 v[24:27], v[164:167], v[204:207], v[24:27]
	v_mfma_f32_16x16x32_bf16 v[20:23], v[172:175], v[204:207], v[20:23]
	v_mfma_f32_16x16x32_bf16 v[8:11], v[164:167], v[212:215], v[8:11]
	v_mfma_f32_16x16x32_bf16 v[4:7], v[172:175], v[212:215], v[4:7]
	v_mfma_f32_16x16x32_bf16 v[56:59], v[168:171], v[192:195], v[56:59]
	v_mfma_f32_16x16x32_bf16 v[52:55], v[176:179], v[192:195], v[52:55]
	v_mfma_f32_16x16x32_bf16 v[40:43], v[168:171], v[200:203], v[40:43]
	v_mfma_f32_16x16x32_bf16 v[36:39], v[176:179], v[200:203], v[36:39]
	v_mfma_f32_16x16x32_bf16 v[24:27], v[168:171], v[208:211], v[24:27]
	v_mfma_f32_16x16x32_bf16 v[20:23], v[176:179], v[208:211], v[20:23]
	v_mfma_f32_16x16x32_bf16 v[8:11], v[168:171], v[216:219], v[8:11]
	v_mfma_f32_16x16x32_bf16 v[4:7], v[176:179], v[216:219], v[4:7]

	s_barrier
	s_add_i32 s55, 0, 0x18000
	s_add_i32 s57, 0, 0x1c000
	v_add_u32_e32 v160, s55, v146
	v_add_u32_e32 v176, s57, v146
	ds_read_b128 v[148:151], v160
	ds_read_b128 v[152:155], v160 offset:1024
	ds_read_b128 v[156:159], v160 offset:2048
	ds_read_b128 v[160:163], v160 offset:3072
	ds_read_b128 v[164:167], v176
	ds_read_b128 v[168:171], v176 offset:1024
	ds_read_b128 v[172:175], v176 offset:2048
	ds_read_b128 v[176:179], v176 offset:3072
	s_add_u32 s28, s28, 0x40000
	s_addc_u32 s29, s29, 0
	s_mov_b32 m0, s38
	v_lshl_add_u64 v[226:227], s[28:29], 0, v[136:137]
	ds_read_b128 v[188:191], v147 offset:32768
	ds_read_b128 v[192:195], v147 offset:33792
	ds_read_b128 v[196:199], v147 offset:34816
	ds_read_b128 v[200:203], v147 offset:35840
	ds_read_b128 v[204:207], v147 offset:36864
	ds_read_b128 v[208:211], v147 offset:37888
	ds_read_b128 v[212:215], v147 offset:38912
	ds_read_b128 v[216:219], v147 offset:39936
	global_load_lds_dwordx4 v[226:227], off
	v_lshl_add_u64 v[226:227], s[28:29], 0, v[134:135]
	s_mov_b32 m0, s39
	s_nop 0
	global_load_lds_dwordx4 v[226:227], off
	s_waitcnt vmcnt(8)
	s_waitcnt lgkmcnt(0)
	s_barrier

	s_waitcnt lgkmcnt(0)
	v_mfma_f32_16x16x32_bf16 v[128:131], v[148:151], v[188:191], v[128:131]
	v_mfma_f32_16x16x32_bf16 v[124:127], v[156:159], v[188:191], v[124:127]
	v_mfma_f32_16x16x32_bf16 v[112:115], v[148:151], v[196:199], v[112:115]
	v_mfma_f32_16x16x32_bf16 v[108:111], v[156:159], v[196:199], v[108:111]
	v_mfma_f32_16x16x32_bf16 v[96:99], v[148:151], v[204:207], v[96:99]
	v_mfma_f32_16x16x32_bf16 v[92:95], v[156:159], v[204:207], v[92:95]
	v_mfma_f32_16x16x32_bf16 v[80:83], v[148:151], v[212:215], v[80:83]
	v_mfma_f32_16x16x32_bf16 v[76:79], v[156:159], v[212:215], v[76:79]
	v_mfma_f32_16x16x32_bf16 v[128:131], v[152:155], v[192:195], v[128:131]
	v_mfma_f32_16x16x32_bf16 v[124:127], v[160:163], v[192:195], v[124:127]
	v_mfma_f32_16x16x32_bf16 v[112:115], v[152:155], v[200:203], v[112:115]
	v_mfma_f32_16x16x32_bf16 v[108:111], v[160:163], v[200:203], v[108:111]
	v_mfma_f32_16x16x32_bf16 v[96:99], v[152:155], v[208:211], v[96:99]
	v_mfma_f32_16x16x32_bf16 v[92:95], v[160:163], v[208:211], v[92:95]
	v_mfma_f32_16x16x32_bf16 v[80:83], v[152:155], v[216:219], v[80:83]
	v_mfma_f32_16x16x32_bf16 v[76:79], v[160:163], v[216:219], v[76:79]


	v_mfma_f32_16x16x32_bf16 v[120:123], v[164:167], v[188:191], v[120:123]
	v_mfma_f32_16x16x32_bf16 v[116:119], v[172:175], v[188:191], v[116:119]
	v_mfma_f32_16x16x32_bf16 v[104:107], v[164:167], v[196:199], v[104:107]
	v_mfma_f32_16x16x32_bf16 v[100:103], v[172:175], v[196:199], v[100:103]
	v_mfma_f32_16x16x32_bf16 v[88:91], v[164:167], v[204:207], v[88:91]
	v_mfma_f32_16x16x32_bf16 v[84:87], v[172:175], v[204:207], v[84:87]
	v_mfma_f32_16x16x32_bf16 v[72:75], v[164:167], v[212:215], v[72:75]
	v_mfma_f32_16x16x32_bf16 v[68:71], v[172:175], v[212:215], v[68:71]
	v_mfma_f32_16x16x32_bf16 v[120:123], v[168:171], v[192:195], v[120:123]
	v_mfma_f32_16x16x32_bf16 v[116:119], v[176:179], v[192:195], v[116:119]
	v_mfma_f32_16x16x32_bf16 v[104:107], v[168:171], v[200:203], v[104:107]
	v_mfma_f32_16x16x32_bf16 v[100:103], v[176:179], v[200:203], v[100:103]
	v_mfma_f32_16x16x32_bf16 v[88:91], v[168:171], v[208:211], v[88:91]
	v_mfma_f32_16x16x32_bf16 v[84:87], v[176:179], v[208:211], v[84:87]
	v_mfma_f32_16x16x32_bf16 v[72:75], v[168:171], v[216:219], v[72:75]
	v_mfma_f32_16x16x32_bf16 v[68:71], v[176:179], v[216:219], v[68:71]

	s_barrier
	s_add_i32 s28, s55, s35
	v_lshl_add_u64 v[142:143], v[142:143], 0, s[52:53]
	s_mov_b32 m0, s28
	ds_read_b128 v[188:191], v147 offset:49152
	ds_read_b128 v[192:195], v147 offset:50176
	ds_read_b128 v[196:199], v147 offset:51200
	ds_read_b128 v[200:203], v147 offset:52224
	ds_read_b128 v[204:207], v147 offset:53248
	ds_read_b128 v[208:211], v147 offset:54272
	ds_read_b128 v[212:215], v147 offset:55296
	ds_read_b128 v[216:219], v147 offset:56320
	global_load_lds_dwordx4 v[142:143], off
	s_add_i32 m0, s28, 0x2000
	s_add_u32 s26, s26, 0x40080
	v_lshl_add_u64 v[142:143], v[220:221], 0, s[52:53]
	s_addc_u32 s27, s27, 0
	s_add_i32 s28, s57, s35
	global_load_lds_dwordx4 v[142:143], off
	v_lshl_add_u64 v[142:143], s[26:27], 0, v[180:181]
	s_mov_b32 m0, s28
	s_nop 0
	global_load_lds_dwordx4 v[142:143], off
	v_lshl_add_u64 v[142:143], s[26:27], 0, v[132:133]
	s_add_i32 m0, s28, 0x2000
	s_nop 0
	global_load_lds_dwordx4 v[142:143], off
	v_lshl_add_u64 v[142:143], v[222:223], 0, s[52:53]
	s_mov_b32 m0, s42
	s_nop 0
	global_load_lds_dwordx4 v[142:143], off
	v_lshl_add_u64 v[142:143], v[224:225], 0, s[52:53]
	s_mov_b32 m0, s43
	s_nop 0
	global_load_lds_dwordx4 v[142:143], off
	s_waitcnt vmcnt(8)
	s_waitcnt lgkmcnt(0)
	s_barrier

	s_waitcnt lgkmcnt(0)
	v_mfma_f32_16x16x32_bf16 v[64:67], v[148:151], v[188:191], v[64:67]
	v_mfma_f32_16x16x32_bf16 v[60:63], v[156:159], v[188:191], v[60:63]
	v_mfma_f32_16x16x32_bf16 v[48:51], v[148:151], v[196:199], v[48:51]
	v_mfma_f32_16x16x32_bf16 v[44:47], v[156:159], v[196:199], v[44:47]
	v_mfma_f32_16x16x32_bf16 v[32:35], v[148:151], v[204:207], v[32:35]
	v_mfma_f32_16x16x32_bf16 v[28:31], v[156:159], v[204:207], v[28:31]
	v_mfma_f32_16x16x32_bf16 v[16:19], v[148:151], v[212:215], v[16:19]
	v_mfma_f32_16x16x32_bf16 v[12:15], v[156:159], v[212:215], v[12:15]
	v_mfma_f32_16x16x32_bf16 v[64:67], v[152:155], v[192:195], v[64:67]
	v_mfma_f32_16x16x32_bf16 v[60:63], v[160:163], v[192:195], v[60:63]
	v_mfma_f32_16x16x32_bf16 v[48:51], v[152:155], v[200:203], v[48:51]
	v_mfma_f32_16x16x32_bf16 v[44:47], v[160:163], v[200:203], v[44:47]
	v_mfma_f32_16x16x32_bf16 v[32:35], v[152:155], v[208:211], v[32:35]
	v_mfma_f32_16x16x32_bf16 v[28:31], v[160:163], v[208:211], v[28:31]
	v_mfma_f32_16x16x32_bf16 v[16:19], v[152:155], v[216:219], v[16:19]
	v_mfma_f32_16x16x32_bf16 v[12:15], v[160:163], v[216:219], v[12:15]


	v_mfma_f32_16x16x32_bf16 v[56:59], v[164:167], v[188:191], v[56:59]
	v_mfma_f32_16x16x32_bf16 v[52:55], v[172:175], v[188:191], v[52:55]
	v_mfma_f32_16x16x32_bf16 v[40:43], v[164:167], v[196:199], v[40:43]
	v_mfma_f32_16x16x32_bf16 v[36:39], v[172:175], v[196:199], v[36:39]
	v_mfma_f32_16x16x32_bf16 v[24:27], v[164:167], v[204:207], v[24:27]
	v_mfma_f32_16x16x32_bf16 v[20:23], v[172:175], v[204:207], v[20:23]
	v_mfma_f32_16x16x32_bf16 v[8:11], v[164:167], v[212:215], v[8:11]
	v_mfma_f32_16x16x32_bf16 v[4:7], v[172:175], v[212:215], v[4:7]
	v_mfma_f32_16x16x32_bf16 v[56:59], v[168:171], v[192:195], v[56:59]
	v_mfma_f32_16x16x32_bf16 v[52:55], v[176:179], v[192:195], v[52:55]
	v_mfma_f32_16x16x32_bf16 v[40:43], v[168:171], v[200:203], v[40:43]
	v_mfma_f32_16x16x32_bf16 v[36:39], v[176:179], v[200:203], v[36:39]
	v_mfma_f32_16x16x32_bf16 v[24:27], v[168:171], v[208:211], v[24:27]
	v_mfma_f32_16x16x32_bf16 v[20:23], v[176:179], v[208:211], v[20:23]
	v_mfma_f32_16x16x32_bf16 v[8:11], v[168:171], v[216:219], v[8:11]
	v_mfma_f32_16x16x32_bf16 v[4:7], v[176:179], v[216:219], v[4:7]

	s_barrier
	s_add_i32 s54, s54, 2
	s_add_u32 s24, s24, 0x100
	s_addc_u32 s25, s25, 0
	s_add_u32 s50, s50, 0x100
	s_addc_u32 s51, s51, 0
	s_cmp_gt_u32 s54, 13
	s_cbranch_scc0 .LBB0_105
	s_setprio 0

.LBB0_254:
	s_ashr_i32 s21, s20, 31
	s_lshl_b64 s[4:5], s[20:21], 19
	s_add_u32 s22, s36, s4
	s_addc_u32 s23, s37, s5
	s_and_b64 s[4:5], s[6:7], exec
	s_cselect_b32 s1, s23, s29
	s_cselect_b32 s2, s22, s28
	s_ashr_i32 s19, s18, 31
	s_lshl_b64 s[4:5], s[18:19], 19
	s_add_u32 s24, s38, s4
	s_addc_u32 s25, s39, s5
	s_and_b64 s[4:5], s[6:7], exec
	s_cselect_b32 s4, s25, s31
	s_cselect_b32 s5, s24, s30
	s_add_u32 s28, s28, 0x40080
	s_addc_u32 s29, s29, 0
	s_add_u32 s19, s30, 0x100
	v_mov_b32_e32 v4, 0
	s_addc_u32 s21, s31, 0
	s_mov_b32 s27, -2
	v_mov_b32_e32 v5, v4
	v_mov_b32_e32 v6, v4
	v_mov_b32_e32 v7, v4
	v_mov_b32_e32 v8, v4
	v_mov_b32_e32 v9, v4
	v_mov_b32_e32 v10, v4
	v_mov_b32_e32 v11, v4
	v_mov_b32_e32 v20, v4
	v_mov_b32_e32 v21, v4
	v_mov_b32_e32 v22, v4
	v_mov_b32_e32 v23, v4
	v_mov_b32_e32 v24, v4
	v_mov_b32_e32 v25, v4
	v_mov_b32_e32 v26, v4
	v_mov_b32_e32 v27, v4
	v_mov_b32_e32 v36, v4
	v_mov_b32_e32 v37, v4
	v_mov_b32_e32 v38, v4
	v_mov_b32_e32 v39, v4
	v_mov_b32_e32 v40, v4
	v_mov_b32_e32 v41, v4
	v_mov_b32_e32 v42, v4
	v_mov_b32_e32 v43, v4
	v_mov_b32_e32 v44, v4
	v_mov_b32_e32 v45, v4
	v_mov_b32_e32 v46, v4
	v_mov_b32_e32 v47, v4
	v_mov_b32_e32 v48, v4
	v_mov_b32_e32 v49, v4
	v_mov_b32_e32 v50, v4
	v_mov_b32_e32 v51, v4
	v_mov_b32_e32 v12, v4
	v_mov_b32_e32 v13, v4
	v_mov_b32_e32 v14, v4
	v_mov_b32_e32 v15, v4
	v_mov_b32_e32 v16, v4
	v_mov_b32_e32 v17, v4
	v_mov_b32_e32 v18, v4
	v_mov_b32_e32 v19, v4
	v_mov_b32_e32 v28, v4
	v_mov_b32_e32 v29, v4
	v_mov_b32_e32 v30, v4
	v_mov_b32_e32 v31, v4
	v_mov_b32_e32 v32, v4
	v_mov_b32_e32 v33, v4
	v_mov_b32_e32 v34, v4
	v_mov_b32_e32 v35, v4
	v_mov_b32_e32 v52, v4
	v_mov_b32_e32 v53, v4
	v_mov_b32_e32 v54, v4
	v_mov_b32_e32 v55, v4
	v_mov_b32_e32 v56, v4
	v_mov_b32_e32 v57, v4
	v_mov_b32_e32 v58, v4
	v_mov_b32_e32 v59, v4
	v_mov_b32_e32 v60, v4
	v_mov_b32_e32 v61, v4
	v_mov_b32_e32 v62, v4
	v_mov_b32_e32 v63, v4
	v_mov_b32_e32 v64, v4
	v_mov_b32_e32 v65, v4
	v_mov_b32_e32 v66, v4
	v_mov_b32_e32 v67, v4
	v_mov_b32_e32 v84, v4
	v_mov_b32_e32 v85, v4
	v_mov_b32_e32 v86, v4
	v_mov_b32_e32 v87, v4
	v_mov_b32_e32 v88, v4
	v_mov_b32_e32 v89, v4
	v_mov_b32_e32 v90, v4
	v_mov_b32_e32 v91, v4
	v_mov_b32_e32 v92, v4
	v_mov_b32_e32 v93, v4
	v_mov_b32_e32 v94, v4
	v_mov_b32_e32 v95, v4
	v_mov_b32_e32 v96, v4
	v_mov_b32_e32 v97, v4
	v_mov_b32_e32 v98, v4
	v_mov_b32_e32 v99, v4
	v_mov_b32_e32 v116, v4
	v_mov_b32_e32 v117, v4
	v_mov_b32_e32 v118, v4
	v_mov_b32_e32 v119, v4
	v_mov_b32_e32 v120, v4
	v_mov_b32_e32 v121, v4
	v_mov_b32_e32 v122, v4
	v_mov_b32_e32 v123, v4
	v_mov_b32_e32 v124, v4
	v_mov_b32_e32 v125, v4
	v_mov_b32_e32 v126, v4
	v_mov_b32_e32 v127, v4
	v_mov_b32_e32 v128, v4
	v_mov_b32_e32 v129, v4
	v_mov_b32_e32 v130, v4
	v_mov_b32_e32 v131, v4
	v_mov_b32_e32 v100, v4
	v_mov_b32_e32 v101, v4
	v_mov_b32_e32 v102, v4
	v_mov_b32_e32 v103, v4
	v_mov_b32_e32 v104, v4
	v_mov_b32_e32 v105, v4
	v_mov_b32_e32 v106, v4
	v_mov_b32_e32 v107, v4
	v_mov_b32_e32 v108, v4
	v_mov_b32_e32 v109, v4
	v_mov_b32_e32 v110, v4
	v_mov_b32_e32 v111, v4
	v_mov_b32_e32 v112, v4
	v_mov_b32_e32 v113, v4
	v_mov_b32_e32 v114, v4
	v_mov_b32_e32 v115, v4
	v_mov_b32_e32 v132, v4
	v_mov_b32_e32 v133, v4
	v_mov_b32_e32 v134, v4
	v_mov_b32_e32 v135, v4
	v_mov_b32_e32 v136, v4
	v_mov_b32_e32 v137, v4
	v_mov_b32_e32 v138, v4
	v_mov_b32_e32 v139, v4
	v_mov_b32_e32 v140, v4
	v_mov_b32_e32 v141, v4
	v_mov_b32_e32 v142, v4
	v_mov_b32_e32 v143, v4
	v_mov_b32_e32 v144, v4
	v_mov_b32_e32 v145, v4
	v_mov_b32_e32 v146, v4
	v_mov_b32_e32 v147, v4
	s_waitcnt vmcnt(0)
	v_readfirstlane_b32 s101, v186
	s_nop 3
	s_lshr_b32 s101, s101, 8
	s_cmp_eq_u32 s101, 1
	s_cbranch_scc0 .Lprio_3
	s_setprio 1
.Lprio_3:
.LBB0_255:
	s_add_u32 s30, s28, 0xfffc0080
	s_addc_u32 s31, s29, -1
	s_add_i32 s33, 0, 0x10000
	s_cmp_eq_u32 s27, 12
	s_cselect_b32 s35, s1, s31
	s_cselect_b32 s34, s2, s30
	s_cselect_b32 s31, s4, s21
	s_cselect_b32 s30, s5, s19
	s_add_i32 s47, 0, 0x14000
	v_add_u32_e32 v80, s33, v212
	v_add_u32_e32 v166, s47, v212
	ds_read_b128 v[68:71], v80
	ds_read_b128 v[72:75], v80 offset:1024
	ds_read_b128 v[76:79], v80 offset:2048
	ds_read_b128 v[80:83], v80 offset:3072
	ds_read_b128 v[148:151], v166
	ds_read_b128 v[158:161], v166 offset:1024
	ds_read_b128 v[162:165], v166 offset:2048
	ds_read_b128 v[166:169], v166 offset:3072
	v_lshl_add_u64 v[178:179], s[28:29], 0, v[154:155]
	s_add_i32 m0, s56, 0xc000
	ds_read_b128 v[170:173], v213
	ds_read_b128 v[174:177], v213 offset:1024
	ds_read_b128 v[188:191], v213 offset:2048
	ds_read_b128 v[192:195], v213 offset:3072
	ds_read_b128 v[196:199], v213 offset:4096
	ds_read_b128 v[200:203], v213 offset:5120
	ds_read_b128 v[204:207], v213 offset:6144
	ds_read_b128 v[208:211], v213 offset:7168
	global_load_lds_dwordx4 v[178:179], off
	v_lshl_add_u64 v[178:179], s[28:29], 0, v[156:157]
	s_add_i32 m0, s56, 0xe000
	s_nop 0
	global_load_lds_dwordx4 v[178:179], off
	s_waitcnt vmcnt(8)
	s_waitcnt lgkmcnt(0)
	s_barrier

	s_waitcnt lgkmcnt(0)
	v_mfma_f32_16x16x32_bf16 v[144:147], v[68:71], v[170:173], v[144:147]
	v_mfma_f32_16x16x32_bf16 v[140:143], v[76:79], v[170:173], v[140:143]
	v_mfma_f32_16x16x32_bf16 v[136:139], v[68:71], v[188:191], v[136:139]
	v_mfma_f32_16x16x32_bf16 v[132:135], v[76:79], v[188:191], v[132:135]
	v_mfma_f32_16x16x32_bf16 v[112:115], v[68:71], v[196:199], v[112:115]
	v_mfma_f32_16x16x32_bf16 v[108:111], v[76:79], v[196:199], v[108:111]
	v_mfma_f32_16x16x32_bf16 v[104:107], v[68:71], v[204:207], v[104:107]
	v_mfma_f32_16x16x32_bf16 v[100:103], v[76:79], v[204:207], v[100:103]
	v_mfma_f32_16x16x32_bf16 v[144:147], v[72:75], v[174:177], v[144:147]
	v_mfma_f32_16x16x32_bf16 v[140:143], v[80:83], v[174:177], v[140:143]
	v_mfma_f32_16x16x32_bf16 v[136:139], v[72:75], v[192:195], v[136:139]
	v_mfma_f32_16x16x32_bf16 v[132:135], v[80:83], v[192:195], v[132:135]
	v_mfma_f32_16x16x32_bf16 v[112:115], v[72:75], v[200:203], v[112:115]
	v_mfma_f32_16x16x32_bf16 v[108:111], v[80:83], v[200:203], v[108:111]
	v_mfma_f32_16x16x32_bf16 v[104:107], v[72:75], v[208:211], v[104:107]
	v_mfma_f32_16x16x32_bf16 v[100:103], v[80:83], v[208:211], v[100:103]


	v_mfma_f32_16x16x32_bf16 v[128:131], v[148:151], v[170:173], v[128:131]
	v_mfma_f32_16x16x32_bf16 v[124:127], v[162:165], v[170:173], v[124:127]
	v_mfma_f32_16x16x32_bf16 v[120:123], v[148:151], v[188:191], v[120:123]
	v_mfma_f32_16x16x32_bf16 v[116:119], v[162:165], v[188:191], v[116:119]
	v_mfma_f32_16x16x32_bf16 v[96:99], v[148:151], v[196:199], v[96:99]
	v_mfma_f32_16x16x32_bf16 v[92:95], v[162:165], v[196:199], v[92:95]
	v_mfma_f32_16x16x32_bf16 v[88:91], v[148:151], v[204:207], v[88:91]
	v_mfma_f32_16x16x32_bf16 v[84:87], v[162:165], v[204:207], v[84:87]
	v_mfma_f32_16x16x32_bf16 v[128:131], v[158:161], v[174:177], v[128:131]
	v_mfma_f32_16x16x32_bf16 v[124:127], v[166:169], v[174:177], v[124:127]
	v_mfma_f32_16x16x32_bf16 v[120:123], v[158:161], v[192:195], v[120:123]
	v_mfma_f32_16x16x32_bf16 v[116:119], v[166:169], v[192:195], v[116:119]
	v_mfma_f32_16x16x32_bf16 v[96:99], v[158:161], v[200:203], v[96:99]
	v_mfma_f32_16x16x32_bf16 v[92:95], v[166:169], v[200:203], v[92:95]
	v_mfma_f32_16x16x32_bf16 v[88:91], v[158:161], v[208:211], v[88:91]
	v_mfma_f32_16x16x32_bf16 v[84:87], v[166:169], v[208:211], v[84:87]

	s_barrier
	s_add_i32 s33, s33, s43
	v_lshl_add_u64 v[178:179], s[30:31], 0, v[180:181]
	s_mov_b32 m0, s33
	ds_read_b128 v[170:173], v213 offset:16384
	ds_read_b128 v[174:177], v213 offset:17408
	ds_read_b128 v[188:191], v213 offset:18432
	ds_read_b128 v[192:195], v213 offset:19456
	ds_read_b128 v[196:199], v213 offset:20480
	ds_read_b128 v[200:203], v213 offset:21504
	ds_read_b128 v[204:207], v213 offset:22528
	ds_read_b128 v[208:211], v213 offset:23552
	global_load_lds_dwordx4 v[178:179], off
	s_add_i32 m0, s33, 0x2000
	s_add_u32 s44, s30, 0x40000
	v_lshl_add_u64 v[214:215], s[30:31], 0, v[152:153]
	s_addc_u32 s45, s31, 0
	s_add_i32 s33, s47, s43
	global_load_lds_dwordx4 v[214:215], off
	v_lshl_add_u64 v[216:217], s[44:45], 0, v[180:181]
	s_mov_b32 m0, s33
	v_lshl_add_u64 v[218:219], s[34:35], 0, v[152:153]
	global_load_lds_dwordx4 v[216:217], off
	v_lshl_add_u64 v[216:217], s[44:45], 0, v[152:153]
	s_add_i32 m0, s33, 0x2000
	s_nop 0
	global_load_lds_dwordx4 v[216:217], off
	v_lshl_add_u64 v[216:217], s[34:35], 0, v[180:181]
	s_mov_b32 m0, s56
	s_nop 0
	global_load_lds_dwordx4 v[216:217], off
	s_mov_b32 m0, s57
	s_nop 0
	global_load_lds_dwordx4 v[218:219], off
	s_waitcnt vmcnt(8)
	s_waitcnt lgkmcnt(0)
	s_barrier

	s_waitcnt lgkmcnt(0)
	v_mfma_f32_16x16x32_bf16 v[64:67], v[68:71], v[170:173], v[64:67]
	v_mfma_f32_16x16x32_bf16 v[60:63], v[76:79], v[170:173], v[60:63]
	v_mfma_f32_16x16x32_bf16 v[56:59], v[68:71], v[188:191], v[56:59]
	v_mfma_f32_16x16x32_bf16 v[52:55], v[76:79], v[188:191], v[52:55]
	v_mfma_f32_16x16x32_bf16 v[32:35], v[68:71], v[196:199], v[32:35]
	v_mfma_f32_16x16x32_bf16 v[28:31], v[76:79], v[196:199], v[28:31]
	v_mfma_f32_16x16x32_bf16 v[16:19], v[68:71], v[204:207], v[16:19]
	v_mfma_f32_16x16x32_bf16 v[12:15], v[76:79], v[204:207], v[12:15]
	v_mfma_f32_16x16x32_bf16 v[64:67], v[72:75], v[174:177], v[64:67]
	v_mfma_f32_16x16x32_bf16 v[60:63], v[80:83], v[174:177], v[60:63]
	v_mfma_f32_16x16x32_bf16 v[56:59], v[72:75], v[192:195], v[56:59]
	v_mfma_f32_16x16x32_bf16 v[52:55], v[80:83], v[192:195], v[52:55]
	v_mfma_f32_16x16x32_bf16 v[32:35], v[72:75], v[200:203], v[32:35]
	v_mfma_f32_16x16x32_bf16 v[28:31], v[80:83], v[200:203], v[28:31]
	v_mfma_f32_16x16x32_bf16 v[16:19], v[72:75], v[208:211], v[16:19]
	v_mfma_f32_16x16x32_bf16 v[12:15], v[80:83], v[208:211], v[12:15]


	v_mfma_f32_16x16x32_bf16 v[48:51], v[148:151], v[170:173], v[48:51]
	v_mfma_f32_16x16x32_bf16 v[44:47], v[162:165], v[170:173], v[44:47]
	v_mfma_f32_16x16x32_bf16 v[40:43], v[148:151], v[188:191], v[40:43]
	v_mfma_f32_16x16x32_bf16 v[36:39], v[162:165], v[188:191], v[36:39]
	v_mfma_f32_16x16x32_bf16 v[24:27], v[148:151], v[196:199], v[24:27]
	v_mfma_f32_16x16x32_bf16 v[20:23], v[162:165], v[196:199], v[20:23]
	v_mfma_f32_16x16x32_bf16 v[8:11], v[148:151], v[204:207], v[8:11]
	v_mfma_f32_16x16x32_bf16 v[4:7], v[162:165], v[204:207], v[4:7]
	v_mfma_f32_16x16x32_bf16 v[48:51], v[158:161], v[174:177], v[48:51]
	v_mfma_f32_16x16x32_bf16 v[44:47], v[166:169], v[174:177], v[44:47]
	v_mfma_f32_16x16x32_bf16 v[40:43], v[158:161], v[192:195], v[40:43]
	v_mfma_f32_16x16x32_bf16 v[36:39], v[166:169], v[192:195], v[36:39]
	v_mfma_f32_16x16x32_bf16 v[24:27], v[158:161], v[200:203], v[24:27]
	v_mfma_f32_16x16x32_bf16 v[20:23], v[166:169], v[200:203], v[20:23]
	v_mfma_f32_16x16x32_bf16 v[8:11], v[158:161], v[208:211], v[8:11]
	v_mfma_f32_16x16x32_bf16 v[4:7], v[166:169], v[208:211], v[4:7]

	s_barrier
	s_add_i32 s33, 0, 0x18000
	s_add_i32 s44, 0, 0x1c000
	v_add_u32_e32 v80, s33, v212
	v_add_u32_e32 v166, s44, v212
	ds_read_b128 v[68:71], v80
	ds_read_b128 v[72:75], v80 offset:1024
	ds_read_b128 v[76:79], v80 offset:2048
	ds_read_b128 v[80:83], v80 offset:3072
	ds_read_b128 v[148:151], v166
	ds_read_b128 v[158:161], v166 offset:1024
	ds_read_b128 v[162:165], v166 offset:2048
	ds_read_b128 v[166:169], v166 offset:3072
	s_add_u32 s34, s34, 0x40000
	s_addc_u32 s35, s35, 0
	s_mov_b32 m0, s58
	v_lshl_add_u64 v[220:221], s[34:35], 0, v[180:181]
	ds_read_b128 v[170:173], v213 offset:32768
	ds_read_b128 v[174:177], v213 offset:33792
	ds_read_b128 v[188:191], v213 offset:34816
	ds_read_b128 v[192:195], v213 offset:35840
	ds_read_b128 v[196:199], v213 offset:36864
	ds_read_b128 v[200:203], v213 offset:37888
	ds_read_b128 v[204:207], v213 offset:38912
	ds_read_b128 v[208:211], v213 offset:39936
	global_load_lds_dwordx4 v[220:221], off
	v_lshl_add_u64 v[220:221], s[34:35], 0, v[152:153]
	s_mov_b32 m0, s59
	s_nop 0
	global_load_lds_dwordx4 v[220:221], off
	s_waitcnt vmcnt(8)
	s_waitcnt lgkmcnt(0)
	s_barrier

	s_waitcnt lgkmcnt(0)
	v_mfma_f32_16x16x32_bf16 v[144:147], v[68:71], v[170:173], v[144:147]
	v_mfma_f32_16x16x32_bf16 v[140:143], v[76:79], v[170:173], v[140:143]
	v_mfma_f32_16x16x32_bf16 v[136:139], v[68:71], v[188:191], v[136:139]
	v_mfma_f32_16x16x32_bf16 v[132:135], v[76:79], v[188:191], v[132:135]
	v_mfma_f32_16x16x32_bf16 v[112:115], v[68:71], v[196:199], v[112:115]
	v_mfma_f32_16x16x32_bf16 v[108:111], v[76:79], v[196:199], v[108:111]
	v_mfma_f32_16x16x32_bf16 v[104:107], v[68:71], v[204:207], v[104:107]
	v_mfma_f32_16x16x32_bf16 v[100:103], v[76:79], v[204:207], v[100:103]
	v_mfma_f32_16x16x32_bf16 v[144:147], v[72:75], v[174:177], v[144:147]
	v_mfma_f32_16x16x32_bf16 v[140:143], v[80:83], v[174:177], v[140:143]
	v_mfma_f32_16x16x32_bf16 v[136:139], v[72:75], v[192:195], v[136:139]
	v_mfma_f32_16x16x32_bf16 v[132:135], v[80:83], v[192:195], v[132:135]
	v_mfma_f32_16x16x32_bf16 v[112:115], v[72:75], v[200:203], v[112:115]
	v_mfma_f32_16x16x32_bf16 v[108:111], v[80:83], v[200:203], v[108:111]
	v_mfma_f32_16x16x32_bf16 v[104:107], v[72:75], v[208:211], v[104:107]
	v_mfma_f32_16x16x32_bf16 v[100:103], v[80:83], v[208:211], v[100:103]


	v_mfma_f32_16x16x32_bf16 v[128:131], v[148:151], v[170:173], v[128:131]
	v_mfma_f32_16x16x32_bf16 v[124:127], v[162:165], v[170:173], v[124:127]
	v_mfma_f32_16x16x32_bf16 v[120:123], v[148:151], v[188:191], v[120:123]
	v_mfma_f32_16x16x32_bf16 v[116:119], v[162:165], v[188:191], v[116:119]
	v_mfma_f32_16x16x32_bf16 v[96:99], v[148:151], v[196:199], v[96:99]
	v_mfma_f32_16x16x32_bf16 v[92:95], v[162:165], v[196:199], v[92:95]
	v_mfma_f32_16x16x32_bf16 v[88:91], v[148:151], v[204:207], v[88:91]
	v_mfma_f32_16x16x32_bf16 v[84:87], v[162:165], v[204:207], v[84:87]
	v_mfma_f32_16x16x32_bf16 v[128:131], v[158:161], v[174:177], v[128:131]
	v_mfma_f32_16x16x32_bf16 v[124:127], v[166:169], v[174:177], v[124:127]
	v_mfma_f32_16x16x32_bf16 v[120:123], v[158:161], v[192:195], v[120:123]
	v_mfma_f32_16x16x32_bf16 v[116:119], v[166:169], v[192:195], v[116:119]
	v_mfma_f32_16x16x32_bf16 v[96:99], v[158:161], v[200:203], v[96:99]
	v_mfma_f32_16x16x32_bf16 v[92:95], v[166:169], v[200:203], v[92:95]
	v_mfma_f32_16x16x32_bf16 v[88:91], v[158:161], v[208:211], v[88:91]
	v_mfma_f32_16x16x32_bf16 v[84:87], v[166:169], v[208:211], v[84:87]

	s_barrier
	s_add_i32 s33, s33, s43
	v_lshl_add_u64 v[178:179], v[178:179], 0, s[52:53]
	s_mov_b32 m0, s33
	ds_read_b128 v[170:173], v213 offset:49152
	ds_read_b128 v[174:177], v213 offset:50176
	ds_read_b128 v[188:191], v213 offset:51200
	ds_read_b128 v[192:195], v213 offset:52224
	ds_read_b128 v[196:199], v213 offset:53248
	ds_read_b128 v[200:203], v213 offset:54272
	ds_read_b128 v[204:207], v213 offset:55296
	ds_read_b128 v[208:211], v213 offset:56320
	global_load_lds_dwordx4 v[178:179], off
	s_add_i32 m0, s33, 0x2000
	s_add_u32 s30, s30, 0x40080
	v_lshl_add_u64 v[178:179], v[214:215], 0, s[52:53]
	s_addc_u32 s31, s31, 0
	s_add_i32 s33, s44, s43
	global_load_lds_dwordx4 v[178:179], off
	v_lshl_add_u64 v[178:179], s[30:31], 0, v[180:181]
	s_mov_b32 m0, s33
	s_nop 0
	global_load_lds_dwordx4 v[178:179], off
	v_lshl_add_u64 v[178:179], s[30:31], 0, v[152:153]
	s_add_i32 m0, s33, 0x2000
	s_nop 0
	global_load_lds_dwordx4 v[178:179], off
	v_lshl_add_u64 v[178:179], v[216:217], 0, s[52:53]
	s_mov_b32 m0, s84
	s_nop 0
	global_load_lds_dwordx4 v[178:179], off
	v_lshl_add_u64 v[178:179], v[218:219], 0, s[52:53]
	s_mov_b32 m0, s85
	s_nop 0
	global_load_lds_dwordx4 v[178:179], off
	s_waitcnt vmcnt(8)
	s_waitcnt lgkmcnt(0)
	s_barrier

	s_waitcnt lgkmcnt(0)
	v_mfma_f32_16x16x32_bf16 v[64:67], v[68:71], v[170:173], v[64:67]
	v_mfma_f32_16x16x32_bf16 v[60:63], v[76:79], v[170:173], v[60:63]
	v_mfma_f32_16x16x32_bf16 v[56:59], v[68:71], v[188:191], v[56:59]
	v_mfma_f32_16x16x32_bf16 v[52:55], v[76:79], v[188:191], v[52:55]
	v_mfma_f32_16x16x32_bf16 v[32:35], v[68:71], v[196:199], v[32:35]
	v_mfma_f32_16x16x32_bf16 v[28:31], v[76:79], v[196:199], v[28:31]
	v_mfma_f32_16x16x32_bf16 v[16:19], v[68:71], v[204:207], v[16:19]
	v_mfma_f32_16x16x32_bf16 v[12:15], v[76:79], v[204:207], v[12:15]
	v_mfma_f32_16x16x32_bf16 v[64:67], v[72:75], v[174:177], v[64:67]
	v_mfma_f32_16x16x32_bf16 v[60:63], v[80:83], v[174:177], v[60:63]
	v_mfma_f32_16x16x32_bf16 v[56:59], v[72:75], v[192:195], v[56:59]
	v_mfma_f32_16x16x32_bf16 v[52:55], v[80:83], v[192:195], v[52:55]
	v_mfma_f32_16x16x32_bf16 v[32:35], v[72:75], v[200:203], v[32:35]
	v_mfma_f32_16x16x32_bf16 v[28:31], v[80:83], v[200:203], v[28:31]
	v_mfma_f32_16x16x32_bf16 v[16:19], v[72:75], v[208:211], v[16:19]
	v_mfma_f32_16x16x32_bf16 v[12:15], v[80:83], v[208:211], v[12:15]


	v_mfma_f32_16x16x32_bf16 v[48:51], v[148:151], v[170:173], v[48:51]
	v_mfma_f32_16x16x32_bf16 v[44:47], v[162:165], v[170:173], v[44:47]
	v_mfma_f32_16x16x32_bf16 v[40:43], v[148:151], v[188:191], v[40:43]
	v_mfma_f32_16x16x32_bf16 v[36:39], v[162:165], v[188:191], v[36:39]
	v_mfma_f32_16x16x32_bf16 v[24:27], v[148:151], v[196:199], v[24:27]
	v_mfma_f32_16x16x32_bf16 v[20:23], v[162:165], v[196:199], v[20:23]
	v_mfma_f32_16x16x32_bf16 v[8:11], v[148:151], v[204:207], v[8:11]
	v_mfma_f32_16x16x32_bf16 v[4:7], v[162:165], v[204:207], v[4:7]
	v_mfma_f32_16x16x32_bf16 v[48:51], v[158:161], v[174:177], v[48:51]
	v_mfma_f32_16x16x32_bf16 v[44:47], v[166:169], v[174:177], v[44:47]
	v_mfma_f32_16x16x32_bf16 v[40:43], v[158:161], v[192:195], v[40:43]
	v_mfma_f32_16x16x32_bf16 v[36:39], v[166:169], v[192:195], v[36:39]
	v_mfma_f32_16x16x32_bf16 v[24:27], v[158:161], v[200:203], v[24:27]
	v_mfma_f32_16x16x32_bf16 v[20:23], v[166:169], v[200:203], v[20:23]
	v_mfma_f32_16x16x32_bf16 v[8:11], v[158:161], v[208:211], v[8:11]
	v_mfma_f32_16x16x32_bf16 v[4:7], v[166:169], v[208:211], v[4:7]

	s_barrier
	s_add_i32 s27, s27, 2
	s_add_u32 s28, s28, 0x100
	s_addc_u32 s29, s29, 0
	s_add_u32 s19, s19, 0x100
	s_addc_u32 s21, s21, 0
	s_cmp_gt_u32 s27, 13
	s_cbranch_scc0 .LBB0_255
	s_setprio 0
	s_and_b64 vcc, exec, s[14:15]
	s_cbranch_vccz .LBB0_258
	s_barrier

.LBB0_299:
	s_mov_b32 s20, s2
	s_ashr_i32 s21, s2, 31
	s_mov_b32 s16, s5
	s_mov_b32 s18, s4
	s_lshl_b64 s[4:5], s[20:21], 19
	s_add_u32 s2, s40, s4
	s_mov_b32 s55, s17
	s_addc_u32 s4, s41, s5
	s_ashr_i32 s17, s16, 31
	s_lshl_b64 s[26:27], s[16:17], 1
	s_add_u32 s24, s2, s26
	s_addc_u32 s25, s4, s27
	s_and_b64 s[4:5], s[22:23], exec
	s_mov_b32 s54, s19
	s_cselect_b32 s2, s25, s35
	s_cselect_b32 s4, s24, s34
	s_ashr_i32 s19, s18, 31
	s_lshl_b64 s[38:39], s[18:19], 19
	s_add_u32 s5, s42, s38
	s_addc_u32 s17, s43, s39
	s_add_u32 s26, s5, s26
	s_addc_u32 s27, s17, s27
	s_and_b64 s[38:39], s[22:23], exec
	s_cselect_b32 s5, s27, s37
	s_cselect_b32 s17, s26, s36
	s_add_i32 s19, s1, -2
	s_add_u32 s34, s34, 0x40080
	s_addc_u32 s35, s35, 0
	s_add_u32 s21, s36, 0x100
	v_mov_b32_e32 v4, 0
	s_addc_u32 s29, s37, 0
	s_mov_b32 s31, 0
	v_mov_b32_e32 v5, v4
	v_mov_b32_e32 v6, v4
	v_mov_b32_e32 v7, v4
	v_mov_b32_e32 v8, v4
	v_mov_b32_e32 v9, v4
	v_mov_b32_e32 v10, v4
	v_mov_b32_e32 v11, v4
	v_mov_b32_e32 v16, v4
	v_mov_b32_e32 v17, v4
	v_mov_b32_e32 v18, v4
	v_mov_b32_e32 v19, v4
	v_mov_b32_e32 v20, v4
	v_mov_b32_e32 v21, v4
	v_mov_b32_e32 v22, v4
	v_mov_b32_e32 v23, v4
	v_mov_b32_e32 v36, v4
	v_mov_b32_e32 v37, v4
	v_mov_b32_e32 v38, v4
	v_mov_b32_e32 v39, v4
	v_mov_b32_e32 v40, v4
	v_mov_b32_e32 v41, v4
	v_mov_b32_e32 v42, v4
	v_mov_b32_e32 v43, v4
	v_mov_b32_e32 v44, v4
	v_mov_b32_e32 v45, v4
	v_mov_b32_e32 v46, v4
	v_mov_b32_e32 v47, v4
	v_mov_b32_e32 v48, v4
	v_mov_b32_e32 v49, v4
	v_mov_b32_e32 v50, v4
	v_mov_b32_e32 v51, v4
	v_mov_b32_e32 v12, v4
	v_mov_b32_e32 v13, v4
	v_mov_b32_e32 v14, v4
	v_mov_b32_e32 v15, v4
	v_mov_b32_e32 v24, v4
	v_mov_b32_e32 v25, v4
	v_mov_b32_e32 v26, v4
	v_mov_b32_e32 v27, v4
	v_mov_b32_e32 v28, v4
	v_mov_b32_e32 v29, v4
	v_mov_b32_e32 v30, v4
	v_mov_b32_e32 v31, v4
	v_mov_b32_e32 v32, v4
	v_mov_b32_e32 v33, v4
	v_mov_b32_e32 v34, v4
	v_mov_b32_e32 v35, v4
	v_mov_b32_e32 v52, v4
	v_mov_b32_e32 v53, v4
	v_mov_b32_e32 v54, v4
	v_mov_b32_e32 v55, v4
	v_mov_b32_e32 v56, v4
	v_mov_b32_e32 v57, v4
	v_mov_b32_e32 v58, v4
	v_mov_b32_e32 v59, v4
	v_mov_b32_e32 v60, v4
	v_mov_b32_e32 v61, v4
	v_mov_b32_e32 v62, v4
	v_mov_b32_e32 v63, v4
	v_mov_b32_e32 v64, v4
	v_mov_b32_e32 v65, v4
	v_mov_b32_e32 v66, v4
	v_mov_b32_e32 v67, v4
	v_mov_b32_e32 v68, v4
	v_mov_b32_e32 v69, v4
	v_mov_b32_e32 v70, v4
	v_mov_b32_e32 v71, v4
	v_mov_b32_e32 v72, v4
	v_mov_b32_e32 v73, v4
	v_mov_b32_e32 v74, v4
	v_mov_b32_e32 v75, v4
	v_mov_b32_e32 v76, v4
	v_mov_b32_e32 v77, v4
	v_mov_b32_e32 v78, v4
	v_mov_b32_e32 v79, v4
	v_mov_b32_e32 v80, v4
	v_mov_b32_e32 v81, v4
	v_mov_b32_e32 v82, v4
	v_mov_b32_e32 v83, v4
	v_mov_b32_e32 v112, v4
	v_mov_b32_e32 v113, v4
	v_mov_b32_e32 v114, v4
	v_mov_b32_e32 v115, v4
	v_mov_b32_e32 v116, v4
	v_mov_b32_e32 v117, v4
	v_mov_b32_e32 v118, v4
	v_mov_b32_e32 v119, v4
	v_mov_b32_e32 v120, v4
	v_mov_b32_e32 v121, v4
	v_mov_b32_e32 v122, v4
	v_mov_b32_e32 v123, v4
	v_mov_b32_e32 v124, v4
	v_mov_b32_e32 v125, v4
	v_mov_b32_e32 v126, v4
	v_mov_b32_e32 v127, v4
	v_mov_b32_e32 v84, v4
	v_mov_b32_e32 v85, v4
	v_mov_b32_e32 v86, v4
	v_mov_b32_e32 v87, v4
	v_mov_b32_e32 v88, v4
	v_mov_b32_e32 v89, v4
	v_mov_b32_e32 v90, v4
	v_mov_b32_e32 v91, v4
	v_mov_b32_e32 v92, v4
	v_mov_b32_e32 v93, v4
	v_mov_b32_e32 v94, v4
	v_mov_b32_e32 v95, v4
	v_mov_b32_e32 v96, v4
	v_mov_b32_e32 v97, v4
	v_mov_b32_e32 v98, v4
	v_mov_b32_e32 v99, v4
	v_mov_b32_e32 v132, v4
	v_mov_b32_e32 v133, v4
	v_mov_b32_e32 v134, v4
	v_mov_b32_e32 v135, v4
	v_mov_b32_e32 v136, v4
	v_mov_b32_e32 v137, v4
	v_mov_b32_e32 v138, v4
	v_mov_b32_e32 v139, v4
	v_mov_b32_e32 v140, v4
	v_mov_b32_e32 v141, v4
	v_mov_b32_e32 v142, v4
	v_mov_b32_e32 v143, v4
	v_mov_b32_e32 v144, v4
	v_mov_b32_e32 v145, v4
	v_mov_b32_e32 v146, v4
	v_mov_b32_e32 v147, v4
	s_waitcnt vmcnt(0)
	v_readfirstlane_b32 s101, v186
	s_nop 3
	s_lshr_b32 s101, s101, 8
	s_cmp_eq_u32 s101, 1
	s_cbranch_scc0 .Lprio_4
	s_setprio 1
.Lprio_4:
.LBB0_300:
	s_add_i32 s33, s31, 2
	s_add_u32 s36, s34, 0xfffc0080
	s_addc_u32 s37, s35, -1
	s_add_i32 s44, 0, 0x10000
	s_cmp_eq_u32 s19, s31
	s_cselect_b32 s39, s2, s37
	s_cselect_b32 s38, s4, s36
	s_cselect_b32 s37, s5, s29
	s_cselect_b32 s36, s17, s21
	s_add_i32 s31, 0, 0x14000
	v_add_u32_e32 v128, s44, v220
	v_add_u32_e32 v160, s31, v220
	ds_read_b128 v[100:103], v128
	ds_read_b128 v[104:107], v128 offset:1024
	ds_read_b128 v[108:111], v128 offset:2048
	ds_read_b128 v[128:131], v128 offset:3072
	ds_read_b128 v[148:151], v160
	ds_read_b128 v[152:155], v160 offset:1024
	ds_read_b128 v[156:159], v160 offset:2048
	ds_read_b128 v[160:163], v160 offset:3072
	v_lshl_add_u64 v[210:211], s[34:35], 0, v[190:191]
	s_add_i32 m0, s51, 0xc000
	ds_read_b128 v[164:167], v221
	ds_read_b128 v[168:171], v221 offset:1024
	ds_read_b128 v[172:175], v221 offset:2048
	ds_read_b128 v[176:179], v221 offset:3072
	ds_read_b128 v[194:197], v221 offset:4096
	ds_read_b128 v[198:201], v221 offset:5120
	ds_read_b128 v[202:205], v221 offset:6144
	ds_read_b128 v[206:209], v221 offset:7168
	global_load_lds_dwordx4 v[210:211], off
	v_lshl_add_u64 v[210:211], s[34:35], 0, v[192:193]
	s_add_i32 m0, s51, 0xe000
	s_nop 0
	global_load_lds_dwordx4 v[210:211], off
	s_waitcnt vmcnt(8)
	s_waitcnt lgkmcnt(0)
	s_barrier

	s_waitcnt lgkmcnt(0)
	v_mfma_f32_16x16x32_bf16 v[144:147], v[100:103], v[164:167], v[144:147]
	v_mfma_f32_16x16x32_bf16 v[140:143], v[108:111], v[164:167], v[140:143]
	v_mfma_f32_16x16x32_bf16 v[136:139], v[100:103], v[172:175], v[136:139]
	v_mfma_f32_16x16x32_bf16 v[132:135], v[108:111], v[172:175], v[132:135]
	v_mfma_f32_16x16x32_bf16 v[96:99], v[100:103], v[194:197], v[96:99]
	v_mfma_f32_16x16x32_bf16 v[92:95], v[108:111], v[194:197], v[92:95]
	v_mfma_f32_16x16x32_bf16 v[88:91], v[100:103], v[202:205], v[88:91]
	v_mfma_f32_16x16x32_bf16 v[84:87], v[108:111], v[202:205], v[84:87]
	v_mfma_f32_16x16x32_bf16 v[144:147], v[104:107], v[168:171], v[144:147]
	v_mfma_f32_16x16x32_bf16 v[140:143], v[128:131], v[168:171], v[140:143]
	v_mfma_f32_16x16x32_bf16 v[136:139], v[104:107], v[176:179], v[136:139]
	v_mfma_f32_16x16x32_bf16 v[132:135], v[128:131], v[176:179], v[132:135]
	v_mfma_f32_16x16x32_bf16 v[96:99], v[104:107], v[198:201], v[96:99]
	v_mfma_f32_16x16x32_bf16 v[92:95], v[128:131], v[198:201], v[92:95]
	v_mfma_f32_16x16x32_bf16 v[88:91], v[104:107], v[206:209], v[88:91]
	v_mfma_f32_16x16x32_bf16 v[84:87], v[128:131], v[206:209], v[84:87]


	v_mfma_f32_16x16x32_bf16 v[124:127], v[148:151], v[164:167], v[124:127]
	v_mfma_f32_16x16x32_bf16 v[120:123], v[156:159], v[164:167], v[120:123]
	v_mfma_f32_16x16x32_bf16 v[116:119], v[148:151], v[172:175], v[116:119]
	v_mfma_f32_16x16x32_bf16 v[112:115], v[156:159], v[172:175], v[112:115]
	v_mfma_f32_16x16x32_bf16 v[80:83], v[148:151], v[194:197], v[80:83]
	v_mfma_f32_16x16x32_bf16 v[76:79], v[156:159], v[194:197], v[76:79]
	v_mfma_f32_16x16x32_bf16 v[72:75], v[148:151], v[202:205], v[72:75]
	v_mfma_f32_16x16x32_bf16 v[68:71], v[156:159], v[202:205], v[68:71]
	v_mfma_f32_16x16x32_bf16 v[124:127], v[152:155], v[168:171], v[124:127]
	v_mfma_f32_16x16x32_bf16 v[120:123], v[160:163], v[168:171], v[120:123]
	v_mfma_f32_16x16x32_bf16 v[116:119], v[152:155], v[176:179], v[116:119]
	v_mfma_f32_16x16x32_bf16 v[112:115], v[160:163], v[176:179], v[112:115]
	v_mfma_f32_16x16x32_bf16 v[80:83], v[152:155], v[198:201], v[80:83]
	v_mfma_f32_16x16x32_bf16 v[76:79], v[160:163], v[198:201], v[76:79]
	v_mfma_f32_16x16x32_bf16 v[72:75], v[152:155], v[206:209], v[72:75]
	v_mfma_f32_16x16x32_bf16 v[68:71], v[160:163], v[206:209], v[68:71]

	s_barrier
	s_add_i32 s44, s44, s50
	v_lshl_add_u64 v[210:211], s[36:37], 0, v[180:181]
	s_mov_b32 m0, s44
	ds_read_b128 v[164:167], v221 offset:16384
	ds_read_b128 v[168:171], v221 offset:17408
	ds_read_b128 v[172:175], v221 offset:18432
	ds_read_b128 v[176:179], v221 offset:19456
	ds_read_b128 v[194:197], v221 offset:20480
	ds_read_b128 v[198:201], v221 offset:21504
	ds_read_b128 v[202:205], v221 offset:22528
	ds_read_b128 v[206:209], v221 offset:23552
	global_load_lds_dwordx4 v[210:211], off
	s_add_i32 m0, s44, 0x2000
	s_add_u32 s44, s36, 0x40000
	v_lshl_add_u64 v[212:213], s[36:37], 0, v[188:189]
	s_addc_u32 s45, s37, 0
	s_add_i32 s31, s31, s50
	global_load_lds_dwordx4 v[212:213], off
	v_lshl_add_u64 v[214:215], s[44:45], 0, v[180:181]
	s_mov_b32 m0, s31
	v_lshl_add_u64 v[216:217], s[38:39], 0, v[188:189]
	global_load_lds_dwordx4 v[214:215], off
	v_lshl_add_u64 v[214:215], s[44:45], 0, v[188:189]
	s_add_i32 m0, s31, 0x2000
	s_nop 0
	global_load_lds_dwordx4 v[214:215], off
	v_lshl_add_u64 v[214:215], s[38:39], 0, v[180:181]
	s_mov_b32 m0, s51
	s_nop 0
	global_load_lds_dwordx4 v[214:215], off
	s_mov_b32 m0, s56
	s_nop 0
	global_load_lds_dwordx4 v[216:217], off
	s_waitcnt vmcnt(8)
	s_waitcnt lgkmcnt(0)
	s_barrier

	s_waitcnt lgkmcnt(0)
	v_mfma_f32_16x16x32_bf16 v[64:67], v[100:103], v[164:167], v[64:67]
	v_mfma_f32_16x16x32_bf16 v[60:63], v[108:111], v[164:167], v[60:63]
	v_mfma_f32_16x16x32_bf16 v[56:59], v[100:103], v[172:175], v[56:59]
	v_mfma_f32_16x16x32_bf16 v[52:55], v[108:111], v[172:175], v[52:55]
	v_mfma_f32_16x16x32_bf16 v[32:35], v[100:103], v[194:197], v[32:35]
	v_mfma_f32_16x16x32_bf16 v[28:31], v[108:111], v[194:197], v[28:31]
	v_mfma_f32_16x16x32_bf16 v[24:27], v[100:103], v[202:205], v[24:27]
	v_mfma_f32_16x16x32_bf16 v[12:15], v[108:111], v[202:205], v[12:15]
	v_mfma_f32_16x16x32_bf16 v[64:67], v[104:107], v[168:171], v[64:67]
	v_mfma_f32_16x16x32_bf16 v[60:63], v[128:131], v[168:171], v[60:63]
	v_mfma_f32_16x16x32_bf16 v[56:59], v[104:107], v[176:179], v[56:59]
	v_mfma_f32_16x16x32_bf16 v[52:55], v[128:131], v[176:179], v[52:55]
	v_mfma_f32_16x16x32_bf16 v[32:35], v[104:107], v[198:201], v[32:35]
	v_mfma_f32_16x16x32_bf16 v[28:31], v[128:131], v[198:201], v[28:31]
	v_mfma_f32_16x16x32_bf16 v[24:27], v[104:107], v[206:209], v[24:27]
	v_mfma_f32_16x16x32_bf16 v[12:15], v[128:131], v[206:209], v[12:15]


	v_mfma_f32_16x16x32_bf16 v[48:51], v[148:151], v[164:167], v[48:51]
	v_mfma_f32_16x16x32_bf16 v[44:47], v[156:159], v[164:167], v[44:47]
	v_mfma_f32_16x16x32_bf16 v[40:43], v[148:151], v[172:175], v[40:43]
	v_mfma_f32_16x16x32_bf16 v[36:39], v[156:159], v[172:175], v[36:39]
	v_mfma_f32_16x16x32_bf16 v[20:23], v[148:151], v[194:197], v[20:23]
	v_mfma_f32_16x16x32_bf16 v[16:19], v[156:159], v[194:197], v[16:19]
	v_mfma_f32_16x16x32_bf16 v[8:11], v[148:151], v[202:205], v[8:11]
	v_mfma_f32_16x16x32_bf16 v[4:7], v[156:159], v[202:205], v[4:7]
	v_mfma_f32_16x16x32_bf16 v[48:51], v[152:155], v[168:171], v[48:51]
	v_mfma_f32_16x16x32_bf16 v[44:47], v[160:163], v[168:171], v[44:47]
	v_mfma_f32_16x16x32_bf16 v[40:43], v[152:155], v[176:179], v[40:43]
	v_mfma_f32_16x16x32_bf16 v[36:39], v[160:163], v[176:179], v[36:39]
	v_mfma_f32_16x16x32_bf16 v[20:23], v[152:155], v[198:201], v[20:23]
	v_mfma_f32_16x16x32_bf16 v[16:19], v[160:163], v[198:201], v[16:19]
	v_mfma_f32_16x16x32_bf16 v[8:11], v[152:155], v[206:209], v[8:11]
	v_mfma_f32_16x16x32_bf16 v[4:7], v[160:163], v[206:209], v[4:7]

	s_barrier
	s_add_i32 s31, 0, 0x18000
	s_add_i32 s44, 0, 0x1c000
	v_add_u32_e32 v128, s31, v220
	v_add_u32_e32 v160, s44, v220
	ds_read_b128 v[100:103], v128
	ds_read_b128 v[104:107], v128 offset:1024
	ds_read_b128 v[108:111], v128 offset:2048
	ds_read_b128 v[128:131], v128 offset:3072
	ds_read_b128 v[148:151], v160
	ds_read_b128 v[152:155], v160 offset:1024
	ds_read_b128 v[156:159], v160 offset:2048
	ds_read_b128 v[160:163], v160 offset:3072
	s_add_u32 s38, s38, 0x40000
	s_addc_u32 s39, s39, 0
	s_mov_b32 m0, s57
	v_lshl_add_u64 v[218:219], s[38:39], 0, v[180:181]
	ds_read_b128 v[164:167], v221 offset:32768
	ds_read_b128 v[168:171], v221 offset:33792
	ds_read_b128 v[172:175], v221 offset:34816
	ds_read_b128 v[176:179], v221 offset:35840
	ds_read_b128 v[194:197], v221 offset:36864
	ds_read_b128 v[198:201], v221 offset:37888
	ds_read_b128 v[202:205], v221 offset:38912
	ds_read_b128 v[206:209], v221 offset:39936
	global_load_lds_dwordx4 v[218:219], off
	v_lshl_add_u64 v[218:219], s[38:39], 0, v[188:189]
	s_mov_b32 m0, s58
	s_nop 0
	global_load_lds_dwordx4 v[218:219], off
	s_waitcnt vmcnt(8)
	s_waitcnt lgkmcnt(0)
	s_barrier

	s_waitcnt lgkmcnt(0)
	v_mfma_f32_16x16x32_bf16 v[144:147], v[100:103], v[164:167], v[144:147]
	v_mfma_f32_16x16x32_bf16 v[140:143], v[108:111], v[164:167], v[140:143]
	v_mfma_f32_16x16x32_bf16 v[136:139], v[100:103], v[172:175], v[136:139]
	v_mfma_f32_16x16x32_bf16 v[132:135], v[108:111], v[172:175], v[132:135]
	v_mfma_f32_16x16x32_bf16 v[96:99], v[100:103], v[194:197], v[96:99]
	v_mfma_f32_16x16x32_bf16 v[92:95], v[108:111], v[194:197], v[92:95]
	v_mfma_f32_16x16x32_bf16 v[88:91], v[100:103], v[202:205], v[88:91]
	v_mfma_f32_16x16x32_bf16 v[84:87], v[108:111], v[202:205], v[84:87]
	v_mfma_f32_16x16x32_bf16 v[144:147], v[104:107], v[168:171], v[144:147]
	v_mfma_f32_16x16x32_bf16 v[140:143], v[128:131], v[168:171], v[140:143]
	v_mfma_f32_16x16x32_bf16 v[136:139], v[104:107], v[176:179], v[136:139]
	v_mfma_f32_16x16x32_bf16 v[132:135], v[128:131], v[176:179], v[132:135]
	v_mfma_f32_16x16x32_bf16 v[96:99], v[104:107], v[198:201], v[96:99]
	v_mfma_f32_16x16x32_bf16 v[92:95], v[128:131], v[198:201], v[92:95]
	v_mfma_f32_16x16x32_bf16 v[88:91], v[104:107], v[206:209], v[88:91]
	v_mfma_f32_16x16x32_bf16 v[84:87], v[128:131], v[206:209], v[84:87]


	v_mfma_f32_16x16x32_bf16 v[124:127], v[148:151], v[164:167], v[124:127]
	v_mfma_f32_16x16x32_bf16 v[120:123], v[156:159], v[164:167], v[120:123]
	v_mfma_f32_16x16x32_bf16 v[116:119], v[148:151], v[172:175], v[116:119]
	v_mfma_f32_16x16x32_bf16 v[112:115], v[156:159], v[172:175], v[112:115]
	v_mfma_f32_16x16x32_bf16 v[80:83], v[148:151], v[194:197], v[80:83]
	v_mfma_f32_16x16x32_bf16 v[76:79], v[156:159], v[194:197], v[76:79]
	v_mfma_f32_16x16x32_bf16 v[72:75], v[148:151], v[202:205], v[72:75]
	v_mfma_f32_16x16x32_bf16 v[68:71], v[156:159], v[202:205], v[68:71]
	v_mfma_f32_16x16x32_bf16 v[124:127], v[152:155], v[168:171], v[124:127]
	v_mfma_f32_16x16x32_bf16 v[120:123], v[160:163], v[168:171], v[120:123]
	v_mfma_f32_16x16x32_bf16 v[116:119], v[152:155], v[176:179], v[116:119]
	v_mfma_f32_16x16x32_bf16 v[112:115], v[160:163], v[176:179], v[112:115]
	v_mfma_f32_16x16x32_bf16 v[80:83], v[152:155], v[198:201], v[80:83]
	v_mfma_f32_16x16x32_bf16 v[76:79], v[160:163], v[198:201], v[76:79]
	v_mfma_f32_16x16x32_bf16 v[72:75], v[152:155], v[206:209], v[72:75]
	v_mfma_f32_16x16x32_bf16 v[68:71], v[160:163], v[206:209], v[68:71]

	s_barrier
	s_add_i32 s31, s31, s50
	v_lshl_add_u64 v[210:211], v[210:211], 0, s[52:53]
	s_mov_b32 m0, s31
	ds_read_b128 v[164:167], v221 offset:49152
	ds_read_b128 v[168:171], v221 offset:50176
	ds_read_b128 v[172:175], v221 offset:51200
	ds_read_b128 v[176:179], v221 offset:52224
	ds_read_b128 v[194:197], v221 offset:53248
	ds_read_b128 v[198:201], v221 offset:54272
	ds_read_b128 v[202:205], v221 offset:55296
	ds_read_b128 v[206:209], v221 offset:56320
	global_load_lds_dwordx4 v[210:211], off
	s_add_i32 m0, s31, 0x2000
	s_add_u32 s36, s36, 0x40080
	v_lshl_add_u64 v[210:211], v[212:213], 0, s[52:53]
	s_addc_u32 s37, s37, 0
	s_add_i32 s31, s44, s50
	global_load_lds_dwordx4 v[210:211], off
	v_lshl_add_u64 v[210:211], s[36:37], 0, v[180:181]
	s_mov_b32 m0, s31
	s_nop 0
	global_load_lds_dwordx4 v[210:211], off
	v_lshl_add_u64 v[210:211], s[36:37], 0, v[188:189]
	s_add_i32 m0, s31, 0x2000
	s_nop 0
	global_load_lds_dwordx4 v[210:211], off
	v_lshl_add_u64 v[210:211], v[214:215], 0, s[52:53]
	s_mov_b32 m0, s85
	s_nop 0
	global_load_lds_dwordx4 v[210:211], off
	v_lshl_add_u64 v[210:211], v[216:217], 0, s[52:53]
	s_mov_b32 m0, s86
	s_nop 0
	global_load_lds_dwordx4 v[210:211], off
	s_waitcnt vmcnt(8)
	s_waitcnt lgkmcnt(0)
	s_barrier

	s_waitcnt lgkmcnt(0)
	v_mfma_f32_16x16x32_bf16 v[64:67], v[100:103], v[164:167], v[64:67]
	v_mfma_f32_16x16x32_bf16 v[60:63], v[108:111], v[164:167], v[60:63]
	v_mfma_f32_16x16x32_bf16 v[56:59], v[100:103], v[172:175], v[56:59]
	v_mfma_f32_16x16x32_bf16 v[52:55], v[108:111], v[172:175], v[52:55]
	v_mfma_f32_16x16x32_bf16 v[32:35], v[100:103], v[194:197], v[32:35]
	v_mfma_f32_16x16x32_bf16 v[28:31], v[108:111], v[194:197], v[28:31]
	v_mfma_f32_16x16x32_bf16 v[24:27], v[100:103], v[202:205], v[24:27]
	v_mfma_f32_16x16x32_bf16 v[12:15], v[108:111], v[202:205], v[12:15]
	v_mfma_f32_16x16x32_bf16 v[64:67], v[104:107], v[168:171], v[64:67]
	v_mfma_f32_16x16x32_bf16 v[60:63], v[128:131], v[168:171], v[60:63]
	v_mfma_f32_16x16x32_bf16 v[56:59], v[104:107], v[176:179], v[56:59]
	v_mfma_f32_16x16x32_bf16 v[52:55], v[128:131], v[176:179], v[52:55]
	v_mfma_f32_16x16x32_bf16 v[32:35], v[104:107], v[198:201], v[32:35]
	v_mfma_f32_16x16x32_bf16 v[28:31], v[128:131], v[198:201], v[28:31]
	v_mfma_f32_16x16x32_bf16 v[24:27], v[104:107], v[206:209], v[24:27]
	v_mfma_f32_16x16x32_bf16 v[12:15], v[128:131], v[206:209], v[12:15]


	v_mfma_f32_16x16x32_bf16 v[48:51], v[148:151], v[164:167], v[48:51]
	v_mfma_f32_16x16x32_bf16 v[44:47], v[156:159], v[164:167], v[44:47]
	v_mfma_f32_16x16x32_bf16 v[40:43], v[148:151], v[172:175], v[40:43]
	v_mfma_f32_16x16x32_bf16 v[36:39], v[156:159], v[172:175], v[36:39]
	v_mfma_f32_16x16x32_bf16 v[20:23], v[148:151], v[194:197], v[20:23]
	v_mfma_f32_16x16x32_bf16 v[16:19], v[156:159], v[194:197], v[16:19]
	v_mfma_f32_16x16x32_bf16 v[8:11], v[148:151], v[202:205], v[8:11]
	v_mfma_f32_16x16x32_bf16 v[4:7], v[156:159], v[202:205], v[4:7]
	v_mfma_f32_16x16x32_bf16 v[48:51], v[152:155], v[168:171], v[48:51]
	v_mfma_f32_16x16x32_bf16 v[44:47], v[160:163], v[168:171], v[44:47]
	v_mfma_f32_16x16x32_bf16 v[40:43], v[152:155], v[176:179], v[40:43]
	v_mfma_f32_16x16x32_bf16 v[36:39], v[160:163], v[176:179], v[36:39]
	v_mfma_f32_16x16x32_bf16 v[20:23], v[152:155], v[198:201], v[20:23]
	v_mfma_f32_16x16x32_bf16 v[16:19], v[160:163], v[198:201], v[16:19]
	v_mfma_f32_16x16x32_bf16 v[8:11], v[152:155], v[206:209], v[8:11]
	v_mfma_f32_16x16x32_bf16 v[4:7], v[160:163], v[206:209], v[4:7]

	s_barrier
	s_add_u32 s34, s34, 0x100
	s_addc_u32 s35, s35, 0
	s_add_u32 s21, s21, 0x100
	s_addc_u32 s29, s29, 0
	s_cmp_ge_i32 s33, s1
	s_mov_b32 s31, s33
	s_cbranch_scc0 .LBB0_300
	s_setprio 0
	s_and_b64 vcc, exec, s[14:15]
	s_cbranch_vccz .LBB0_303
	s_barrier

.LBB0_670:
	s_ashr_i32 s21, s20, 31
	s_lshl_b64 s[0:1], s[20:21], 19
	s_add_u32 s22, s8, s0
	s_addc_u32 s23, s9, s1
	s_and_b64 s[0:1], s[6:7], exec
	s_cselect_b32 s0, s23, s31
	s_cselect_b32 s1, s22, s30
	s_ashr_i32 s19, s18, 31
	s_lshl_b64 s[4:5], s[18:19], 19
	s_add_u32 s24, s40, s4
	s_addc_u32 s25, s41, s5
	s_and_b64 s[4:5], s[6:7], exec
	s_cselect_b32 s2, s25, s35
	s_cselect_b32 s4, s24, s34
	s_add_u32 s30, s30, 0x40080
	s_addc_u32 s31, s31, 0
	s_add_u32 s5, s34, 0x100
	s_addc_u32 s19, s35, 0
	s_mov_b32 s21, -2
	v_readfirstlane_b32 s101, v186
	s_nop 3
	s_lshr_b32 s101, s101, 8
	s_cmp_eq_u32 s101, 1
	s_cbranch_scc0 .Lprio_5
	s_setprio 1
.Lprio_5:
	s_add_u32 s27, s30, 0xfffc0080
	s_addc_u32 s29, s31, -1
	s_add_i32 s33, 0, 0x10000
	s_cmp_eq_u32 s21, 12
	s_cselect_b32 s37, s0, s29
	s_cselect_b32 s36, s1, s27
	v_add_u32_e32 v144, s33, v157
	s_cselect_b32 s35, s2, s19
	s_cselect_b32 s34, s4, s5
	s_add_i32 s27, 0, 0x14000
	ds_read_b128 v[148:151], v144
	ds_read_b128 v[152:155], v144 offset:1024
	ds_read_b128 v[160:163], v144 offset:2048
	ds_read_b128 v[164:167], v144 offset:3072
	v_add_u32_e32 v144, s27, v157
	ds_read_b128 v[168:171], v144
	ds_read_b128 v[172:175], v144 offset:1024
	ds_read_b128 v[176:179], v144 offset:2048
	ds_read_b128 v[188:191], v144 offset:3072
	v_lshl_add_u64 v[144:145], s[30:31], 0, v[140:141]
	s_add_i32 m0, s43, 0xc000
	ds_read_b128 v[192:195], v158
	ds_read_b128 v[196:199], v158 offset:1024
	ds_read_b128 v[200:203], v158 offset:2048
	ds_read_b128 v[204:207], v158 offset:3072
	ds_read_b128 v[208:211], v158 offset:4096
	ds_read_b128 v[212:215], v158 offset:5120
	ds_read_b128 v[216:219], v158 offset:6144
	ds_read_b128 v[220:223], v158 offset:7168
	global_load_lds_dwordx4 v[144:145], off
	v_lshl_add_u64 v[144:145], s[30:31], 0, v[142:143]
	s_add_i32 m0, s43, 0xe000
	s_nop 0
	global_load_lds_dwordx4 v[144:145], off
	s_waitcnt vmcnt(24)
	s_waitcnt lgkmcnt(0)
	s_barrier

	s_waitcnt lgkmcnt(0)
	v_mfma_f32_16x16x32_bf16 v[128:131], v[148:151], v[192:195], 0
	v_mfma_f32_16x16x32_bf16 v[124:127], v[160:163], v[192:195], 0
	v_mfma_f32_16x16x32_bf16 v[112:115], v[148:151], v[200:203], 0
	v_mfma_f32_16x16x32_bf16 v[108:111], v[160:163], v[200:203], 0
	v_mfma_f32_16x16x32_bf16 v[96:99], v[148:151], v[208:211], 0
	v_mfma_f32_16x16x32_bf16 v[92:95], v[160:163], v[208:211], 0
	v_mfma_f32_16x16x32_bf16 v[80:83], v[148:151], v[216:219], 0
	v_mfma_f32_16x16x32_bf16 v[76:79], v[160:163], v[216:219], 0
	v_mfma_f32_16x16x32_bf16 v[128:131], v[152:155], v[196:199], v[128:131]
	v_mfma_f32_16x16x32_bf16 v[124:127], v[164:167], v[196:199], v[124:127]
	v_mfma_f32_16x16x32_bf16 v[112:115], v[152:155], v[204:207], v[112:115]
	v_mfma_f32_16x16x32_bf16 v[108:111], v[164:167], v[204:207], v[108:111]
	v_mfma_f32_16x16x32_bf16 v[96:99], v[152:155], v[212:215], v[96:99]
	v_mfma_f32_16x16x32_bf16 v[92:95], v[164:167], v[212:215], v[92:95]
	v_mfma_f32_16x16x32_bf16 v[80:83], v[152:155], v[220:223], v[80:83]
	v_mfma_f32_16x16x32_bf16 v[76:79], v[164:167], v[220:223], v[76:79]


	v_mfma_f32_16x16x32_bf16 v[120:123], v[168:171], v[192:195], 0
	v_mfma_f32_16x16x32_bf16 v[116:119], v[176:179], v[192:195], 0
	v_mfma_f32_16x16x32_bf16 v[104:107], v[168:171], v[200:203], 0
	v_mfma_f32_16x16x32_bf16 v[100:103], v[176:179], v[200:203], 0
	v_mfma_f32_16x16x32_bf16 v[88:91], v[168:171], v[208:211], 0
	v_mfma_f32_16x16x32_bf16 v[84:87], v[176:179], v[208:211], 0
	v_mfma_f32_16x16x32_bf16 v[72:75], v[168:171], v[216:219], 0
	v_mfma_f32_16x16x32_bf16 v[68:71], v[176:179], v[216:219], 0
	v_mfma_f32_16x16x32_bf16 v[120:123], v[172:175], v[196:199], v[120:123]
	v_mfma_f32_16x16x32_bf16 v[116:119], v[188:191], v[196:199], v[116:119]
	v_mfma_f32_16x16x32_bf16 v[104:107], v[172:175], v[204:207], v[104:107]
	v_mfma_f32_16x16x32_bf16 v[100:103], v[188:191], v[204:207], v[100:103]
	v_mfma_f32_16x16x32_bf16 v[88:91], v[172:175], v[212:215], v[88:91]
	v_mfma_f32_16x16x32_bf16 v[84:87], v[188:191], v[212:215], v[84:87]
	v_mfma_f32_16x16x32_bf16 v[72:75], v[172:175], v[220:223], v[72:75]
	v_mfma_f32_16x16x32_bf16 v[68:71], v[188:191], v[220:223], v[68:71]

	s_barrier
	s_add_i32 s29, s33, s42
	v_lshl_add_u64 v[144:145], s[34:35], 0, v[134:135]
	s_mov_b32 m0, s29
	ds_read_b128 v[192:195], v158 offset:16384
	ds_read_b128 v[196:199], v158 offset:17408
	ds_read_b128 v[200:203], v158 offset:18432
	ds_read_b128 v[204:207], v158 offset:19456
	ds_read_b128 v[208:211], v158 offset:20480
	ds_read_b128 v[212:215], v158 offset:21504
	ds_read_b128 v[216:219], v158 offset:22528
	ds_read_b128 v[220:223], v158 offset:23552
	global_load_lds_dwordx4 v[144:145], off
	s_add_i32 m0, s29, 0x2000
	s_add_u32 s44, s34, 0x40000
	v_lshl_add_u64 v[224:225], s[34:35], 0, v[138:139]
	s_addc_u32 s45, s35, 0
	s_add_i32 s27, s27, s42
	global_load_lds_dwordx4 v[224:225], off
	v_lshl_add_u64 v[226:227], s[44:45], 0, v[134:135]
	s_mov_b32 m0, s27
	v_lshl_add_u64 v[228:229], s[36:37], 0, v[136:137]
	global_load_lds_dwordx4 v[226:227], off
	v_lshl_add_u64 v[226:227], s[44:45], 0, v[138:139]
	s_add_i32 m0, s27, 0x2000
	s_nop 0
	global_load_lds_dwordx4 v[226:227], off
	v_lshl_add_u64 v[226:227], s[36:37], 0, v[132:133]
	s_mov_b32 m0, s43
	s_nop 0
	global_load_lds_dwordx4 v[226:227], off
	s_mov_b32 m0, s48
	s_nop 0
	global_load_lds_dwordx4 v[228:229], off
	s_waitcnt vmcnt(24)
	s_waitcnt lgkmcnt(0)
	s_barrier

	s_waitcnt lgkmcnt(0)
	v_mfma_f32_16x16x32_bf16 v[64:67], v[148:151], v[192:195], 0
	v_mfma_f32_16x16x32_bf16 v[60:63], v[160:163], v[192:195], 0
	v_mfma_f32_16x16x32_bf16 v[48:51], v[148:151], v[200:203], 0
	v_mfma_f32_16x16x32_bf16 v[44:47], v[160:163], v[200:203], 0
	v_mfma_f32_16x16x32_bf16 v[32:35], v[148:151], v[208:211], 0
	v_mfma_f32_16x16x32_bf16 v[28:31], v[160:163], v[208:211], 0
	v_mfma_f32_16x16x32_bf16 v[16:19], v[148:151], v[216:219], 0
	v_mfma_f32_16x16x32_bf16 v[12:15], v[160:163], v[216:219], 0
	v_mfma_f32_16x16x32_bf16 v[64:67], v[152:155], v[196:199], v[64:67]
	v_mfma_f32_16x16x32_bf16 v[60:63], v[164:167], v[196:199], v[60:63]
	v_mfma_f32_16x16x32_bf16 v[48:51], v[152:155], v[204:207], v[48:51]
	v_mfma_f32_16x16x32_bf16 v[44:47], v[164:167], v[204:207], v[44:47]
	v_mfma_f32_16x16x32_bf16 v[32:35], v[152:155], v[212:215], v[32:35]
	v_mfma_f32_16x16x32_bf16 v[28:31], v[164:167], v[212:215], v[28:31]
	v_mfma_f32_16x16x32_bf16 v[16:19], v[152:155], v[220:223], v[16:19]
	v_mfma_f32_16x16x32_bf16 v[12:15], v[164:167], v[220:223], v[12:15]


	v_mfma_f32_16x16x32_bf16 v[56:59], v[168:171], v[192:195], 0
	v_mfma_f32_16x16x32_bf16 v[52:55], v[176:179], v[192:195], 0
	v_mfma_f32_16x16x32_bf16 v[40:43], v[168:171], v[200:203], 0
	v_mfma_f32_16x16x32_bf16 v[36:39], v[176:179], v[200:203], 0
	v_mfma_f32_16x16x32_bf16 v[24:27], v[168:171], v[208:211], 0
	v_mfma_f32_16x16x32_bf16 v[20:23], v[176:179], v[208:211], 0
	v_mfma_f32_16x16x32_bf16 v[8:11], v[168:171], v[216:219], 0
	v_mfma_f32_16x16x32_bf16 v[4:7], v[176:179], v[216:219], 0
	v_mfma_f32_16x16x32_bf16 v[56:59], v[172:175], v[196:199], v[56:59]
	v_mfma_f32_16x16x32_bf16 v[52:55], v[188:191], v[196:199], v[52:55]
	v_mfma_f32_16x16x32_bf16 v[40:43], v[172:175], v[204:207], v[40:43]
	v_mfma_f32_16x16x32_bf16 v[36:39], v[188:191], v[204:207], v[36:39]
	v_mfma_f32_16x16x32_bf16 v[24:27], v[172:175], v[212:215], v[24:27]
	v_mfma_f32_16x16x32_bf16 v[20:23], v[188:191], v[212:215], v[20:23]
	v_mfma_f32_16x16x32_bf16 v[8:11], v[172:175], v[220:223], v[8:11]
	v_mfma_f32_16x16x32_bf16 v[4:7], v[188:191], v[220:223], v[4:7]

	s_barrier
	s_add_i32 s27, 0, 0x18000
	v_add_u32_e32 v146, s27, v157
	s_add_i32 s29, 0, 0x1c000
	ds_read_b128 v[148:151], v146
	ds_read_b128 v[152:155], v146 offset:1024
	ds_read_b128 v[160:163], v146 offset:2048
	ds_read_b128 v[164:167], v146 offset:3072
	v_add_u32_e32 v146, s29, v157
	ds_read_b128 v[168:171], v146
	ds_read_b128 v[172:175], v146 offset:1024
	ds_read_b128 v[176:179], v146 offset:2048
	ds_read_b128 v[188:191], v146 offset:3072
	s_add_u32 s36, s36, 0x40000
	s_addc_u32 s37, s37, 0
	s_mov_b32 m0, s50
	v_lshl_add_u64 v[230:231], s[36:37], 0, v[132:133]
	ds_read_b128 v[192:195], v158 offset:32768
	ds_read_b128 v[196:199], v158 offset:33792
	ds_read_b128 v[200:203], v158 offset:34816
	ds_read_b128 v[204:207], v158 offset:35840
	ds_read_b128 v[208:211], v158 offset:36864
	ds_read_b128 v[212:215], v158 offset:37888
	ds_read_b128 v[216:219], v158 offset:38912
	ds_read_b128 v[220:223], v158 offset:39936
	global_load_lds_dwordx4 v[230:231], off
	v_lshl_add_u64 v[230:231], s[36:37], 0, v[136:137]
	s_mov_b32 m0, s51
	s_nop 0
	global_load_lds_dwordx4 v[230:231], off
	s_waitcnt vmcnt(8)
	s_waitcnt lgkmcnt(0)
	s_barrier

	s_waitcnt lgkmcnt(0)
	v_mfma_f32_16x16x32_bf16 v[128:131], v[148:151], v[192:195], v[128:131]
	v_mfma_f32_16x16x32_bf16 v[124:127], v[160:163], v[192:195], v[124:127]
	v_mfma_f32_16x16x32_bf16 v[112:115], v[148:151], v[200:203], v[112:115]
	v_mfma_f32_16x16x32_bf16 v[108:111], v[160:163], v[200:203], v[108:111]
	v_mfma_f32_16x16x32_bf16 v[96:99], v[148:151], v[208:211], v[96:99]
	v_mfma_f32_16x16x32_bf16 v[92:95], v[160:163], v[208:211], v[92:95]
	v_mfma_f32_16x16x32_bf16 v[80:83], v[148:151], v[216:219], v[80:83]
	v_mfma_f32_16x16x32_bf16 v[76:79], v[160:163], v[216:219], v[76:79]
	v_mfma_f32_16x16x32_bf16 v[128:131], v[152:155], v[196:199], v[128:131]
	v_mfma_f32_16x16x32_bf16 v[124:127], v[164:167], v[196:199], v[124:127]
	v_mfma_f32_16x16x32_bf16 v[112:115], v[152:155], v[204:207], v[112:115]
	v_mfma_f32_16x16x32_bf16 v[108:111], v[164:167], v[204:207], v[108:111]
	v_mfma_f32_16x16x32_bf16 v[96:99], v[152:155], v[212:215], v[96:99]
	v_mfma_f32_16x16x32_bf16 v[92:95], v[164:167], v[212:215], v[92:95]
	v_mfma_f32_16x16x32_bf16 v[80:83], v[152:155], v[220:223], v[80:83]
	v_mfma_f32_16x16x32_bf16 v[76:79], v[164:167], v[220:223], v[76:79]


	v_mfma_f32_16x16x32_bf16 v[120:123], v[168:171], v[192:195], v[120:123]
	v_mfma_f32_16x16x32_bf16 v[116:119], v[176:179], v[192:195], v[116:119]
	v_mfma_f32_16x16x32_bf16 v[104:107], v[168:171], v[200:203], v[104:107]
	v_mfma_f32_16x16x32_bf16 v[100:103], v[176:179], v[200:203], v[100:103]
	v_mfma_f32_16x16x32_bf16 v[88:91], v[168:171], v[208:211], v[88:91]
	v_mfma_f32_16x16x32_bf16 v[84:87], v[176:179], v[208:211], v[84:87]
	v_mfma_f32_16x16x32_bf16 v[72:75], v[168:171], v[216:219], v[72:75]
	v_mfma_f32_16x16x32_bf16 v[68:71], v[176:179], v[216:219], v[68:71]
	v_mfma_f32_16x16x32_bf16 v[120:123], v[172:175], v[196:199], v[120:123]
	v_mfma_f32_16x16x32_bf16 v[116:119], v[188:191], v[196:199], v[116:119]
	v_mfma_f32_16x16x32_bf16 v[104:107], v[172:175], v[204:207], v[104:107]
	v_mfma_f32_16x16x32_bf16 v[100:103], v[188:191], v[204:207], v[100:103]
	v_mfma_f32_16x16x32_bf16 v[88:91], v[172:175], v[212:215], v[88:91]
	v_mfma_f32_16x16x32_bf16 v[84:87], v[188:191], v[212:215], v[84:87]
	v_mfma_f32_16x16x32_bf16 v[72:75], v[172:175], v[220:223], v[72:75]
	v_mfma_f32_16x16x32_bf16 v[68:71], v[188:191], v[220:223], v[68:71]

	s_barrier
	s_add_i32 s27, s27, s42
	v_lshl_add_u64 v[144:145], v[144:145], 0, s[52:53]
	s_mov_b32 m0, s27
	ds_read_b128 v[192:195], v158 offset:49152
	ds_read_b128 v[196:199], v158 offset:50176
	ds_read_b128 v[200:203], v158 offset:51200
	ds_read_b128 v[204:207], v158 offset:52224
	ds_read_b128 v[208:211], v158 offset:53248
	ds_read_b128 v[212:215], v158 offset:54272
	ds_read_b128 v[216:219], v158 offset:55296
	ds_read_b128 v[220:223], v158 offset:56320
	global_load_lds_dwordx4 v[144:145], off
	s_add_i32 m0, s27, 0x2000
	s_add_u32 s34, s34, 0x40080
	v_lshl_add_u64 v[144:145], v[224:225], 0, s[52:53]
	s_addc_u32 s35, s35, 0
	s_add_i32 s27, s29, s42
	global_load_lds_dwordx4 v[144:145], off
	v_lshl_add_u64 v[144:145], s[34:35], 0, v[134:135]
	s_mov_b32 m0, s27
	s_nop 0
	global_load_lds_dwordx4 v[144:145], off
	v_lshl_add_u64 v[144:145], s[34:35], 0, v[138:139]
	s_add_i32 m0, s27, 0x2000
	s_nop 0
	global_load_lds_dwordx4 v[144:145], off
	v_lshl_add_u64 v[144:145], v[226:227], 0, s[52:53]
	s_mov_b32 m0, s58
	s_nop 0
	global_load_lds_dwordx4 v[144:145], off
	v_lshl_add_u64 v[144:145], v[228:229], 0, s[52:53]
	s_mov_b32 m0, s59
	s_nop 0
	global_load_lds_dwordx4 v[144:145], off
	s_waitcnt vmcnt(8)
	s_waitcnt lgkmcnt(0)
	s_barrier

	s_waitcnt lgkmcnt(0)
	v_mfma_f32_16x16x32_bf16 v[64:67], v[148:151], v[192:195], v[64:67]
	v_mfma_f32_16x16x32_bf16 v[60:63], v[160:163], v[192:195], v[60:63]
	v_mfma_f32_16x16x32_bf16 v[48:51], v[148:151], v[200:203], v[48:51]
	v_mfma_f32_16x16x32_bf16 v[44:47], v[160:163], v[200:203], v[44:47]
	v_mfma_f32_16x16x32_bf16 v[32:35], v[148:151], v[208:211], v[32:35]
	v_mfma_f32_16x16x32_bf16 v[28:31], v[160:163], v[208:211], v[28:31]
	v_mfma_f32_16x16x32_bf16 v[16:19], v[148:151], v[216:219], v[16:19]
	v_mfma_f32_16x16x32_bf16 v[12:15], v[160:163], v[216:219], v[12:15]
	v_mfma_f32_16x16x32_bf16 v[64:67], v[152:155], v[196:199], v[64:67]
	v_mfma_f32_16x16x32_bf16 v[60:63], v[164:167], v[196:199], v[60:63]
	v_mfma_f32_16x16x32_bf16 v[48:51], v[152:155], v[204:207], v[48:51]
	v_mfma_f32_16x16x32_bf16 v[44:47], v[164:167], v[204:207], v[44:47]
	v_mfma_f32_16x16x32_bf16 v[32:35], v[152:155], v[212:215], v[32:35]
	v_mfma_f32_16x16x32_bf16 v[28:31], v[164:167], v[212:215], v[28:31]
	v_mfma_f32_16x16x32_bf16 v[16:19], v[152:155], v[220:223], v[16:19]
	v_mfma_f32_16x16x32_bf16 v[12:15], v[164:167], v[220:223], v[12:15]


	v_mfma_f32_16x16x32_bf16 v[56:59], v[168:171], v[192:195], v[56:59]
	v_mfma_f32_16x16x32_bf16 v[52:55], v[176:179], v[192:195], v[52:55]
	v_mfma_f32_16x16x32_bf16 v[40:43], v[168:171], v[200:203], v[40:43]
	v_mfma_f32_16x16x32_bf16 v[36:39], v[176:179], v[200:203], v[36:39]
	v_mfma_f32_16x16x32_bf16 v[24:27], v[168:171], v[208:211], v[24:27]
	v_mfma_f32_16x16x32_bf16 v[20:23], v[176:179], v[208:211], v[20:23]
	v_mfma_f32_16x16x32_bf16 v[8:11], v[168:171], v[216:219], v[8:11]
	v_mfma_f32_16x16x32_bf16 v[4:7], v[176:179], v[216:219], v[4:7]
	v_mfma_f32_16x16x32_bf16 v[56:59], v[172:175], v[196:199], v[56:59]
	v_mfma_f32_16x16x32_bf16 v[52:55], v[188:191], v[196:199], v[52:55]
	v_mfma_f32_16x16x32_bf16 v[40:43], v[172:175], v[204:207], v[40:43]
	v_mfma_f32_16x16x32_bf16 v[36:39], v[188:191], v[204:207], v[36:39]
	v_mfma_f32_16x16x32_bf16 v[24:27], v[172:175], v[212:215], v[24:27]
	v_mfma_f32_16x16x32_bf16 v[20:23], v[188:191], v[212:215], v[20:23]
	v_mfma_f32_16x16x32_bf16 v[8:11], v[172:175], v[220:223], v[8:11]
	v_mfma_f32_16x16x32_bf16 v[4:7], v[188:191], v[220:223], v[4:7]

	s_barrier
	s_add_i32 s21, s21, 2
	s_add_u32 s30, s30, 0x100
	s_addc_u32 s31, s31, 0
	s_add_u32 s5, s5, 0x100
	s_addc_u32 s19, s19, 0
	s_cmp_gt_u32 s21, 13
	s_cbranch_scc1 .Lkexit_1
.LBB0_671:
	s_add_u32 s27, s30, 0xfffc0080
	s_addc_u32 s29, s31, -1
	s_add_i32 s33, 0, 0x10000
	s_cmp_eq_u32 s21, 12
	s_cselect_b32 s37, s0, s29
	s_cselect_b32 s36, s1, s27
	v_add_u32_e32 v144, s33, v157
	s_cselect_b32 s35, s2, s19
	s_cselect_b32 s34, s4, s5
	s_add_i32 s27, 0, 0x14000
	ds_read_b128 v[148:151], v144
	ds_read_b128 v[152:155], v144 offset:1024
	ds_read_b128 v[160:163], v144 offset:2048
	ds_read_b128 v[164:167], v144 offset:3072
	v_add_u32_e32 v144, s27, v157
	ds_read_b128 v[168:171], v144
	ds_read_b128 v[172:175], v144 offset:1024
	ds_read_b128 v[176:179], v144 offset:2048
	ds_read_b128 v[188:191], v144 offset:3072
	v_lshl_add_u64 v[144:145], s[30:31], 0, v[140:141]
	s_add_i32 m0, s43, 0xc000
	ds_read_b128 v[192:195], v158
	ds_read_b128 v[196:199], v158 offset:1024
	ds_read_b128 v[200:203], v158 offset:2048
	ds_read_b128 v[204:207], v158 offset:3072
	ds_read_b128 v[208:211], v158 offset:4096
	ds_read_b128 v[212:215], v158 offset:5120
	ds_read_b128 v[216:219], v158 offset:6144
	ds_read_b128 v[220:223], v158 offset:7168
	global_load_lds_dwordx4 v[144:145], off
	v_lshl_add_u64 v[144:145], s[30:31], 0, v[142:143]
	s_add_i32 m0, s43, 0xe000
	s_nop 0
	global_load_lds_dwordx4 v[144:145], off
	s_waitcnt vmcnt(8)
	s_waitcnt lgkmcnt(0)
	s_barrier

	s_waitcnt lgkmcnt(0)
	v_mfma_f32_16x16x32_bf16 v[128:131], v[148:151], v[192:195], v[128:131]
	v_mfma_f32_16x16x32_bf16 v[124:127], v[160:163], v[192:195], v[124:127]
	v_mfma_f32_16x16x32_bf16 v[112:115], v[148:151], v[200:203], v[112:115]
	v_mfma_f32_16x16x32_bf16 v[108:111], v[160:163], v[200:203], v[108:111]
	v_mfma_f32_16x16x32_bf16 v[96:99], v[148:151], v[208:211], v[96:99]
	v_mfma_f32_16x16x32_bf16 v[92:95], v[160:163], v[208:211], v[92:95]
	v_mfma_f32_16x16x32_bf16 v[80:83], v[148:151], v[216:219], v[80:83]
	v_mfma_f32_16x16x32_bf16 v[76:79], v[160:163], v[216:219], v[76:79]
	v_mfma_f32_16x16x32_bf16 v[128:131], v[152:155], v[196:199], v[128:131]
	v_mfma_f32_16x16x32_bf16 v[124:127], v[164:167], v[196:199], v[124:127]
	v_mfma_f32_16x16x32_bf16 v[112:115], v[152:155], v[204:207], v[112:115]
	v_mfma_f32_16x16x32_bf16 v[108:111], v[164:167], v[204:207], v[108:111]
	v_mfma_f32_16x16x32_bf16 v[96:99], v[152:155], v[212:215], v[96:99]
	v_mfma_f32_16x16x32_bf16 v[92:95], v[164:167], v[212:215], v[92:95]
	v_mfma_f32_16x16x32_bf16 v[80:83], v[152:155], v[220:223], v[80:83]
	v_mfma_f32_16x16x32_bf16 v[76:79], v[164:167], v[220:223], v[76:79]


	v_mfma_f32_16x16x32_bf16 v[120:123], v[168:171], v[192:195], v[120:123]
	v_mfma_f32_16x16x32_bf16 v[116:119], v[176:179], v[192:195], v[116:119]
	v_mfma_f32_16x16x32_bf16 v[104:107], v[168:171], v[200:203], v[104:107]
	v_mfma_f32_16x16x32_bf16 v[100:103], v[176:179], v[200:203], v[100:103]
	v_mfma_f32_16x16x32_bf16 v[88:91], v[168:171], v[208:211], v[88:91]
	v_mfma_f32_16x16x32_bf16 v[84:87], v[176:179], v[208:211], v[84:87]
	v_mfma_f32_16x16x32_bf16 v[72:75], v[168:171], v[216:219], v[72:75]
	v_mfma_f32_16x16x32_bf16 v[68:71], v[176:179], v[216:219], v[68:71]
	v_mfma_f32_16x16x32_bf16 v[120:123], v[172:175], v[196:199], v[120:123]
	v_mfma_f32_16x16x32_bf16 v[116:119], v[188:191], v[196:199], v[116:119]
	v_mfma_f32_16x16x32_bf16 v[104:107], v[172:175], v[204:207], v[104:107]
	v_mfma_f32_16x16x32_bf16 v[100:103], v[188:191], v[204:207], v[100:103]
	v_mfma_f32_16x16x32_bf16 v[88:91], v[172:175], v[212:215], v[88:91]
	v_mfma_f32_16x16x32_bf16 v[84:87], v[188:191], v[212:215], v[84:87]
	v_mfma_f32_16x16x32_bf16 v[72:75], v[172:175], v[220:223], v[72:75]
	v_mfma_f32_16x16x32_bf16 v[68:71], v[188:191], v[220:223], v[68:71]

	s_barrier
	s_add_i32 s29, s33, s42
	v_lshl_add_u64 v[144:145], s[34:35], 0, v[134:135]
	s_mov_b32 m0, s29
	ds_read_b128 v[192:195], v158 offset:16384
	ds_read_b128 v[196:199], v158 offset:17408
	ds_read_b128 v[200:203], v158 offset:18432
	ds_read_b128 v[204:207], v158 offset:19456
	ds_read_b128 v[208:211], v158 offset:20480
	ds_read_b128 v[212:215], v158 offset:21504
	ds_read_b128 v[216:219], v158 offset:22528
	ds_read_b128 v[220:223], v158 offset:23552
	global_load_lds_dwordx4 v[144:145], off
	s_add_i32 m0, s29, 0x2000
	s_add_u32 s44, s34, 0x40000
	v_lshl_add_u64 v[224:225], s[34:35], 0, v[138:139]
	s_addc_u32 s45, s35, 0
	s_add_i32 s27, s27, s42
	global_load_lds_dwordx4 v[224:225], off
	v_lshl_add_u64 v[226:227], s[44:45], 0, v[134:135]
	s_mov_b32 m0, s27
	v_lshl_add_u64 v[228:229], s[36:37], 0, v[136:137]
	global_load_lds_dwordx4 v[226:227], off
	v_lshl_add_u64 v[226:227], s[44:45], 0, v[138:139]
	s_add_i32 m0, s27, 0x2000
	s_nop 0
	global_load_lds_dwordx4 v[226:227], off
	v_lshl_add_u64 v[226:227], s[36:37], 0, v[132:133]
	s_mov_b32 m0, s43
	s_nop 0
	global_load_lds_dwordx4 v[226:227], off
	s_mov_b32 m0, s48
	s_nop 0
	global_load_lds_dwordx4 v[228:229], off
	s_waitcnt vmcnt(8)
	s_waitcnt lgkmcnt(0)
	s_barrier

	s_waitcnt lgkmcnt(0)
	v_mfma_f32_16x16x32_bf16 v[64:67], v[148:151], v[192:195], v[64:67]
	v_mfma_f32_16x16x32_bf16 v[60:63], v[160:163], v[192:195], v[60:63]
	v_mfma_f32_16x16x32_bf16 v[48:51], v[148:151], v[200:203], v[48:51]
	v_mfma_f32_16x16x32_bf16 v[44:47], v[160:163], v[200:203], v[44:47]
	v_mfma_f32_16x16x32_bf16 v[32:35], v[148:151], v[208:211], v[32:35]
	v_mfma_f32_16x16x32_bf16 v[28:31], v[160:163], v[208:211], v[28:31]
	v_mfma_f32_16x16x32_bf16 v[16:19], v[148:151], v[216:219], v[16:19]
	v_mfma_f32_16x16x32_bf16 v[12:15], v[160:163], v[216:219], v[12:15]
	v_mfma_f32_16x16x32_bf16 v[64:67], v[152:155], v[196:199], v[64:67]
	v_mfma_f32_16x16x32_bf16 v[60:63], v[164:167], v[196:199], v[60:63]
	v_mfma_f32_16x16x32_bf16 v[48:51], v[152:155], v[204:207], v[48:51]
	v_mfma_f32_16x16x32_bf16 v[44:47], v[164:167], v[204:207], v[44:47]
	v_mfma_f32_16x16x32_bf16 v[32:35], v[152:155], v[212:215], v[32:35]
	v_mfma_f32_16x16x32_bf16 v[28:31], v[164:167], v[212:215], v[28:31]
	v_mfma_f32_16x16x32_bf16 v[16:19], v[152:155], v[220:223], v[16:19]
	v_mfma_f32_16x16x32_bf16 v[12:15], v[164:167], v[220:223], v[12:15]


	v_mfma_f32_16x16x32_bf16 v[56:59], v[168:171], v[192:195], v[56:59]
	v_mfma_f32_16x16x32_bf16 v[52:55], v[176:179], v[192:195], v[52:55]
	v_mfma_f32_16x16x32_bf16 v[40:43], v[168:171], v[200:203], v[40:43]
	v_mfma_f32_16x16x32_bf16 v[36:39], v[176:179], v[200:203], v[36:39]
	v_mfma_f32_16x16x32_bf16 v[24:27], v[168:171], v[208:211], v[24:27]
	v_mfma_f32_16x16x32_bf16 v[20:23], v[176:179], v[208:211], v[20:23]
	v_mfma_f32_16x16x32_bf16 v[8:11], v[168:171], v[216:219], v[8:11]
	v_mfma_f32_16x16x32_bf16 v[4:7], v[176:179], v[216:219], v[4:7]
	v_mfma_f32_16x16x32_bf16 v[56:59], v[172:175], v[196:199], v[56:59]
	v_mfma_f32_16x16x32_bf16 v[52:55], v[188:191], v[196:199], v[52:55]
	v_mfma_f32_16x16x32_bf16 v[40:43], v[172:175], v[204:207], v[40:43]
	v_mfma_f32_16x16x32_bf16 v[36:39], v[188:191], v[204:207], v[36:39]
	v_mfma_f32_16x16x32_bf16 v[24:27], v[172:175], v[212:215], v[24:27]
	v_mfma_f32_16x16x32_bf16 v[20:23], v[188:191], v[212:215], v[20:23]
	v_mfma_f32_16x16x32_bf16 v[8:11], v[172:175], v[220:223], v[8:11]
	v_mfma_f32_16x16x32_bf16 v[4:7], v[188:191], v[220:223], v[4:7]

	s_barrier
	s_add_i32 s27, 0, 0x18000
	v_add_u32_e32 v146, s27, v157
	s_add_i32 s29, 0, 0x1c000
	ds_read_b128 v[148:151], v146
	ds_read_b128 v[152:155], v146 offset:1024
	ds_read_b128 v[160:163], v146 offset:2048
	ds_read_b128 v[164:167], v146 offset:3072
	v_add_u32_e32 v146, s29, v157
	ds_read_b128 v[168:171], v146
	ds_read_b128 v[172:175], v146 offset:1024
	ds_read_b128 v[176:179], v146 offset:2048
	ds_read_b128 v[188:191], v146 offset:3072
	s_add_u32 s36, s36, 0x40000
	s_addc_u32 s37, s37, 0
	s_mov_b32 m0, s50
	v_lshl_add_u64 v[230:231], s[36:37], 0, v[132:133]
	ds_read_b128 v[192:195], v158 offset:32768
	ds_read_b128 v[196:199], v158 offset:33792
	ds_read_b128 v[200:203], v158 offset:34816
	ds_read_b128 v[204:207], v158 offset:35840
	ds_read_b128 v[208:211], v158 offset:36864
	ds_read_b128 v[212:215], v158 offset:37888
	ds_read_b128 v[216:219], v158 offset:38912
	ds_read_b128 v[220:223], v158 offset:39936
	global_load_lds_dwordx4 v[230:231], off
	v_lshl_add_u64 v[230:231], s[36:37], 0, v[136:137]
	s_mov_b32 m0, s51
	s_nop 0
	global_load_lds_dwordx4 v[230:231], off
	s_waitcnt vmcnt(8)
	s_waitcnt lgkmcnt(0)
	s_barrier

	s_waitcnt lgkmcnt(0)
	v_mfma_f32_16x16x32_bf16 v[128:131], v[148:151], v[192:195], v[128:131]
	v_mfma_f32_16x16x32_bf16 v[124:127], v[160:163], v[192:195], v[124:127]
	v_mfma_f32_16x16x32_bf16 v[112:115], v[148:151], v[200:203], v[112:115]
	v_mfma_f32_16x16x32_bf16 v[108:111], v[160:163], v[200:203], v[108:111]
	v_mfma_f32_16x16x32_bf16 v[96:99], v[148:151], v[208:211], v[96:99]
	v_mfma_f32_16x16x32_bf16 v[92:95], v[160:163], v[208:211], v[92:95]
	v_mfma_f32_16x16x32_bf16 v[80:83], v[148:151], v[216:219], v[80:83]
	v_mfma_f32_16x16x32_bf16 v[76:79], v[160:163], v[216:219], v[76:79]
	v_mfma_f32_16x16x32_bf16 v[128:131], v[152:155], v[196:199], v[128:131]
	v_mfma_f32_16x16x32_bf16 v[124:127], v[164:167], v[196:199], v[124:127]
	v_mfma_f32_16x16x32_bf16 v[112:115], v[152:155], v[204:207], v[112:115]
	v_mfma_f32_16x16x32_bf16 v[108:111], v[164:167], v[204:207], v[108:111]
	v_mfma_f32_16x16x32_bf16 v[96:99], v[152:155], v[212:215], v[96:99]
	v_mfma_f32_16x16x32_bf16 v[92:95], v[164:167], v[212:215], v[92:95]
	v_mfma_f32_16x16x32_bf16 v[80:83], v[152:155], v[220:223], v[80:83]
	v_mfma_f32_16x16x32_bf16 v[76:79], v[164:167], v[220:223], v[76:79]


	v_mfma_f32_16x16x32_bf16 v[120:123], v[168:171], v[192:195], v[120:123]
	v_mfma_f32_16x16x32_bf16 v[116:119], v[176:179], v[192:195], v[116:119]
	v_mfma_f32_16x16x32_bf16 v[104:107], v[168:171], v[200:203], v[104:107]
	v_mfma_f32_16x16x32_bf16 v[100:103], v[176:179], v[200:203], v[100:103]
	v_mfma_f32_16x16x32_bf16 v[88:91], v[168:171], v[208:211], v[88:91]
	v_mfma_f32_16x16x32_bf16 v[84:87], v[176:179], v[208:211], v[84:87]
	v_mfma_f32_16x16x32_bf16 v[72:75], v[168:171], v[216:219], v[72:75]
	v_mfma_f32_16x16x32_bf16 v[68:71], v[176:179], v[216:219], v[68:71]
	v_mfma_f32_16x16x32_bf16 v[120:123], v[172:175], v[196:199], v[120:123]
	v_mfma_f32_16x16x32_bf16 v[116:119], v[188:191], v[196:199], v[116:119]
	v_mfma_f32_16x16x32_bf16 v[104:107], v[172:175], v[204:207], v[104:107]
	v_mfma_f32_16x16x32_bf16 v[100:103], v[188:191], v[204:207], v[100:103]
	v_mfma_f32_16x16x32_bf16 v[88:91], v[172:175], v[212:215], v[88:91]
	v_mfma_f32_16x16x32_bf16 v[84:87], v[188:191], v[212:215], v[84:87]
	v_mfma_f32_16x16x32_bf16 v[72:75], v[172:175], v[220:223], v[72:75]
	v_mfma_f32_16x16x32_bf16 v[68:71], v[188:191], v[220:223], v[68:71]

	s_barrier
	s_add_i32 s27, s27, s42
	v_lshl_add_u64 v[144:145], v[144:145], 0, s[52:53]
	s_mov_b32 m0, s27
	ds_read_b128 v[192:195], v158 offset:49152
	ds_read_b128 v[196:199], v158 offset:50176
	ds_read_b128 v[200:203], v158 offset:51200
	ds_read_b128 v[204:207], v158 offset:52224
	ds_read_b128 v[208:211], v158 offset:53248
	ds_read_b128 v[212:215], v158 offset:54272
	ds_read_b128 v[216:219], v158 offset:55296
	ds_read_b128 v[220:223], v158 offset:56320
	global_load_lds_dwordx4 v[144:145], off
	s_add_i32 m0, s27, 0x2000
	s_add_u32 s34, s34, 0x40080
	v_lshl_add_u64 v[144:145], v[224:225], 0, s[52:53]
	s_addc_u32 s35, s35, 0
	s_add_i32 s27, s29, s42
	global_load_lds_dwordx4 v[144:145], off
	v_lshl_add_u64 v[144:145], s[34:35], 0, v[134:135]
	s_mov_b32 m0, s27
	s_nop 0
	global_load_lds_dwordx4 v[144:145], off
	v_lshl_add_u64 v[144:145], s[34:35], 0, v[138:139]
	s_add_i32 m0, s27, 0x2000
	s_nop 0
	global_load_lds_dwordx4 v[144:145], off
	v_lshl_add_u64 v[144:145], v[226:227], 0, s[52:53]
	s_mov_b32 m0, s58
	s_nop 0
	global_load_lds_dwordx4 v[144:145], off
	v_lshl_add_u64 v[144:145], v[228:229], 0, s[52:53]
	s_mov_b32 m0, s59
	s_nop 0
	global_load_lds_dwordx4 v[144:145], off
	s_waitcnt vmcnt(8)
	s_waitcnt lgkmcnt(0)
	s_barrier

	s_waitcnt lgkmcnt(0)
	v_mfma_f32_16x16x32_bf16 v[64:67], v[148:151], v[192:195], v[64:67]
	v_mfma_f32_16x16x32_bf16 v[60:63], v[160:163], v[192:195], v[60:63]
	v_mfma_f32_16x16x32_bf16 v[48:51], v[148:151], v[200:203], v[48:51]
	v_mfma_f32_16x16x32_bf16 v[44:47], v[160:163], v[200:203], v[44:47]
	v_mfma_f32_16x16x32_bf16 v[32:35], v[148:151], v[208:211], v[32:35]
	v_mfma_f32_16x16x32_bf16 v[28:31], v[160:163], v[208:211], v[28:31]
	v_mfma_f32_16x16x32_bf16 v[16:19], v[148:151], v[216:219], v[16:19]
	v_mfma_f32_16x16x32_bf16 v[12:15], v[160:163], v[216:219], v[12:15]
	v_mfma_f32_16x16x32_bf16 v[64:67], v[152:155], v[196:199], v[64:67]
	v_mfma_f32_16x16x32_bf16 v[60:63], v[164:167], v[196:199], v[60:63]
	v_mfma_f32_16x16x32_bf16 v[48:51], v[152:155], v[204:207], v[48:51]
	v_mfma_f32_16x16x32_bf16 v[44:47], v[164:167], v[204:207], v[44:47]
	v_mfma_f32_16x16x32_bf16 v[32:35], v[152:155], v[212:215], v[32:35]
	v_mfma_f32_16x16x32_bf16 v[28:31], v[164:167], v[212:215], v[28:31]
	v_mfma_f32_16x16x32_bf16 v[16:19], v[152:155], v[220:223], v[16:19]
	v_mfma_f32_16x16x32_bf16 v[12:15], v[164:167], v[220:223], v[12:15]


	v_mfma_f32_16x16x32_bf16 v[56:59], v[168:171], v[192:195], v[56:59]
	v_mfma_f32_16x16x32_bf16 v[52:55], v[176:179], v[192:195], v[52:55]
	v_mfma_f32_16x16x32_bf16 v[40:43], v[168:171], v[200:203], v[40:43]
	v_mfma_f32_16x16x32_bf16 v[36:39], v[176:179], v[200:203], v[36:39]
	v_mfma_f32_16x16x32_bf16 v[24:27], v[168:171], v[208:211], v[24:27]
	v_mfma_f32_16x16x32_bf16 v[20:23], v[176:179], v[208:211], v[20:23]
	v_mfma_f32_16x16x32_bf16 v[8:11], v[168:171], v[216:219], v[8:11]
	v_mfma_f32_16x16x32_bf16 v[4:7], v[176:179], v[216:219], v[4:7]
	v_mfma_f32_16x16x32_bf16 v[56:59], v[172:175], v[196:199], v[56:59]
	v_mfma_f32_16x16x32_bf16 v[52:55], v[188:191], v[196:199], v[52:55]
	v_mfma_f32_16x16x32_bf16 v[40:43], v[172:175], v[204:207], v[40:43]
	v_mfma_f32_16x16x32_bf16 v[36:39], v[188:191], v[204:207], v[36:39]
	v_mfma_f32_16x16x32_bf16 v[24:27], v[172:175], v[212:215], v[24:27]
	v_mfma_f32_16x16x32_bf16 v[20:23], v[188:191], v[212:215], v[20:23]
	v_mfma_f32_16x16x32_bf16 v[8:11], v[172:175], v[220:223], v[8:11]
	v_mfma_f32_16x16x32_bf16 v[4:7], v[188:191], v[220:223], v[4:7]

	s_barrier
	s_add_i32 s21, s21, 2
	s_add_u32 s30, s30, 0x100
	s_addc_u32 s31, s31, 0
	s_add_u32 s5, s5, 0x100
	s_addc_u32 s19, s19, 0
	s_cmp_gt_u32 s21, 13
	s_cbranch_scc0 .LBB0_671
	s_setprio 0
